# priority raise of the compute half issued before the barrier so the compute segment starts on a bare MFMA head (on top of segment trim + merged waits)
# baseline (speedup 1.0000x reference)
;     __host__ __device__ bool next(int i, Unit& u) const { if (!b.next(i >> 1, u)) return false; u.sel = i & 1; return true; }
; #define PG8_STAGE(bufoff, gbase, voff) do { _Pragma("unroll") for (int _i = 0; _i < 2; ++_i) \
;         __builtin_amdgcn_global_load_lds((const unsigned*)((const char*)(gbase) + (voff)[_i]), (PG8_LAS unsigned*)(lds + (bufoff) + ldsw + _i * 8192), 16, 0, 0); } while (0)
; #define PG8_BAR __builtin_amdgcn_s_barrier()
;     __host__ __device__ bool next(int i, Unit& u) const {
;         const long L = (long)i * G + c; if (L >= nwg) return false;
;         int wgid = (int)L; { const int q = nwg / NXCD, r = nwg % NXCD, xcd = wgid % NXCD, off = wgid / NXCD; wgid = (xcd < r ? xcd * (q + 1) : r * (q + 1) + (xcd - r) * q) + off; }
;         const int nig = WGM * nN, gid = wgid / nig, fm = gid * WGM, gsz = (nM - fm) < WGM ? (nM - fm) : WGM;
;         u.pm = fm + ((wgid % nig) % gsz); u.pn = (wgid % nig) / gsz; u.sel = 0; return true;
; template <class Epi, class Sched, bool ALIGN_EPI = false, bool SP2 = false>
; __device__ __forceinline__ void gemm_phase(PG8_LAS unsigned char* lds, const Gemm g, const Sched& S, const Epi& E) {
;     ...
;         const bool has_next = S.next(ui + 1, nxt);
;         const char* nA = has_next ? PG8_ABASE(nxt) : cA; const char* nB = has_next ? PG8_BBASE(nxt) : cB;
;         for (int t = 0; t < nt; t += 2) {
;             const bool last = (t == nt - 2);
;             const char* a1 = cA + (size_t)(t + 1) * kstepA;
;             const char* a2 = last ? nA : cA + (size_t)(t + 2) * kstepA; const char* b2 = last ? nB : cB + (size_t)(t + 2) * kstep;
;             const char* a3 = a2 + kstepA; const char* b3 = b2 + kstep;
;             if (last && has_next) S.a_ready(nxt);
;             if constexpr (SP2) {
;             PG8_LDB(B0, 0, 0); PG8_LDB(B1, 0, 1); PG8_SCHED; PG8_LDA(At, 0, 0); PG8_STAGE(PG8_SA(1, 1), a1 + hstep, voffA);
;             PG8_WAIT_V(8); PG8_WAIT_L(0); PG8_BAR; PG8_MMA(0, 0, At, B0); PG8_MMA(0, 1, At, B1); PG8_BAR; PG8_SCHED;
;             if constexpr (Epi::PREFETCH) { if (t == tpf) E.prefetch(cur, wid, lane); }
;             PG8_LDA(At, 0, 1); PG8_STAGE(PG8_SB(0, 0), b2, voffB); PG8_STAGE(PG8_SB(0, 1), b2 + hstep, voffB); PG8_STAGE(PG8_SA(0, 0), a2, voffA);
;             PG8_WAIT_V(8); PG8_WAIT_L(0); PG8_BAR; PG8_MMA(1, 0, At, B0); PG8_MMA(1, 1, At, B1); PG8_BAR; PG8_SCHED;
.LBB0_205:
	s_add_u32 s22, s22, 0x40080
	s_addc_u32 s23, s23, 0
	s_add_u32 s52, s24, 0x100
	s_addc_u32 s53, s25, 0
	s_mov_b32 s54, -2
	ds_read_b128 v[154:157], v150
	ds_read_b128 v[158:161], v150 offset:1024
	ds_read_b128 v[162:165], v150 offset:2048
	ds_read_b128 v[166:169], v150 offset:3072
	ds_read_b128 v[170:173], v151
	ds_read_b128 v[174:177], v151 offset:1024
	ds_read_b128 v[178:181], v151 offset:2048
	ds_read_b128 v[182:185], v151 offset:3072
	s_add_u32 s24, s22, 0xfffc0080
	s_addc_u32 s25, s23, -1
	s_cmp_eq_u32 s54, 12
	s_cselect_b32 s27, s15, s25
	s_cselect_b32 s26, s50, s24
	s_cselect_b32 s25, s13, s53
	s_cselect_b32 s24, s51, s52
	v_lshl_add_u64 v[218:219], s[22:23], 0, v[140:141]
	s_add_i32 m0, s37, 0xc000
	ds_read_b128 v[186:189], v152
	ds_read_b128 v[190:193], v152 offset:1024
	ds_read_b128 v[194:197], v152 offset:2048
	ds_read_b128 v[198:201], v152 offset:3072
	ds_read_b128 v[202:205], v152 offset:4096
	ds_read_b128 v[206:209], v152 offset:5120
	ds_read_b128 v[210:213], v152 offset:6144
	ds_read_b128 v[214:217], v152 offset:7168
	global_load_lds_dwordx4 v[218:219], off
	v_lshl_add_u64 v[218:219], s[22:23], 0, v[142:143]
	s_add_i32 m0, s37, 0xe000
	s_nop 0
	global_load_lds_dwordx4 v[218:219], off
	s_add_i32 s44, s44, 1
	s_mul_i32 s0, s44, s46
	s_mul_hi_u32 s1, s44, s33
	s_add_i32 s1, s1, s0
	s_mul_i32 s0, s44, s33
	s_add_u32 s16, s0, s87
	s_addc_u32 s17, s1, s35
	v_cmp_lt_i64_e64 s[0:1], s[16:17], v[144:145]
	s_ashr_i32 s12, s16, 31
	s_lshr_b32 s12, s12, 29
	s_add_i32 s12, s16, s12
	s_ashr_i32 s13, s12, 3
	s_and_b32 s12, s12, -8
	s_sub_i32 s12, s16, s12
	s_cmp_lt_i32 s12, 0
	s_cselect_b32 s14, s36, 0x160
	s_mul_i32 s12, s12, s14
	s_add_i32 s12, s12, s13
	s_mul_hi_i32 s13, s12, 0x2e8ba2e9
	s_lshr_b32 s14, s13, 31
	s_ashr_i32 s13, s13, 3
	s_add_i32 s13, s13, s14
	s_lshl_b32 s14, s13, 1
	s_mul_i32 s13, s13, 44
	s_sub_i32 s13, s12, s13
	s_lshr_b32 s12, s13, 1
	s_and_b32 s13, s13, 1
	s_add_i32 s14, s14, s13
	s_ashr_i32 s15, s14, 31
	s_lshl_b64 s[16:17], s[14:15], 19
	s_add_u32 s16, s28, s16
	s_addc_u32 s17, s29, s17
	s_and_b64 s[18:19], s[0:1], exec
	s_cselect_b32 s15, s17, s29
	s_cselect_b32 s50, s16, s28
	s_ashr_i32 s13, s12, 31
	s_lshl_b64 s[18:19], s[12:13], 19
	s_add_u32 s18, s30, s18
	s_addc_u32 s19, s31, s19
	s_and_b64 s[98:99], s[0:1], exec
	s_cselect_b32 s13, s19, s31
	s_cselect_b32 s51, s18, s30
	s_waitcnt vmcnt(8) lgkmcnt(0)
	s_setprio 1
	s_barrier
	v_mfma_f32_16x16x32_bf16 v[126:129], v[154:157], v[186:189], 0
	v_mfma_f32_16x16x32_bf16 v[122:125], v[162:165], v[186:189], 0
	v_mfma_f32_16x16x32_bf16 v[110:113], v[154:157], v[194:197], 0
	v_mfma_f32_16x16x32_bf16 v[106:109], v[162:165], v[194:197], 0
	v_mfma_f32_16x16x32_bf16 v[94:97], v[154:157], v[202:205], 0
	v_mfma_f32_16x16x32_bf16 v[90:93], v[162:165], v[202:205], 0
	v_mfma_f32_16x16x32_bf16 v[78:81], v[154:157], v[210:213], 0
	v_mfma_f32_16x16x32_bf16 v[74:77], v[162:165], v[210:213], 0
	v_mfma_f32_16x16x32_bf16 v[126:129], v[158:161], v[190:193], v[126:129]
	v_mfma_f32_16x16x32_bf16 v[122:125], v[166:169], v[190:193], v[122:125]
	v_mfma_f32_16x16x32_bf16 v[110:113], v[158:161], v[198:201], v[110:113]
	v_mfma_f32_16x16x32_bf16 v[106:109], v[166:169], v[198:201], v[106:109]
	v_mfma_f32_16x16x32_bf16 v[94:97], v[158:161], v[206:209], v[94:97]
	v_mfma_f32_16x16x32_bf16 v[90:93], v[166:169], v[206:209], v[90:93]
	v_mfma_f32_16x16x32_bf16 v[78:81], v[158:161], v[214:217], v[78:81]
	v_mfma_f32_16x16x32_bf16 v[74:77], v[166:169], v[214:217], v[74:77]
	v_mfma_f32_16x16x32_bf16 v[118:121], v[170:173], v[186:189], 0
	v_mfma_f32_16x16x32_bf16 v[114:117], v[178:181], v[186:189], 0
	v_mfma_f32_16x16x32_bf16 v[102:105], v[170:173], v[194:197], 0
	v_mfma_f32_16x16x32_bf16 v[98:101], v[178:181], v[194:197], 0
	v_mfma_f32_16x16x32_bf16 v[86:89], v[170:173], v[202:205], 0
	v_mfma_f32_16x16x32_bf16 v[82:85], v[178:181], v[202:205], 0
	v_mfma_f32_16x16x32_bf16 v[70:73], v[170:173], v[210:213], 0
	v_mfma_f32_16x16x32_bf16 v[66:69], v[178:181], v[210:213], 0
	v_mfma_f32_16x16x32_bf16 v[118:121], v[174:177], v[190:193], v[118:121]
	v_mfma_f32_16x16x32_bf16 v[114:117], v[182:185], v[190:193], v[114:117]
	v_mfma_f32_16x16x32_bf16 v[102:105], v[174:177], v[198:201], v[102:105]
	v_mfma_f32_16x16x32_bf16 v[98:101], v[182:185], v[198:201], v[98:101]
	v_mfma_f32_16x16x32_bf16 v[86:89], v[174:177], v[206:209], v[86:89]
	v_mfma_f32_16x16x32_bf16 v[82:85], v[182:185], v[206:209], v[82:85]
	v_mfma_f32_16x16x32_bf16 v[70:73], v[174:177], v[214:217], v[70:73]
	v_mfma_f32_16x16x32_bf16 v[66:69], v[182:185], v[214:217], v[66:69]
	s_setprio 0
	s_barrier
	s_add_i32 s55, s47, s34
	v_lshl_add_u64 v[218:219], s[24:25], 0, v[134:135]
	s_mov_b32 m0, s55
	ds_read_b128 v[186:189], v152 offset:16384
	ds_read_b128 v[190:193], v152 offset:17408
	ds_read_b128 v[194:197], v152 offset:18432
	ds_read_b128 v[198:201], v152 offset:19456
	ds_read_b128 v[202:205], v152 offset:20480
	ds_read_b128 v[206:209], v152 offset:21504
	ds_read_b128 v[210:213], v152 offset:22528
	ds_read_b128 v[214:217], v152 offset:23552
	global_load_lds_dwordx4 v[218:219], off
	s_add_i32 m0, s55, 0x2000
	s_add_u32 s56, s24, 0x40000
	v_lshl_add_u64 v[222:223], s[24:25], 0, v[130:131]
	s_addc_u32 s57, s25, 0
	s_add_i32 s55, s48, s34
	global_load_lds_dwordx4 v[222:223], off
	v_lshl_add_u64 v[224:225], s[56:57], 0, v[134:135]
	s_mov_b32 m0, s55
	v_lshl_add_u64 v[226:227], s[26:27], 0, v[132:133]
	global_load_lds_dwordx4 v[224:225], off
	v_lshl_add_u64 v[224:225], s[56:57], 0, v[130:131]
	s_add_i32 m0, s55, 0x2000
	s_nop 0
	global_load_lds_dwordx4 v[224:225], off
	v_lshl_add_u64 v[224:225], s[26:27], 0, v[136:137]
	s_mov_b32 m0, s37
	s_nop 0
	global_load_lds_dwordx4 v[224:225], off
	s_mov_b32 m0, s38
	s_nop 0
	global_load_lds_dwordx4 v[226:227], off
	s_waitcnt vmcnt(8) lgkmcnt(0)
	s_setprio 1
	s_barrier
; #define PG8_STAGE(bufoff, gbase, voff) do { _Pragma("unroll") for (int _i = 0; _i < 2; ++_i) \
;         __builtin_amdgcn_global_load_lds((const unsigned*)((const char*)(gbase) + (voff)[_i]), (PG8_LAS unsigned*)(lds + (bufoff) + ldsw + _i * 8192), 16, 0, 0); } while (0)
; #define PG8_LDA(dst, b, h) do { _Pragma("unroll") for (int m = 0; m < 4; ++m) _Pragma("unroll") for (int k = 0; k < 2; ++k) dst[m][k] = *(const PG8_LAS bf16x8*)(lds + PG8_SA(b, h) + aoff + m * 2048 + k * 1024); } while (0)
; #define PG8_LDB(dst, b, h) do { _Pragma("unroll") for (int n = 0; n < 2; ++n) _Pragma("unroll") for (int k = 0; k < 2; ++k) dst[n][k] = *(const PG8_LAS bf16x8*)(lds + PG8_SB(b, h) + boff + n * 2048 + k * 1024); } while (0)
; #define PG8_MMA(ai, bj, At, Bt) do { __builtin_amdgcn_s_setprio(1); _Pragma("unroll") for (int m = 0; m < 4; ++m) _Pragma("unroll") for (int n = 0; n < 2; ++n) _Pragma("unroll") for (int k = 0; k < 2; ++k) \
;         acc[ai][bj][m][n] = __builtin_amdgcn_mfma_f32_16x16x32_bf16(Bt[n][k], At[m][k], acc[ai][bj][m][n], 0, 0, 0); __builtin_amdgcn_s_setprio(0); } while (0)
; #define PG8_WAIT_V(n) asm volatile("s_waitcnt vmcnt(" #n ")" ::: "memory")
; #define PG8_WAIT_L(n) asm volatile("s_waitcnt lgkmcnt(" #n ")" ::: "memory")
; #define PG8_BAR __builtin_amdgcn_s_barrier()
; #define PG8_SCHED __builtin_amdgcn_sched_barrier(0)
;     __device__ __forceinline__ void prefetch(const Unit& u, int wid, int lane) const { epi_prefetch(scr, ssq, bias + (size_t)(u.pm >> 5) * NGU + u.pn * BM, u, wid, lane); }
; template <class Epi, class Sched, bool ALIGN_EPI = false, bool SP2 = false>
; __device__ __forceinline__ void gemm_phase(PG8_LAS unsigned char* lds, const Gemm g, const Sched& S, const Epi& E) {
;     ...
;             PG8_LDB(B0, 0, 0); PG8_LDB(B1, 0, 1); PG8_SCHED; PG8_LDA(At, 0, 0); PG8_STAGE(PG8_SA(1, 1), a1 + hstep, voffA);
;             PG8_WAIT_V(8); PG8_WAIT_L(0); PG8_BAR; PG8_MMA(0, 0, At, B0); PG8_MMA(0, 1, At, B1); PG8_BAR; PG8_SCHED;
;             if constexpr (Epi::PREFETCH) { if (t == tpf) E.prefetch(cur, wid, lane); }
;             PG8_LDA(At, 0, 1); PG8_STAGE(PG8_SB(0, 0), b2, voffB); PG8_STAGE(PG8_SB(0, 1), b2 + hstep, voffB); PG8_STAGE(PG8_SA(0, 0), a2, voffA);
;             PG8_WAIT_V(8); PG8_WAIT_L(0); PG8_BAR; PG8_MMA(1, 0, At, B0); PG8_MMA(1, 1, At, B1); PG8_BAR; PG8_SCHED;
	v_mfma_f32_16x16x32_bf16 v[62:65], v[154:157], v[186:189], 0
	v_mfma_f32_16x16x32_bf16 v[58:61], v[162:165], v[186:189], 0
	v_mfma_f32_16x16x32_bf16 v[46:49], v[154:157], v[194:197], 0
	v_mfma_f32_16x16x32_bf16 v[42:45], v[162:165], v[194:197], 0
	v_mfma_f32_16x16x32_bf16 v[30:33], v[154:157], v[202:205], 0
	v_mfma_f32_16x16x32_bf16 v[26:29], v[162:165], v[202:205], 0
	v_mfma_f32_16x16x32_bf16 v[14:17], v[154:157], v[210:213], 0
	v_mfma_f32_16x16x32_bf16 v[10:13], v[162:165], v[210:213], 0
	v_mfma_f32_16x16x32_bf16 v[62:65], v[158:161], v[190:193], v[62:65]
	v_mfma_f32_16x16x32_bf16 v[58:61], v[166:169], v[190:193], v[58:61]
	v_mfma_f32_16x16x32_bf16 v[46:49], v[158:161], v[198:201], v[46:49]
	v_mfma_f32_16x16x32_bf16 v[42:45], v[166:169], v[198:201], v[42:45]
	v_mfma_f32_16x16x32_bf16 v[30:33], v[158:161], v[206:209], v[30:33]
	v_mfma_f32_16x16x32_bf16 v[26:29], v[166:169], v[206:209], v[26:29]
	v_mfma_f32_16x16x32_bf16 v[14:17], v[158:161], v[214:217], v[14:17]
	v_mfma_f32_16x16x32_bf16 v[10:13], v[166:169], v[214:217], v[10:13]
	v_mfma_f32_16x16x32_bf16 v[54:57], v[170:173], v[186:189], 0
	v_mfma_f32_16x16x32_bf16 v[50:53], v[178:181], v[186:189], 0
	v_mfma_f32_16x16x32_bf16 v[38:41], v[170:173], v[194:197], 0
	v_mfma_f32_16x16x32_bf16 v[34:37], v[178:181], v[194:197], 0
	v_mfma_f32_16x16x32_bf16 v[22:25], v[170:173], v[202:205], 0
	v_mfma_f32_16x16x32_bf16 v[18:21], v[178:181], v[202:205], 0
	v_mfma_f32_16x16x32_bf16 v[6:9], v[170:173], v[210:213], 0
	v_mfma_f32_16x16x32_bf16 v[2:5], v[178:181], v[210:213], 0
	v_mfma_f32_16x16x32_bf16 v[54:57], v[174:177], v[190:193], v[54:57]
	v_mfma_f32_16x16x32_bf16 v[50:53], v[182:185], v[190:193], v[50:53]
	v_mfma_f32_16x16x32_bf16 v[38:41], v[174:177], v[198:201], v[38:41]
	v_mfma_f32_16x16x32_bf16 v[34:37], v[182:185], v[198:201], v[34:37]
	v_mfma_f32_16x16x32_bf16 v[22:25], v[174:177], v[206:209], v[22:25]
	v_mfma_f32_16x16x32_bf16 v[18:21], v[182:185], v[206:209], v[18:21]
	v_mfma_f32_16x16x32_bf16 v[6:9], v[174:177], v[214:217], v[6:9]
	v_mfma_f32_16x16x32_bf16 v[2:5], v[182:185], v[214:217], v[2:5]
	s_setprio 0
	s_barrier
	s_branch .Lpz1_mid
.LBB0_208:
	ds_read_b128 v[154:157], v150
	ds_read_b128 v[158:161], v150 offset:1024
	ds_read_b128 v[162:165], v150 offset:2048
	ds_read_b128 v[166:169], v150 offset:3072
	ds_read_b128 v[170:173], v151
	ds_read_b128 v[174:177], v151 offset:1024
	ds_read_b128 v[178:181], v151 offset:2048
	ds_read_b128 v[182:185], v151 offset:3072
	s_add_u32 s24, s22, 0xfffc0080
	s_addc_u32 s25, s23, -1
	s_cmp_eq_u32 s54, 12
	s_cselect_b32 s27, s15, s25
	s_cselect_b32 s26, s50, s24
	s_cselect_b32 s25, s13, s53
	s_cselect_b32 s24, s51, s52
	v_lshl_add_u64 v[218:219], s[22:23], 0, v[140:141]
	s_add_i32 m0, s37, 0xc000
	ds_read_b128 v[186:189], v152
	ds_read_b128 v[190:193], v152 offset:1024
	ds_read_b128 v[194:197], v152 offset:2048
	ds_read_b128 v[198:201], v152 offset:3072
	ds_read_b128 v[202:205], v152 offset:4096
	ds_read_b128 v[206:209], v152 offset:5120
	ds_read_b128 v[210:213], v152 offset:6144
	ds_read_b128 v[214:217], v152 offset:7168
	global_load_lds_dwordx4 v[218:219], off
	v_lshl_add_u64 v[218:219], s[22:23], 0, v[142:143]
	s_add_i32 m0, s37, 0xe000
	s_nop 0
	global_load_lds_dwordx4 v[218:219], off
	s_waitcnt vmcnt(8) lgkmcnt(0)
	s_setprio 1
	s_barrier
	v_mfma_f32_16x16x32_bf16 v[126:129], v[154:157], v[186:189], v[126:129]
	v_mfma_f32_16x16x32_bf16 v[122:125], v[162:165], v[186:189], v[122:125]
	v_mfma_f32_16x16x32_bf16 v[110:113], v[154:157], v[194:197], v[110:113]
	v_mfma_f32_16x16x32_bf16 v[106:109], v[162:165], v[194:197], v[106:109]
	v_mfma_f32_16x16x32_bf16 v[94:97], v[154:157], v[202:205], v[94:97]
	v_mfma_f32_16x16x32_bf16 v[90:93], v[162:165], v[202:205], v[90:93]
	v_mfma_f32_16x16x32_bf16 v[78:81], v[154:157], v[210:213], v[78:81]
	v_mfma_f32_16x16x32_bf16 v[74:77], v[162:165], v[210:213], v[74:77]
	v_mfma_f32_16x16x32_bf16 v[126:129], v[158:161], v[190:193], v[126:129]
	v_mfma_f32_16x16x32_bf16 v[122:125], v[166:169], v[190:193], v[122:125]
	v_mfma_f32_16x16x32_bf16 v[110:113], v[158:161], v[198:201], v[110:113]
	v_mfma_f32_16x16x32_bf16 v[106:109], v[166:169], v[198:201], v[106:109]
	v_mfma_f32_16x16x32_bf16 v[94:97], v[158:161], v[206:209], v[94:97]
	v_mfma_f32_16x16x32_bf16 v[90:93], v[166:169], v[206:209], v[90:93]
	v_mfma_f32_16x16x32_bf16 v[78:81], v[158:161], v[214:217], v[78:81]
	v_mfma_f32_16x16x32_bf16 v[74:77], v[166:169], v[214:217], v[74:77]
	v_mfma_f32_16x16x32_bf16 v[118:121], v[170:173], v[186:189], v[118:121]
	v_mfma_f32_16x16x32_bf16 v[114:117], v[178:181], v[186:189], v[114:117]
	v_mfma_f32_16x16x32_bf16 v[102:105], v[170:173], v[194:197], v[102:105]
	v_mfma_f32_16x16x32_bf16 v[98:101], v[178:181], v[194:197], v[98:101]
	v_mfma_f32_16x16x32_bf16 v[86:89], v[170:173], v[202:205], v[86:89]
	v_mfma_f32_16x16x32_bf16 v[82:85], v[178:181], v[202:205], v[82:85]
	v_mfma_f32_16x16x32_bf16 v[70:73], v[170:173], v[210:213], v[70:73]
	v_mfma_f32_16x16x32_bf16 v[66:69], v[178:181], v[210:213], v[66:69]
	v_mfma_f32_16x16x32_bf16 v[118:121], v[174:177], v[190:193], v[118:121]
	v_mfma_f32_16x16x32_bf16 v[114:117], v[182:185], v[190:193], v[114:117]
	v_mfma_f32_16x16x32_bf16 v[102:105], v[174:177], v[198:201], v[102:105]
	v_mfma_f32_16x16x32_bf16 v[98:101], v[182:185], v[198:201], v[98:101]
	v_mfma_f32_16x16x32_bf16 v[86:89], v[174:177], v[206:209], v[86:89]
	v_mfma_f32_16x16x32_bf16 v[82:85], v[182:185], v[206:209], v[82:85]
	v_mfma_f32_16x16x32_bf16 v[70:73], v[174:177], v[214:217], v[70:73]
	v_mfma_f32_16x16x32_bf16 v[66:69], v[182:185], v[214:217], v[66:69]
	s_setprio 0
	s_barrier
; #define PG8_STAGE(bufoff, gbase, voff) do { _Pragma("unroll") for (int _i = 0; _i < 2; ++_i) \
;         __builtin_amdgcn_global_load_lds((const unsigned*)((const char*)(gbase) + (voff)[_i]), (PG8_LAS unsigned*)(lds + (bufoff) + ldsw + _i * 8192), 16, 0, 0); } while (0)
; #define PG8_LDA(dst, b, h) do { _Pragma("unroll") for (int m = 0; m < 4; ++m) _Pragma("unroll") for (int k = 0; k < 2; ++k) dst[m][k] = *(const PG8_LAS bf16x8*)(lds + PG8_SA(b, h) + aoff + m * 2048 + k * 1024); } while (0)
; #define PG8_LDB(dst, b, h) do { _Pragma("unroll") for (int n = 0; n < 2; ++n) _Pragma("unroll") for (int k = 0; k < 2; ++k) dst[n][k] = *(const PG8_LAS bf16x8*)(lds + PG8_SB(b, h) + boff + n * 2048 + k * 1024); } while (0)
; #define PG8_MMA(ai, bj, At, Bt) do { __builtin_amdgcn_s_setprio(1); _Pragma("unroll") for (int m = 0; m < 4; ++m) _Pragma("unroll") for (int n = 0; n < 2; ++n) _Pragma("unroll") for (int k = 0; k < 2; ++k) \
;         acc[ai][bj][m][n] = __builtin_amdgcn_mfma_f32_16x16x32_bf16(Bt[n][k], At[m][k], acc[ai][bj][m][n], 0, 0, 0); __builtin_amdgcn_s_setprio(0); } while (0)
; #define PG8_WAIT_V(n) asm volatile("s_waitcnt vmcnt(" #n ")" ::: "memory")
; #define PG8_WAIT_L(n) asm volatile("s_waitcnt lgkmcnt(" #n ")" ::: "memory")
; #define PG8_BAR __builtin_amdgcn_s_barrier()
; #define PG8_SCHED __builtin_amdgcn_sched_barrier(0)
; template <class Epi, class Sched, bool ALIGN_EPI = false, bool SP2 = false>
; __device__ __forceinline__ void gemm_phase(PG8_LAS unsigned char* lds, const Gemm g, const Sched& S, const Epi& E) {
;     ...
;             PG8_LDA(At, 0, 1); PG8_STAGE(PG8_SB(0, 0), b2, voffB); PG8_STAGE(PG8_SB(0, 1), b2 + hstep, voffB); PG8_STAGE(PG8_SA(0, 0), a2, voffA);
;             PG8_WAIT_V(8); PG8_WAIT_L(0); PG8_BAR; PG8_MMA(1, 0, At, B0); PG8_MMA(1, 1, At, B1); PG8_BAR; PG8_SCHED;
;             PG8_LDB(B0, 1, 0); PG8_LDB(B1, 1, 1); PG8_SCHED; PG8_LDA(At, 1, 0); PG8_STAGE(PG8_SA(0, 1), a2 + hstep, voffA);
;             PG8_WAIT_V(8); PG8_WAIT_L(0); PG8_BAR; PG8_MMA(0, 0, At, B0); PG8_MMA(0, 1, At, B1); PG8_BAR; PG8_SCHED;
	s_add_i32 s55, s47, s34
	v_lshl_add_u64 v[218:219], s[24:25], 0, v[134:135]
	s_mov_b32 m0, s55
	ds_read_b128 v[186:189], v152 offset:16384
	ds_read_b128 v[190:193], v152 offset:17408
	ds_read_b128 v[194:197], v152 offset:18432
	ds_read_b128 v[198:201], v152 offset:19456
	ds_read_b128 v[202:205], v152 offset:20480
	ds_read_b128 v[206:209], v152 offset:21504
	ds_read_b128 v[210:213], v152 offset:22528
	ds_read_b128 v[214:217], v152 offset:23552
	global_load_lds_dwordx4 v[218:219], off
	s_add_i32 m0, s55, 0x2000
	s_add_u32 s56, s24, 0x40000
	v_lshl_add_u64 v[222:223], s[24:25], 0, v[130:131]
	s_addc_u32 s57, s25, 0
	s_add_i32 s55, s48, s34
	global_load_lds_dwordx4 v[222:223], off
	v_lshl_add_u64 v[224:225], s[56:57], 0, v[134:135]
	s_mov_b32 m0, s55
	v_lshl_add_u64 v[226:227], s[26:27], 0, v[132:133]
	global_load_lds_dwordx4 v[224:225], off
	v_lshl_add_u64 v[224:225], s[56:57], 0, v[130:131]
	s_add_i32 m0, s55, 0x2000
	s_nop 0
	global_load_lds_dwordx4 v[224:225], off
	v_lshl_add_u64 v[224:225], s[26:27], 0, v[136:137]
	s_mov_b32 m0, s37
	s_nop 0
	global_load_lds_dwordx4 v[224:225], off
	s_mov_b32 m0, s38
	s_nop 0
	global_load_lds_dwordx4 v[226:227], off
	s_waitcnt vmcnt(8) lgkmcnt(0)
	s_setprio 1
	s_barrier
	v_mfma_f32_16x16x32_bf16 v[62:65], v[154:157], v[186:189], v[62:65]
	v_mfma_f32_16x16x32_bf16 v[58:61], v[162:165], v[186:189], v[58:61]
	v_mfma_f32_16x16x32_bf16 v[46:49], v[154:157], v[194:197], v[46:49]
	v_mfma_f32_16x16x32_bf16 v[42:45], v[162:165], v[194:197], v[42:45]
	v_mfma_f32_16x16x32_bf16 v[30:33], v[154:157], v[202:205], v[30:33]
	v_mfma_f32_16x16x32_bf16 v[26:29], v[162:165], v[202:205], v[26:29]
	v_mfma_f32_16x16x32_bf16 v[14:17], v[154:157], v[210:213], v[14:17]
	v_mfma_f32_16x16x32_bf16 v[10:13], v[162:165], v[210:213], v[10:13]
	v_mfma_f32_16x16x32_bf16 v[62:65], v[158:161], v[190:193], v[62:65]
	v_mfma_f32_16x16x32_bf16 v[58:61], v[166:169], v[190:193], v[58:61]
	v_mfma_f32_16x16x32_bf16 v[46:49], v[158:161], v[198:201], v[46:49]
	v_mfma_f32_16x16x32_bf16 v[42:45], v[166:169], v[198:201], v[42:45]
	v_mfma_f32_16x16x32_bf16 v[30:33], v[158:161], v[206:209], v[30:33]
	v_mfma_f32_16x16x32_bf16 v[26:29], v[166:169], v[206:209], v[26:29]
	v_mfma_f32_16x16x32_bf16 v[14:17], v[158:161], v[214:217], v[14:17]
	v_mfma_f32_16x16x32_bf16 v[10:13], v[166:169], v[214:217], v[10:13]
	v_mfma_f32_16x16x32_bf16 v[54:57], v[170:173], v[186:189], v[54:57]
	v_mfma_f32_16x16x32_bf16 v[50:53], v[178:181], v[186:189], v[50:53]
	v_mfma_f32_16x16x32_bf16 v[38:41], v[170:173], v[194:197], v[38:41]
	v_mfma_f32_16x16x32_bf16 v[34:37], v[178:181], v[194:197], v[34:37]
	v_mfma_f32_16x16x32_bf16 v[22:25], v[170:173], v[202:205], v[22:25]
	v_mfma_f32_16x16x32_bf16 v[18:21], v[178:181], v[202:205], v[18:21]
	v_mfma_f32_16x16x32_bf16 v[6:9], v[170:173], v[210:213], v[6:9]
	v_mfma_f32_16x16x32_bf16 v[2:5], v[178:181], v[210:213], v[2:5]
	v_mfma_f32_16x16x32_bf16 v[54:57], v[174:177], v[190:193], v[54:57]
	v_mfma_f32_16x16x32_bf16 v[50:53], v[182:185], v[190:193], v[50:53]
	v_mfma_f32_16x16x32_bf16 v[38:41], v[174:177], v[198:201], v[38:41]
	v_mfma_f32_16x16x32_bf16 v[34:37], v[182:185], v[198:201], v[34:37]
	v_mfma_f32_16x16x32_bf16 v[22:25], v[174:177], v[206:209], v[22:25]
	v_mfma_f32_16x16x32_bf16 v[18:21], v[182:185], v[206:209], v[18:21]
	v_mfma_f32_16x16x32_bf16 v[6:9], v[174:177], v[214:217], v[6:9]
	v_mfma_f32_16x16x32_bf16 v[2:5], v[182:185], v[214:217], v[2:5]
	s_setprio 0
	s_barrier
.Lpz1_mid:
	s_add_i32 s55, 0, 0x18000
	v_add_u32_e32 v138, s55, v149
	s_add_i32 s56, 0, 0x1c000
	ds_read_b128 v[154:157], v138
	ds_read_b128 v[158:161], v138 offset:1024
	ds_read_b128 v[162:165], v138 offset:2048
	ds_read_b128 v[166:169], v138 offset:3072
	v_add_u32_e32 v138, s56, v149
	ds_read_b128 v[170:173], v138
	ds_read_b128 v[174:177], v138 offset:1024
	ds_read_b128 v[178:181], v138 offset:2048
	ds_read_b128 v[182:185], v138 offset:3072
	s_add_u32 s26, s26, 0x40000
	s_addc_u32 s27, s27, 0
	s_mov_b32 m0, s39
	v_lshl_add_u64 v[228:229], s[26:27], 0, v[136:137]
	ds_read_b128 v[186:189], v152 offset:32768
	ds_read_b128 v[190:193], v152 offset:33792
	ds_read_b128 v[194:197], v152 offset:34816
	ds_read_b128 v[198:201], v152 offset:35840
	ds_read_b128 v[202:205], v152 offset:36864
	ds_read_b128 v[206:209], v152 offset:37888
	ds_read_b128 v[210:213], v152 offset:38912
	ds_read_b128 v[214:217], v152 offset:39936
	global_load_lds_dwordx4 v[228:229], off
	v_lshl_add_u64 v[228:229], s[26:27], 0, v[132:133]
	s_mov_b32 m0, s40
	s_nop 0
	global_load_lds_dwordx4 v[228:229], off
	s_waitcnt vmcnt(8) lgkmcnt(0)
	s_setprio 1
	s_barrier
; #define PG8_STAGE(bufoff, gbase, voff) do { _Pragma("unroll") for (int _i = 0; _i < 2; ++_i) \
;         __builtin_amdgcn_global_load_lds((const unsigned*)((const char*)(gbase) + (voff)[_i]), (PG8_LAS unsigned*)(lds + (bufoff) + ldsw + _i * 8192), 16, 0, 0); } while (0)
; #define PG8_LDA(dst, b, h) do { _Pragma("unroll") for (int m = 0; m < 4; ++m) _Pragma("unroll") for (int k = 0; k < 2; ++k) dst[m][k] = *(const PG8_LAS bf16x8*)(lds + PG8_SA(b, h) + aoff + m * 2048 + k * 1024); } while (0)
; #define PG8_MMA(ai, bj, At, Bt) do { __builtin_amdgcn_s_setprio(1); _Pragma("unroll") for (int m = 0; m < 4; ++m) _Pragma("unroll") for (int n = 0; n < 2; ++n) _Pragma("unroll") for (int k = 0; k < 2; ++k) \
;         acc[ai][bj][m][n] = __builtin_amdgcn_mfma_f32_16x16x32_bf16(Bt[n][k], At[m][k], acc[ai][bj][m][n], 0, 0, 0); __builtin_amdgcn_s_setprio(0); } while (0)
; #define PG8_WAIT_V(n) asm volatile("s_waitcnt vmcnt(" #n ")" ::: "memory")
; #define PG8_WAIT_L(n) asm volatile("s_waitcnt lgkmcnt(" #n ")" ::: "memory")
; #define PG8_BAR __builtin_amdgcn_s_barrier()
; #define PG8_SCHED __builtin_amdgcn_sched_barrier(0)
; template <class Epi, class Sched, bool ALIGN_EPI = false, bool SP2 = false>
; __device__ __forceinline__ void gemm_phase(PG8_LAS unsigned char* lds, const Gemm g, const Sched& S, const Epi& E) {
;     ...
;         for (int t = 0; t < nt; t += 2) {
;             const bool last = (t == nt - 2);
;     ...
;             PG8_WAIT_V(8); PG8_WAIT_L(0); PG8_BAR; PG8_MMA(0, 0, At, B0); PG8_MMA(0, 1, At, B1); PG8_BAR; PG8_SCHED;
;             PG8_LDA(At, 1, 1); PG8_STAGE(PG8_SB(1, 0), b3, voffB); PG8_STAGE(PG8_SB(1, 1), b3 + hstep, voffB); PG8_STAGE(PG8_SA(1, 0), a3, voffA);
;             PG8_WAIT_V(8); PG8_WAIT_L(0); PG8_BAR; PG8_MMA(1, 0, At, B0); PG8_MMA(1, 1, At, B1); PG8_BAR; PG8_SCHED;
	v_mfma_f32_16x16x32_bf16 v[126:129], v[154:157], v[186:189], v[126:129]
	v_mfma_f32_16x16x32_bf16 v[122:125], v[162:165], v[186:189], v[122:125]
	v_mfma_f32_16x16x32_bf16 v[110:113], v[154:157], v[194:197], v[110:113]
	v_mfma_f32_16x16x32_bf16 v[106:109], v[162:165], v[194:197], v[106:109]
	v_mfma_f32_16x16x32_bf16 v[94:97], v[154:157], v[202:205], v[94:97]
	v_mfma_f32_16x16x32_bf16 v[90:93], v[162:165], v[202:205], v[90:93]
	v_mfma_f32_16x16x32_bf16 v[78:81], v[154:157], v[210:213], v[78:81]
	v_mfma_f32_16x16x32_bf16 v[74:77], v[162:165], v[210:213], v[74:77]
	v_mfma_f32_16x16x32_bf16 v[126:129], v[158:161], v[190:193], v[126:129]
	v_mfma_f32_16x16x32_bf16 v[122:125], v[166:169], v[190:193], v[122:125]
	v_mfma_f32_16x16x32_bf16 v[110:113], v[158:161], v[198:201], v[110:113]
	v_mfma_f32_16x16x32_bf16 v[106:109], v[166:169], v[198:201], v[106:109]
	v_mfma_f32_16x16x32_bf16 v[94:97], v[158:161], v[206:209], v[94:97]
	v_mfma_f32_16x16x32_bf16 v[90:93], v[166:169], v[206:209], v[90:93]
	v_mfma_f32_16x16x32_bf16 v[78:81], v[158:161], v[214:217], v[78:81]
	v_mfma_f32_16x16x32_bf16 v[74:77], v[166:169], v[214:217], v[74:77]
	v_mfma_f32_16x16x32_bf16 v[118:121], v[170:173], v[186:189], v[118:121]
	v_mfma_f32_16x16x32_bf16 v[114:117], v[178:181], v[186:189], v[114:117]
	v_mfma_f32_16x16x32_bf16 v[102:105], v[170:173], v[194:197], v[102:105]
	v_mfma_f32_16x16x32_bf16 v[98:101], v[178:181], v[194:197], v[98:101]
	v_mfma_f32_16x16x32_bf16 v[86:89], v[170:173], v[202:205], v[86:89]
	v_mfma_f32_16x16x32_bf16 v[82:85], v[178:181], v[202:205], v[82:85]
	v_mfma_f32_16x16x32_bf16 v[70:73], v[170:173], v[210:213], v[70:73]
	v_mfma_f32_16x16x32_bf16 v[66:69], v[178:181], v[210:213], v[66:69]
	v_mfma_f32_16x16x32_bf16 v[118:121], v[174:177], v[190:193], v[118:121]
	v_mfma_f32_16x16x32_bf16 v[114:117], v[182:185], v[190:193], v[114:117]
	v_mfma_f32_16x16x32_bf16 v[102:105], v[174:177], v[198:201], v[102:105]
	v_mfma_f32_16x16x32_bf16 v[98:101], v[182:185], v[198:201], v[98:101]
	v_mfma_f32_16x16x32_bf16 v[86:89], v[174:177], v[206:209], v[86:89]
	v_mfma_f32_16x16x32_bf16 v[82:85], v[182:185], v[206:209], v[82:85]
	v_mfma_f32_16x16x32_bf16 v[70:73], v[174:177], v[214:217], v[70:73]
	v_mfma_f32_16x16x32_bf16 v[66:69], v[182:185], v[214:217], v[66:69]
	s_setprio 0
	s_barrier
	s_add_i32 s26, s55, s34
	v_lshl_add_u64 v[218:219], v[218:219], 0, s[8:9]
	s_mov_b32 m0, s26
	ds_read_b128 v[186:189], v152 offset:49152
	ds_read_b128 v[190:193], v152 offset:50176
	ds_read_b128 v[194:197], v152 offset:51200
	ds_read_b128 v[198:201], v152 offset:52224
	ds_read_b128 v[202:205], v152 offset:53248
	ds_read_b128 v[206:209], v152 offset:54272
	ds_read_b128 v[210:213], v152 offset:55296
	ds_read_b128 v[214:217], v152 offset:56320
	global_load_lds_dwordx4 v[218:219], off
	s_add_i32 m0, s26, 0x2000
	s_add_u32 s24, s24, 0x40080
	v_lshl_add_u64 v[218:219], v[222:223], 0, s[8:9]
	s_addc_u32 s25, s25, 0
	s_add_i32 s26, s56, s34
	global_load_lds_dwordx4 v[218:219], off
	v_lshl_add_u64 v[218:219], s[24:25], 0, v[134:135]
	s_mov_b32 m0, s26
	s_nop 0
	global_load_lds_dwordx4 v[218:219], off
	v_lshl_add_u64 v[218:219], s[24:25], 0, v[130:131]
	s_add_i32 m0, s26, 0x2000
	s_nop 0
	global_load_lds_dwordx4 v[218:219], off
	v_lshl_add_u64 v[218:219], v[224:225], 0, s[8:9]
	s_mov_b32 m0, s42
	s_nop 0
	global_load_lds_dwordx4 v[218:219], off
	v_lshl_add_u64 v[218:219], v[226:227], 0, s[8:9]
	s_mov_b32 m0, s43
	s_nop 0
	global_load_lds_dwordx4 v[218:219], off
	s_waitcnt vmcnt(8) lgkmcnt(0)
	s_setprio 1
	s_barrier
	v_mfma_f32_16x16x32_bf16 v[62:65], v[154:157], v[186:189], v[62:65]
	v_mfma_f32_16x16x32_bf16 v[58:61], v[162:165], v[186:189], v[58:61]
	v_mfma_f32_16x16x32_bf16 v[46:49], v[154:157], v[194:197], v[46:49]
	v_mfma_f32_16x16x32_bf16 v[42:45], v[162:165], v[194:197], v[42:45]
	v_mfma_f32_16x16x32_bf16 v[30:33], v[154:157], v[202:205], v[30:33]
	v_mfma_f32_16x16x32_bf16 v[26:29], v[162:165], v[202:205], v[26:29]
	v_mfma_f32_16x16x32_bf16 v[14:17], v[154:157], v[210:213], v[14:17]
	v_mfma_f32_16x16x32_bf16 v[10:13], v[162:165], v[210:213], v[10:13]
	v_mfma_f32_16x16x32_bf16 v[62:65], v[158:161], v[190:193], v[62:65]
	v_mfma_f32_16x16x32_bf16 v[58:61], v[166:169], v[190:193], v[58:61]
	v_mfma_f32_16x16x32_bf16 v[46:49], v[158:161], v[198:201], v[46:49]
	v_mfma_f32_16x16x32_bf16 v[42:45], v[166:169], v[198:201], v[42:45]
	v_mfma_f32_16x16x32_bf16 v[30:33], v[158:161], v[206:209], v[30:33]
	v_mfma_f32_16x16x32_bf16 v[26:29], v[166:169], v[206:209], v[26:29]
	v_mfma_f32_16x16x32_bf16 v[14:17], v[158:161], v[214:217], v[14:17]
	v_mfma_f32_16x16x32_bf16 v[10:13], v[166:169], v[214:217], v[10:13]
	v_mfma_f32_16x16x32_bf16 v[54:57], v[170:173], v[186:189], v[54:57]
	v_mfma_f32_16x16x32_bf16 v[50:53], v[178:181], v[186:189], v[50:53]
	v_mfma_f32_16x16x32_bf16 v[38:41], v[170:173], v[194:197], v[38:41]
	v_mfma_f32_16x16x32_bf16 v[34:37], v[178:181], v[194:197], v[34:37]
	v_mfma_f32_16x16x32_bf16 v[22:25], v[170:173], v[202:205], v[22:25]
	v_mfma_f32_16x16x32_bf16 v[18:21], v[178:181], v[202:205], v[18:21]
	v_mfma_f32_16x16x32_bf16 v[6:9], v[170:173], v[210:213], v[6:9]
	v_mfma_f32_16x16x32_bf16 v[2:5], v[178:181], v[210:213], v[2:5]
	v_mfma_f32_16x16x32_bf16 v[54:57], v[174:177], v[190:193], v[54:57]
	v_mfma_f32_16x16x32_bf16 v[50:53], v[182:185], v[190:193], v[50:53]
	v_mfma_f32_16x16x32_bf16 v[38:41], v[174:177], v[198:201], v[38:41]
	v_mfma_f32_16x16x32_bf16 v[34:37], v[182:185], v[198:201], v[34:37]
	v_mfma_f32_16x16x32_bf16 v[22:25], v[174:177], v[206:209], v[22:25]
	v_mfma_f32_16x16x32_bf16 v[18:21], v[182:185], v[206:209], v[18:21]
	v_mfma_f32_16x16x32_bf16 v[6:9], v[174:177], v[214:217], v[6:9]
	v_mfma_f32_16x16x32_bf16 v[2:5], v[182:185], v[214:217], v[2:5]
	s_setprio 0
	s_barrier
	s_add_i32 s54, s54, 2
	s_add_u32 s22, s22, 0x100
	s_addc_u32 s23, s23, 0
	s_add_u32 s52, s52, 0x100
	s_addc_u32 s53, s53, 0
	s_cmp_gt_u32 s54, 13
	s_cbranch_scc0 .LBB0_208
	s_and_b64 vcc, exec, s[10:11]
	s_cbranch_vccz .LBB0_211
	s_barrier

; #define PG8_STAGE(bufoff, gbase, voff) do { _Pragma("unroll") for (int _i = 0; _i < 2; ++_i) \
;         __builtin_amdgcn_global_load_lds((const unsigned*)((const char*)(gbase) + (voff)[_i]), (PG8_LAS unsigned*)(lds + (bufoff) + ldsw + _i * 8192), 16, 0, 0); } while (0)
; #define PG8_LDA(dst, b, h) do { _Pragma("unroll") for (int m = 0; m < 4; ++m) _Pragma("unroll") for (int k = 0; k < 2; ++k) dst[m][k] = *(const PG8_LAS bf16x8*)(lds + PG8_SA(b, h) + aoff + m * 2048 + k * 1024); } while (0)
; #define PG8_LDB(dst, b, h) do { _Pragma("unroll") for (int n = 0; n < 2; ++n) _Pragma("unroll") for (int k = 0; k < 2; ++k) dst[n][k] = *(const PG8_LAS bf16x8*)(lds + PG8_SB(b, h) + boff + n * 2048 + k * 1024); } while (0)
; #define PG8_MMA(ai, bj, At, Bt) do { __builtin_amdgcn_s_setprio(1); _Pragma("unroll") for (int m = 0; m < 4; ++m) _Pragma("unroll") for (int n = 0; n < 2; ++n) _Pragma("unroll") for (int k = 0; k < 2; ++k) \
;         acc[ai][bj][m][n] = __builtin_amdgcn_mfma_f32_16x16x32_bf16(Bt[n][k], At[m][k], acc[ai][bj][m][n], 0, 0, 0); __builtin_amdgcn_s_setprio(0); } while (0)
; #define PG8_WAIT_V(n) asm volatile("s_waitcnt vmcnt(" #n ")" ::: "memory")
; #define PG8_WAIT_L(n) asm volatile("s_waitcnt lgkmcnt(" #n ")" ::: "memory")
; template <class Epi, class Sched, bool ALIGN_EPI = false, bool SP2 = false>
; __device__ __forceinline__ void gemm_phase(PG8_LAS unsigned char* lds, const Gemm g, const Sched& S, const Epi& E) {
;     ...
;     f32x4 acc[2][2][4][2];
; #pragma unroll
;     for (int a = 0; a < 2; ++a)
; #pragma unroll
;         for (int b = 0; b < 2; ++b)
; #pragma unroll
;             for (int m = 0; m < 4; ++m)
; #pragma unroll
;                 for (int n = 0; n < 2; ++n) acc[a][b][m][n] = (f32x4){0.f, 0.f, 0.f, 0.f};
;     ...
;             PG8_LDB(B0, 0, 0); PG8_LDB(B1, 0, 1); PG8_SCHED; PG8_LDA(At, 0, 0); PG8_STAGE(PG8_SA(1, 1), a1 + hstep, voffA);
;             PG8_WAIT_V(8); PG8_WAIT_L(0); PG8_BAR; PG8_MMA(0, 0, At, B0); PG8_MMA(0, 1, At, B1); PG8_BAR; PG8_SCHED;
;             if constexpr (Epi::PREFETCH) { if (t == tpf) E.prefetch(cur, wid, lane); }
;             PG8_LDA(At, 0, 1); PG8_STAGE(PG8_SB(0, 0), b2, voffB); PG8_STAGE(PG8_SB(0, 1), b2 + hstep, voffB); PG8_STAGE(PG8_SA(0, 0), a2, voffA);
;             PG8_WAIT_V(8); PG8_WAIT_L(0); PG8_BAR; PG8_MMA(1, 0, At, B0); PG8_MMA(1, 1, At, B1); PG8_BAR; PG8_SCHED;
.LBB0_288:
	s_add_u32 s39, s6, 0x100
	s_addc_u32 s40, s7, 0
	s_mov_b32 s41, -2
	ds_read_b128 v[130:133], v223
	ds_read_b128 v[134:137], v223 offset:1024
	ds_read_b128 v[138:141], v223 offset:2048
	ds_read_b128 v[142:145], v223 offset:3072
	ds_read_b128 v[164:167], v224
	ds_read_b128 v[168:171], v224 offset:1024
	ds_read_b128 v[172:175], v224 offset:2048
	ds_read_b128 v[176:179], v224 offset:3072
	s_add_u32 s0, s4, 0x200
	s_addc_u32 s1, s5, 0
	s_cmp_eq_u32 s41, 40
	s_cselect_b32 s37, s31, s1
	s_cselect_b32 s36, s30, s0
	s_cselect_b32 s7, s35, s40
	s_cselect_b32 s6, s34, s39
	v_lshl_add_u64 v[160:161], s[4:5], 0, v[156:157]
	s_add_i32 m0, s51, 0xc000
	ds_read_b128 v[180:183], v225
	ds_read_b128 v[184:187], v225 offset:1024
	ds_read_b128 v[188:191], v225 offset:2048
	ds_read_b128 v[192:195], v225 offset:3072
	ds_read_b128 v[196:199], v225 offset:4096
	ds_read_b128 v[200:203], v225 offset:5120
	ds_read_b128 v[204:207], v225 offset:6144
	ds_read_b128 v[208:211], v225 offset:7168
	global_load_lds_dwordx4 v[160:161], off
	v_lshl_add_u64 v[160:161], s[4:5], 0, v[158:159]
	s_add_i32 m0, s51, 0xe000
	s_nop 0
	global_load_lds_dwordx4 v[160:161], off
	s_waitcnt vmcnt(8) lgkmcnt(0)
	s_setprio 1
	s_barrier
	v_mfma_f32_16x16x32_bf16 v[126:129], v[130:133], v[180:183], 0
	v_mfma_f32_16x16x32_bf16 v[122:125], v[138:141], v[180:183], 0
	v_mfma_f32_16x16x32_bf16 v[110:113], v[130:133], v[188:191], 0
	v_mfma_f32_16x16x32_bf16 v[106:109], v[138:141], v[188:191], 0
	v_mfma_f32_16x16x32_bf16 v[94:97], v[130:133], v[196:199], 0
	v_mfma_f32_16x16x32_bf16 v[90:93], v[138:141], v[196:199], 0
	v_mfma_f32_16x16x32_bf16 v[78:81], v[130:133], v[204:207], 0
	v_mfma_f32_16x16x32_bf16 v[74:77], v[138:141], v[204:207], 0
	v_mfma_f32_16x16x32_bf16 v[126:129], v[134:137], v[184:187], v[126:129]
	v_mfma_f32_16x16x32_bf16 v[122:125], v[142:145], v[184:187], v[122:125]
	v_mfma_f32_16x16x32_bf16 v[110:113], v[134:137], v[192:195], v[110:113]
	v_mfma_f32_16x16x32_bf16 v[106:109], v[142:145], v[192:195], v[106:109]
	v_mfma_f32_16x16x32_bf16 v[94:97], v[134:137], v[200:203], v[94:97]
	v_mfma_f32_16x16x32_bf16 v[90:93], v[142:145], v[200:203], v[90:93]
	v_mfma_f32_16x16x32_bf16 v[78:81], v[134:137], v[208:211], v[78:81]
	v_mfma_f32_16x16x32_bf16 v[74:77], v[142:145], v[208:211], v[74:77]
	v_mfma_f32_16x16x32_bf16 v[118:121], v[164:167], v[180:183], 0
	v_mfma_f32_16x16x32_bf16 v[114:117], v[172:175], v[180:183], 0
	v_mfma_f32_16x16x32_bf16 v[102:105], v[164:167], v[188:191], 0
	v_mfma_f32_16x16x32_bf16 v[98:101], v[172:175], v[188:191], 0
	v_mfma_f32_16x16x32_bf16 v[86:89], v[164:167], v[196:199], 0
	v_mfma_f32_16x16x32_bf16 v[82:85], v[172:175], v[196:199], 0
	v_mfma_f32_16x16x32_bf16 v[70:73], v[164:167], v[204:207], 0
	v_mfma_f32_16x16x32_bf16 v[66:69], v[172:175], v[204:207], 0
	v_mfma_f32_16x16x32_bf16 v[118:121], v[168:171], v[184:187], v[118:121]
	v_mfma_f32_16x16x32_bf16 v[114:117], v[176:179], v[184:187], v[114:117]
	v_mfma_f32_16x16x32_bf16 v[102:105], v[168:171], v[192:195], v[102:105]
	v_mfma_f32_16x16x32_bf16 v[98:101], v[176:179], v[192:195], v[98:101]
	v_mfma_f32_16x16x32_bf16 v[86:89], v[168:171], v[200:203], v[86:89]
	v_mfma_f32_16x16x32_bf16 v[82:85], v[176:179], v[200:203], v[82:85]
	v_mfma_f32_16x16x32_bf16 v[70:73], v[168:171], v[208:211], v[70:73]
	v_mfma_f32_16x16x32_bf16 v[66:69], v[176:179], v[208:211], v[66:69]
	s_setprio 0
	s_barrier
	s_add_i32 s4, s68, s50
	v_lshl_add_u64 v[160:161], s[6:7], 0, v[148:149]
	s_mov_b32 m0, s4
	ds_read_b128 v[180:183], v225 offset:16384
	ds_read_b128 v[184:187], v225 offset:17408
	ds_read_b128 v[188:191], v225 offset:18432
	ds_read_b128 v[192:195], v225 offset:19456
	ds_read_b128 v[196:199], v225 offset:20480
	ds_read_b128 v[200:203], v225 offset:21504
	ds_read_b128 v[204:207], v225 offset:22528
	ds_read_b128 v[208:211], v225 offset:23552
	global_load_lds_dwordx4 v[160:161], off
	s_add_i32 m0, s4, 0x2000
	s_add_u32 s4, s6, 0xb0000
	v_lshl_add_u64 v[162:163], s[6:7], 0, v[152:153]
	s_addc_u32 s5, s7, 0
	s_add_i32 s42, s69, s50
	global_load_lds_dwordx4 v[162:163], off
	v_lshl_add_u64 v[212:213], s[4:5], 0, v[148:149]
	s_mov_b32 m0, s42
	v_lshl_add_u64 v[214:215], s[36:37], 0, v[150:151]
	global_load_lds_dwordx4 v[212:213], off
	v_lshl_add_u64 v[212:213], s[4:5], 0, v[152:153]
	s_add_i32 m0, s42, 0x2000
	s_nop 0
	global_load_lds_dwordx4 v[212:213], off
	v_lshl_add_u64 v[212:213], s[36:37], 0, v[146:147]
	s_mov_b32 m0, s51
	s_nop 0
	global_load_lds_dwordx4 v[212:213], off
	s_mov_b32 m0, s52
	s_nop 0
	global_load_lds_dwordx4 v[214:215], off
	s_waitcnt vmcnt(8) lgkmcnt(0)
	s_setprio 1
	s_barrier
	v_mfma_f32_16x16x32_bf16 v[62:65], v[130:133], v[180:183], 0
	v_mfma_f32_16x16x32_bf16 v[58:61], v[138:141], v[180:183], 0
	v_mfma_f32_16x16x32_bf16 v[46:49], v[130:133], v[188:191], 0
	v_mfma_f32_16x16x32_bf16 v[42:45], v[138:141], v[188:191], 0
	v_mfma_f32_16x16x32_bf16 v[30:33], v[130:133], v[196:199], 0
	v_mfma_f32_16x16x32_bf16 v[26:29], v[138:141], v[196:199], 0
	v_mfma_f32_16x16x32_bf16 v[14:17], v[130:133], v[204:207], 0
	v_mfma_f32_16x16x32_bf16 v[10:13], v[138:141], v[204:207], 0
	v_mfma_f32_16x16x32_bf16 v[62:65], v[134:137], v[184:187], v[62:65]
	v_mfma_f32_16x16x32_bf16 v[58:61], v[142:145], v[184:187], v[58:61]
	v_mfma_f32_16x16x32_bf16 v[46:49], v[134:137], v[192:195], v[46:49]
	v_mfma_f32_16x16x32_bf16 v[42:45], v[142:145], v[192:195], v[42:45]
	v_mfma_f32_16x16x32_bf16 v[30:33], v[134:137], v[200:203], v[30:33]
	v_mfma_f32_16x16x32_bf16 v[26:29], v[142:145], v[200:203], v[26:29]
	v_mfma_f32_16x16x32_bf16 v[14:17], v[134:137], v[208:211], v[14:17]
	v_mfma_f32_16x16x32_bf16 v[10:13], v[142:145], v[208:211], v[10:13]
	v_mfma_f32_16x16x32_bf16 v[54:57], v[164:167], v[180:183], 0
	v_mfma_f32_16x16x32_bf16 v[50:53], v[172:175], v[180:183], 0
	v_mfma_f32_16x16x32_bf16 v[38:41], v[164:167], v[188:191], 0
	v_mfma_f32_16x16x32_bf16 v[34:37], v[172:175], v[188:191], 0
	v_mfma_f32_16x16x32_bf16 v[22:25], v[164:167], v[196:199], 0
	v_mfma_f32_16x16x32_bf16 v[18:21], v[172:175], v[196:199], 0
	v_mfma_f32_16x16x32_bf16 v[6:9], v[164:167], v[204:207], 0
	v_mfma_f32_16x16x32_bf16 v[2:5], v[172:175], v[204:207], 0
	v_mfma_f32_16x16x32_bf16 v[54:57], v[168:171], v[184:187], v[54:57]
	v_mfma_f32_16x16x32_bf16 v[50:53], v[176:179], v[184:187], v[50:53]
	v_mfma_f32_16x16x32_bf16 v[38:41], v[168:171], v[192:195], v[38:41]
	v_mfma_f32_16x16x32_bf16 v[34:37], v[176:179], v[192:195], v[34:37]
	v_mfma_f32_16x16x32_bf16 v[22:25], v[168:171], v[200:203], v[22:25]
	v_mfma_f32_16x16x32_bf16 v[18:21], v[176:179], v[200:203], v[18:21]
	v_mfma_f32_16x16x32_bf16 v[6:9], v[168:171], v[208:211], v[6:9]
	v_mfma_f32_16x16x32_bf16 v[2:5], v[176:179], v[208:211], v[2:5]
	s_setprio 0
	s_barrier
	s_branch .Lpz2_mid
; #define PG8_STAGE(bufoff, gbase, voff) do { _Pragma("unroll") for (int _i = 0; _i < 2; ++_i) \
;         __builtin_amdgcn_global_load_lds((const unsigned*)((const char*)(gbase) + (voff)[_i]), (PG8_LAS unsigned*)(lds + (bufoff) + ldsw + _i * 8192), 16, 0, 0); } while (0)
; #define PG8_LDA(dst, b, h) do { _Pragma("unroll") for (int m = 0; m < 4; ++m) _Pragma("unroll") for (int k = 0; k < 2; ++k) dst[m][k] = *(const PG8_LAS bf16x8*)(lds + PG8_SA(b, h) + aoff + m * 2048 + k * 1024); } while (0)
; #define PG8_LDB(dst, b, h) do { _Pragma("unroll") for (int n = 0; n < 2; ++n) _Pragma("unroll") for (int k = 0; k < 2; ++k) dst[n][k] = *(const PG8_LAS bf16x8*)(lds + PG8_SB(b, h) + boff + n * 2048 + k * 1024); } while (0)
; #define PG8_MMA(ai, bj, At, Bt) do { __builtin_amdgcn_s_setprio(1); _Pragma("unroll") for (int m = 0; m < 4; ++m) _Pragma("unroll") for (int n = 0; n < 2; ++n) _Pragma("unroll") for (int k = 0; k < 2; ++k) \
;         acc[ai][bj][m][n] = __builtin_amdgcn_mfma_f32_16x16x32_bf16(Bt[n][k], At[m][k], acc[ai][bj][m][n], 0, 0, 0); __builtin_amdgcn_s_setprio(0); } while (0)
; #define PG8_WAIT_V(n) asm volatile("s_waitcnt vmcnt(" #n ")" ::: "memory")
; #define PG8_WAIT_L(n) asm volatile("s_waitcnt lgkmcnt(" #n ")" ::: "memory")
; #define PG8_BAR __builtin_amdgcn_s_barrier()
; #define PG8_SCHED __builtin_amdgcn_sched_barrier(0)
;     __device__ __forceinline__ void prefetch(const Unit& u, int wid, int lane) const { epi_prefetch(scr, ssq, bias + (size_t)(u.pm >> 5) * NGU + u.pn * BM, u, wid, lane); }
; template <class Epi, class Sched, bool ALIGN_EPI = false, bool SP2 = false>
; __device__ __forceinline__ void gemm_phase(PG8_LAS unsigned char* lds, const Gemm g, const Sched& S, const Epi& E) {
;     ...
;             PG8_LDB(B0, 0, 0); PG8_LDB(B1, 0, 1); PG8_SCHED; PG8_LDA(At, 0, 0); PG8_STAGE(PG8_SA(1, 1), a1 + hstep, voffA);
;             PG8_WAIT_V(8); PG8_WAIT_L(0); PG8_BAR; PG8_MMA(0, 0, At, B0); PG8_MMA(0, 1, At, B1); PG8_BAR; PG8_SCHED;
;             if constexpr (Epi::PREFETCH) { if (t == tpf) E.prefetch(cur, wid, lane); }
;             PG8_LDA(At, 0, 1); PG8_STAGE(PG8_SB(0, 0), b2, voffB); PG8_STAGE(PG8_SB(0, 1), b2 + hstep, voffB); PG8_STAGE(PG8_SA(0, 0), a2, voffA);
;             PG8_WAIT_V(8); PG8_WAIT_L(0); PG8_BAR; PG8_MMA(1, 0, At, B0); PG8_MMA(1, 1, At, B1); PG8_BAR; PG8_SCHED;
.LBB0_289:
	ds_read_b128 v[130:133], v223
	ds_read_b128 v[134:137], v223 offset:1024
	ds_read_b128 v[138:141], v223 offset:2048
	ds_read_b128 v[142:145], v223 offset:3072
	ds_read_b128 v[164:167], v224
	ds_read_b128 v[168:171], v224 offset:1024
	ds_read_b128 v[172:175], v224 offset:2048
	ds_read_b128 v[176:179], v224 offset:3072
	s_add_u32 s0, s4, 0x200
	s_addc_u32 s1, s5, 0
	s_cmp_eq_u32 s41, 40
	s_cselect_b32 s37, s31, s1
	s_cselect_b32 s36, s30, s0
	s_cselect_b32 s7, s35, s40
	s_cselect_b32 s6, s34, s39
	v_lshl_add_u64 v[160:161], s[4:5], 0, v[156:157]
	s_add_i32 m0, s51, 0xc000
	ds_read_b128 v[180:183], v225
	ds_read_b128 v[184:187], v225 offset:1024
	ds_read_b128 v[188:191], v225 offset:2048
	ds_read_b128 v[192:195], v225 offset:3072
	ds_read_b128 v[196:199], v225 offset:4096
	ds_read_b128 v[200:203], v225 offset:5120
	ds_read_b128 v[204:207], v225 offset:6144
	ds_read_b128 v[208:211], v225 offset:7168
	global_load_lds_dwordx4 v[160:161], off
	v_lshl_add_u64 v[160:161], s[4:5], 0, v[158:159]
	s_add_i32 m0, s51, 0xe000
	s_nop 0
	global_load_lds_dwordx4 v[160:161], off
	s_waitcnt vmcnt(8) lgkmcnt(0)
	s_setprio 1
	s_barrier
	v_mfma_f32_16x16x32_bf16 v[126:129], v[130:133], v[180:183], v[126:129]
	v_mfma_f32_16x16x32_bf16 v[122:125], v[138:141], v[180:183], v[122:125]
	v_mfma_f32_16x16x32_bf16 v[110:113], v[130:133], v[188:191], v[110:113]
	v_mfma_f32_16x16x32_bf16 v[106:109], v[138:141], v[188:191], v[106:109]
	v_mfma_f32_16x16x32_bf16 v[94:97], v[130:133], v[196:199], v[94:97]
	v_mfma_f32_16x16x32_bf16 v[90:93], v[138:141], v[196:199], v[90:93]
	v_mfma_f32_16x16x32_bf16 v[78:81], v[130:133], v[204:207], v[78:81]
	v_mfma_f32_16x16x32_bf16 v[74:77], v[138:141], v[204:207], v[74:77]
	v_mfma_f32_16x16x32_bf16 v[126:129], v[134:137], v[184:187], v[126:129]
	v_mfma_f32_16x16x32_bf16 v[122:125], v[142:145], v[184:187], v[122:125]
	v_mfma_f32_16x16x32_bf16 v[110:113], v[134:137], v[192:195], v[110:113]
	v_mfma_f32_16x16x32_bf16 v[106:109], v[142:145], v[192:195], v[106:109]
	v_mfma_f32_16x16x32_bf16 v[94:97], v[134:137], v[200:203], v[94:97]
	v_mfma_f32_16x16x32_bf16 v[90:93], v[142:145], v[200:203], v[90:93]
	v_mfma_f32_16x16x32_bf16 v[78:81], v[134:137], v[208:211], v[78:81]
	v_mfma_f32_16x16x32_bf16 v[74:77], v[142:145], v[208:211], v[74:77]
	v_mfma_f32_16x16x32_bf16 v[118:121], v[164:167], v[180:183], v[118:121]
	v_mfma_f32_16x16x32_bf16 v[114:117], v[172:175], v[180:183], v[114:117]
	v_mfma_f32_16x16x32_bf16 v[102:105], v[164:167], v[188:191], v[102:105]
	v_mfma_f32_16x16x32_bf16 v[98:101], v[172:175], v[188:191], v[98:101]
	v_mfma_f32_16x16x32_bf16 v[86:89], v[164:167], v[196:199], v[86:89]
	v_mfma_f32_16x16x32_bf16 v[82:85], v[172:175], v[196:199], v[82:85]
	v_mfma_f32_16x16x32_bf16 v[70:73], v[164:167], v[204:207], v[70:73]
	v_mfma_f32_16x16x32_bf16 v[66:69], v[172:175], v[204:207], v[66:69]
	v_mfma_f32_16x16x32_bf16 v[118:121], v[168:171], v[184:187], v[118:121]
	v_mfma_f32_16x16x32_bf16 v[114:117], v[176:179], v[184:187], v[114:117]
	v_mfma_f32_16x16x32_bf16 v[102:105], v[168:171], v[192:195], v[102:105]
	v_mfma_f32_16x16x32_bf16 v[98:101], v[176:179], v[192:195], v[98:101]
	v_mfma_f32_16x16x32_bf16 v[86:89], v[168:171], v[200:203], v[86:89]
	v_mfma_f32_16x16x32_bf16 v[82:85], v[176:179], v[200:203], v[82:85]
	v_mfma_f32_16x16x32_bf16 v[70:73], v[168:171], v[208:211], v[70:73]
	v_mfma_f32_16x16x32_bf16 v[66:69], v[176:179], v[208:211], v[66:69]
	s_setprio 0
	s_barrier
	s_add_i32 s4, s68, s50
	v_lshl_add_u64 v[160:161], s[6:7], 0, v[148:149]
	s_mov_b32 m0, s4
	ds_read_b128 v[180:183], v225 offset:16384
	ds_read_b128 v[184:187], v225 offset:17408
	ds_read_b128 v[188:191], v225 offset:18432
	ds_read_b128 v[192:195], v225 offset:19456
	ds_read_b128 v[196:199], v225 offset:20480
	ds_read_b128 v[200:203], v225 offset:21504
	ds_read_b128 v[204:207], v225 offset:22528
	ds_read_b128 v[208:211], v225 offset:23552
	global_load_lds_dwordx4 v[160:161], off
	s_add_i32 m0, s4, 0x2000
	s_add_u32 s4, s6, 0xb0000
	v_lshl_add_u64 v[162:163], s[6:7], 0, v[152:153]
	s_addc_u32 s5, s7, 0
	s_add_i32 s42, s69, s50
	global_load_lds_dwordx4 v[162:163], off
	v_lshl_add_u64 v[212:213], s[4:5], 0, v[148:149]
	s_mov_b32 m0, s42
	v_lshl_add_u64 v[214:215], s[36:37], 0, v[150:151]
	global_load_lds_dwordx4 v[212:213], off
	v_lshl_add_u64 v[212:213], s[4:5], 0, v[152:153]
	s_add_i32 m0, s42, 0x2000
	s_nop 0
	global_load_lds_dwordx4 v[212:213], off
	v_lshl_add_u64 v[212:213], s[36:37], 0, v[146:147]
	s_mov_b32 m0, s51
	s_nop 0
	global_load_lds_dwordx4 v[212:213], off
	s_mov_b32 m0, s52
	s_nop 0
	global_load_lds_dwordx4 v[214:215], off
	s_waitcnt vmcnt(8) lgkmcnt(0)
	s_setprio 1
	s_barrier
	v_mfma_f32_16x16x32_bf16 v[62:65], v[130:133], v[180:183], v[62:65]
	v_mfma_f32_16x16x32_bf16 v[58:61], v[138:141], v[180:183], v[58:61]
	v_mfma_f32_16x16x32_bf16 v[46:49], v[130:133], v[188:191], v[46:49]
	v_mfma_f32_16x16x32_bf16 v[42:45], v[138:141], v[188:191], v[42:45]
	v_mfma_f32_16x16x32_bf16 v[30:33], v[130:133], v[196:199], v[30:33]
	v_mfma_f32_16x16x32_bf16 v[26:29], v[138:141], v[196:199], v[26:29]
	v_mfma_f32_16x16x32_bf16 v[14:17], v[130:133], v[204:207], v[14:17]
	v_mfma_f32_16x16x32_bf16 v[10:13], v[138:141], v[204:207], v[10:13]
	v_mfma_f32_16x16x32_bf16 v[62:65], v[134:137], v[184:187], v[62:65]
	v_mfma_f32_16x16x32_bf16 v[58:61], v[142:145], v[184:187], v[58:61]
	v_mfma_f32_16x16x32_bf16 v[46:49], v[134:137], v[192:195], v[46:49]
	v_mfma_f32_16x16x32_bf16 v[42:45], v[142:145], v[192:195], v[42:45]
	v_mfma_f32_16x16x32_bf16 v[30:33], v[134:137], v[200:203], v[30:33]
	v_mfma_f32_16x16x32_bf16 v[26:29], v[142:145], v[200:203], v[26:29]
	v_mfma_f32_16x16x32_bf16 v[14:17], v[134:137], v[208:211], v[14:17]
	v_mfma_f32_16x16x32_bf16 v[10:13], v[142:145], v[208:211], v[10:13]
	v_mfma_f32_16x16x32_bf16 v[54:57], v[164:167], v[180:183], v[54:57]
	v_mfma_f32_16x16x32_bf16 v[50:53], v[172:175], v[180:183], v[50:53]
	v_mfma_f32_16x16x32_bf16 v[38:41], v[164:167], v[188:191], v[38:41]
	v_mfma_f32_16x16x32_bf16 v[34:37], v[172:175], v[188:191], v[34:37]
	v_mfma_f32_16x16x32_bf16 v[22:25], v[164:167], v[196:199], v[22:25]
	v_mfma_f32_16x16x32_bf16 v[18:21], v[172:175], v[196:199], v[18:21]
	v_mfma_f32_16x16x32_bf16 v[6:9], v[164:167], v[204:207], v[6:9]
	v_mfma_f32_16x16x32_bf16 v[2:5], v[172:175], v[204:207], v[2:5]
	v_mfma_f32_16x16x32_bf16 v[54:57], v[168:171], v[184:187], v[54:57]
	v_mfma_f32_16x16x32_bf16 v[50:53], v[176:179], v[184:187], v[50:53]
	v_mfma_f32_16x16x32_bf16 v[38:41], v[168:171], v[192:195], v[38:41]
	v_mfma_f32_16x16x32_bf16 v[34:37], v[176:179], v[192:195], v[34:37]
	v_mfma_f32_16x16x32_bf16 v[22:25], v[168:171], v[200:203], v[22:25]
	v_mfma_f32_16x16x32_bf16 v[18:21], v[176:179], v[200:203], v[18:21]
	v_mfma_f32_16x16x32_bf16 v[6:9], v[168:171], v[208:211], v[6:9]
	v_mfma_f32_16x16x32_bf16 v[2:5], v[176:179], v[208:211], v[2:5]
	s_setprio 0
	s_barrier
; #define PG8_STAGE(bufoff, gbase, voff) do { _Pragma("unroll") for (int _i = 0; _i < 2; ++_i) \
;         __builtin_amdgcn_global_load_lds((const unsigned*)((const char*)(gbase) + (voff)[_i]), (PG8_LAS unsigned*)(lds + (bufoff) + ldsw + _i * 8192), 16, 0, 0); } while (0)
; #define PG8_LDA(dst, b, h) do { _Pragma("unroll") for (int m = 0; m < 4; ++m) _Pragma("unroll") for (int k = 0; k < 2; ++k) dst[m][k] = *(const PG8_LAS bf16x8*)(lds + PG8_SA(b, h) + aoff + m * 2048 + k * 1024); } while (0)
; #define PG8_LDB(dst, b, h) do { _Pragma("unroll") for (int n = 0; n < 2; ++n) _Pragma("unroll") for (int k = 0; k < 2; ++k) dst[n][k] = *(const PG8_LAS bf16x8*)(lds + PG8_SB(b, h) + boff + n * 2048 + k * 1024); } while (0)
; #define PG8_MMA(ai, bj, At, Bt) do { __builtin_amdgcn_s_setprio(1); _Pragma("unroll") for (int m = 0; m < 4; ++m) _Pragma("unroll") for (int n = 0; n < 2; ++n) _Pragma("unroll") for (int k = 0; k < 2; ++k) \
;         acc[ai][bj][m][n] = __builtin_amdgcn_mfma_f32_16x16x32_bf16(Bt[n][k], At[m][k], acc[ai][bj][m][n], 0, 0, 0); __builtin_amdgcn_s_setprio(0); } while (0)
; #define PG8_WAIT_V(n) asm volatile("s_waitcnt vmcnt(" #n ")" ::: "memory")
; #define PG8_WAIT_L(n) asm volatile("s_waitcnt lgkmcnt(" #n ")" ::: "memory")
; #define PG8_BAR __builtin_amdgcn_s_barrier()
; #define PG8_SCHED __builtin_amdgcn_sched_barrier(0)
; template <class Epi, class Sched, bool ALIGN_EPI = false, bool SP2 = false>
; __device__ __forceinline__ void gemm_phase(PG8_LAS unsigned char* lds, const Gemm g, const Sched& S, const Epi& E) {
;     ...
;             PG8_LDB(B0, 1, 0); PG8_LDB(B1, 1, 1); PG8_SCHED; PG8_LDA(At, 1, 0); PG8_STAGE(PG8_SA(0, 1), a2 + hstep, voffA);
;             PG8_WAIT_V(8); PG8_WAIT_L(0); PG8_BAR; PG8_MMA(0, 0, At, B0); PG8_MMA(0, 1, At, B1); PG8_BAR; PG8_SCHED;
.Lpz2_mid:
	s_add_i32 s42, 0, 0x18000
	s_add_i32 s43, 0, 0x1c000
	v_add_u32_e32 v142, s42, v222
	v_add_u32_e32 v154, s43, v222
	ds_read_b128 v[130:133], v142
	ds_read_b128 v[134:137], v142 offset:1024
	ds_read_b128 v[138:141], v142 offset:2048
	ds_read_b128 v[142:145], v142 offset:3072
	ds_read_b128 v[164:167], v154
	ds_read_b128 v[168:171], v154 offset:1024
	ds_read_b128 v[172:175], v154 offset:2048
	ds_read_b128 v[176:179], v154 offset:3072
	s_add_u32 s4, s36, 0xb0000
	s_addc_u32 s5, s37, 0
	s_mov_b32 m0, s53
	v_lshl_add_u64 v[216:217], s[4:5], 0, v[146:147]
	ds_read_b128 v[180:183], v225 offset:32768
	ds_read_b128 v[184:187], v225 offset:33792
	ds_read_b128 v[188:191], v225 offset:34816
	ds_read_b128 v[192:195], v225 offset:35840
	ds_read_b128 v[196:199], v225 offset:36864
	ds_read_b128 v[200:203], v225 offset:37888
	ds_read_b128 v[204:207], v225 offset:38912
	ds_read_b128 v[208:211], v225 offset:39936
	global_load_lds_dwordx4 v[216:217], off
	v_lshl_add_u64 v[216:217], s[4:5], 0, v[150:151]
	s_mov_b32 m0, s54
	s_nop 0
	global_load_lds_dwordx4 v[216:217], off
	s_waitcnt vmcnt(8) lgkmcnt(0)
	s_setprio 1
	s_barrier
	v_mfma_f32_16x16x32_bf16 v[126:129], v[130:133], v[180:183], v[126:129]
	v_mfma_f32_16x16x32_bf16 v[122:125], v[138:141], v[180:183], v[122:125]
	v_mfma_f32_16x16x32_bf16 v[110:113], v[130:133], v[188:191], v[110:113]
	v_mfma_f32_16x16x32_bf16 v[106:109], v[138:141], v[188:191], v[106:109]
	v_mfma_f32_16x16x32_bf16 v[94:97], v[130:133], v[196:199], v[94:97]
	v_mfma_f32_16x16x32_bf16 v[90:93], v[138:141], v[196:199], v[90:93]
	v_mfma_f32_16x16x32_bf16 v[78:81], v[130:133], v[204:207], v[78:81]
	v_mfma_f32_16x16x32_bf16 v[74:77], v[138:141], v[204:207], v[74:77]
	v_mfma_f32_16x16x32_bf16 v[126:129], v[134:137], v[184:187], v[126:129]
	v_mfma_f32_16x16x32_bf16 v[122:125], v[142:145], v[184:187], v[122:125]
	v_mfma_f32_16x16x32_bf16 v[110:113], v[134:137], v[192:195], v[110:113]
	v_mfma_f32_16x16x32_bf16 v[106:109], v[142:145], v[192:195], v[106:109]
	v_mfma_f32_16x16x32_bf16 v[94:97], v[134:137], v[200:203], v[94:97]
	v_mfma_f32_16x16x32_bf16 v[90:93], v[142:145], v[200:203], v[90:93]
	v_mfma_f32_16x16x32_bf16 v[78:81], v[134:137], v[208:211], v[78:81]
	v_mfma_f32_16x16x32_bf16 v[74:77], v[142:145], v[208:211], v[74:77]
	v_mfma_f32_16x16x32_bf16 v[118:121], v[164:167], v[180:183], v[118:121]
	v_mfma_f32_16x16x32_bf16 v[114:117], v[172:175], v[180:183], v[114:117]
	v_mfma_f32_16x16x32_bf16 v[102:105], v[164:167], v[188:191], v[102:105]
	v_mfma_f32_16x16x32_bf16 v[98:101], v[172:175], v[188:191], v[98:101]
	v_mfma_f32_16x16x32_bf16 v[86:89], v[164:167], v[196:199], v[86:89]
	v_mfma_f32_16x16x32_bf16 v[82:85], v[172:175], v[196:199], v[82:85]
	v_mfma_f32_16x16x32_bf16 v[70:73], v[164:167], v[204:207], v[70:73]
	v_mfma_f32_16x16x32_bf16 v[66:69], v[172:175], v[204:207], v[66:69]
	v_mfma_f32_16x16x32_bf16 v[118:121], v[168:171], v[184:187], v[118:121]
	v_mfma_f32_16x16x32_bf16 v[114:117], v[176:179], v[184:187], v[114:117]
	v_mfma_f32_16x16x32_bf16 v[102:105], v[168:171], v[192:195], v[102:105]
	v_mfma_f32_16x16x32_bf16 v[98:101], v[176:179], v[192:195], v[98:101]
	v_mfma_f32_16x16x32_bf16 v[86:89], v[168:171], v[200:203], v[86:89]
	v_mfma_f32_16x16x32_bf16 v[82:85], v[176:179], v[200:203], v[82:85]
	v_mfma_f32_16x16x32_bf16 v[70:73], v[168:171], v[208:211], v[70:73]
	v_mfma_f32_16x16x32_bf16 v[66:69], v[176:179], v[208:211], v[66:69]
	s_setprio 0
	s_barrier
; #define PG8_STAGE(bufoff, gbase, voff) do { _Pragma("unroll") for (int _i = 0; _i < 2; ++_i) \
;         __builtin_amdgcn_global_load_lds((const unsigned*)((const char*)(gbase) + (voff)[_i]), (PG8_LAS unsigned*)(lds + (bufoff) + ldsw + _i * 8192), 16, 0, 0); } while (0)
; #define PG8_LDA(dst, b, h) do { _Pragma("unroll") for (int m = 0; m < 4; ++m) _Pragma("unroll") for (int k = 0; k < 2; ++k) dst[m][k] = *(const PG8_LAS bf16x8*)(lds + PG8_SA(b, h) + aoff + m * 2048 + k * 1024); } while (0)
; #define PG8_MMA(ai, bj, At, Bt) do { __builtin_amdgcn_s_setprio(1); _Pragma("unroll") for (int m = 0; m < 4; ++m) _Pragma("unroll") for (int n = 0; n < 2; ++n) _Pragma("unroll") for (int k = 0; k < 2; ++k) \
;         acc[ai][bj][m][n] = __builtin_amdgcn_mfma_f32_16x16x32_bf16(Bt[n][k], At[m][k], acc[ai][bj][m][n], 0, 0, 0); __builtin_amdgcn_s_setprio(0); } while (0)
; #define PG8_WAIT_V(n) asm volatile("s_waitcnt vmcnt(" #n ")" ::: "memory")
; #define PG8_WAIT_L(n) asm volatile("s_waitcnt lgkmcnt(" #n ")" ::: "memory")
; #define PG8_BAR __builtin_amdgcn_s_barrier()
; #define PG8_SCHED __builtin_amdgcn_sched_barrier(0)
; template <class Epi, class Sched, bool ALIGN_EPI = false, bool SP2 = false>
; __device__ __forceinline__ void gemm_phase(PG8_LAS unsigned char* lds, const Gemm g, const Sched& S, const Epi& E) {
;     ...
;         for (int t = 0; t < nt; t += 2) {
;             const bool last = (t == nt - 2);
;     ...
;             PG8_LDA(At, 1, 1); PG8_STAGE(PG8_SB(1, 0), b3, voffB); PG8_STAGE(PG8_SB(1, 1), b3 + hstep, voffB); PG8_STAGE(PG8_SA(1, 0), a3, voffA);
;             PG8_WAIT_V(8); PG8_WAIT_L(0); PG8_BAR; PG8_MMA(1, 0, At, B0); PG8_MMA(1, 1, At, B1); PG8_BAR; PG8_SCHED;
	s_add_i32 s4, s42, s50
	v_lshl_add_u64 v[160:161], v[160:161], 0, s[22:23]
	s_mov_b32 m0, s4
	ds_read_b128 v[180:183], v225 offset:49152
	ds_read_b128 v[184:187], v225 offset:50176
	ds_read_b128 v[188:191], v225 offset:51200
	ds_read_b128 v[192:195], v225 offset:52224
	ds_read_b128 v[196:199], v225 offset:53248
	ds_read_b128 v[200:203], v225 offset:54272
	ds_read_b128 v[204:207], v225 offset:55296
	ds_read_b128 v[208:211], v225 offset:56320
	global_load_lds_dwordx4 v[160:161], off
	s_add_i32 m0, s4, 0x2000
	s_add_u32 s4, s6, 0xb0080
	v_lshl_add_u64 v[160:161], v[162:163], 0, s[22:23]
	s_addc_u32 s5, s7, 0
	s_add_i32 s6, s43, s50
	global_load_lds_dwordx4 v[160:161], off
	v_lshl_add_u64 v[160:161], s[4:5], 0, v[148:149]
	s_mov_b32 m0, s6
	s_nop 0
	global_load_lds_dwordx4 v[160:161], off
	v_lshl_add_u64 v[160:161], s[4:5], 0, v[152:153]
	s_add_i32 m0, s6, 0x2000
	s_nop 0
	global_load_lds_dwordx4 v[160:161], off
	v_lshl_add_u64 v[160:161], v[212:213], 0, s[24:25]
	s_mov_b32 m0, s63
	s_nop 0
	global_load_lds_dwordx4 v[160:161], off
	v_lshl_add_u64 v[160:161], v[214:215], 0, s[24:25]
	s_mov_b32 m0, s64
	s_nop 0
	global_load_lds_dwordx4 v[160:161], off
	s_waitcnt vmcnt(8) lgkmcnt(0)
	s_setprio 1
	s_barrier
	v_mfma_f32_16x16x32_bf16 v[62:65], v[130:133], v[180:183], v[62:65]
	v_mfma_f32_16x16x32_bf16 v[58:61], v[138:141], v[180:183], v[58:61]
	v_mfma_f32_16x16x32_bf16 v[46:49], v[130:133], v[188:191], v[46:49]
	v_mfma_f32_16x16x32_bf16 v[42:45], v[138:141], v[188:191], v[42:45]
	v_mfma_f32_16x16x32_bf16 v[30:33], v[130:133], v[196:199], v[30:33]
	v_mfma_f32_16x16x32_bf16 v[26:29], v[138:141], v[196:199], v[26:29]
	v_mfma_f32_16x16x32_bf16 v[14:17], v[130:133], v[204:207], v[14:17]
	v_mfma_f32_16x16x32_bf16 v[10:13], v[138:141], v[204:207], v[10:13]
	v_mfma_f32_16x16x32_bf16 v[62:65], v[134:137], v[184:187], v[62:65]
	v_mfma_f32_16x16x32_bf16 v[58:61], v[142:145], v[184:187], v[58:61]
	v_mfma_f32_16x16x32_bf16 v[46:49], v[134:137], v[192:195], v[46:49]
	v_mfma_f32_16x16x32_bf16 v[42:45], v[142:145], v[192:195], v[42:45]
	v_mfma_f32_16x16x32_bf16 v[30:33], v[134:137], v[200:203], v[30:33]
	v_mfma_f32_16x16x32_bf16 v[26:29], v[142:145], v[200:203], v[26:29]
	v_mfma_f32_16x16x32_bf16 v[14:17], v[134:137], v[208:211], v[14:17]
	v_mfma_f32_16x16x32_bf16 v[10:13], v[142:145], v[208:211], v[10:13]
	v_mfma_f32_16x16x32_bf16 v[54:57], v[164:167], v[180:183], v[54:57]
	v_mfma_f32_16x16x32_bf16 v[50:53], v[172:175], v[180:183], v[50:53]
	v_mfma_f32_16x16x32_bf16 v[38:41], v[164:167], v[188:191], v[38:41]
	v_mfma_f32_16x16x32_bf16 v[34:37], v[172:175], v[188:191], v[34:37]
	v_mfma_f32_16x16x32_bf16 v[22:25], v[164:167], v[196:199], v[22:25]
	v_mfma_f32_16x16x32_bf16 v[18:21], v[172:175], v[196:199], v[18:21]
	v_mfma_f32_16x16x32_bf16 v[6:9], v[164:167], v[204:207], v[6:9]
	v_mfma_f32_16x16x32_bf16 v[2:5], v[172:175], v[204:207], v[2:5]
	v_mfma_f32_16x16x32_bf16 v[54:57], v[168:171], v[184:187], v[54:57]
	v_mfma_f32_16x16x32_bf16 v[50:53], v[176:179], v[184:187], v[50:53]
	v_mfma_f32_16x16x32_bf16 v[38:41], v[168:171], v[192:195], v[38:41]
	v_mfma_f32_16x16x32_bf16 v[34:37], v[176:179], v[192:195], v[34:37]
	v_mfma_f32_16x16x32_bf16 v[22:25], v[168:171], v[200:203], v[22:25]
	v_mfma_f32_16x16x32_bf16 v[18:21], v[176:179], v[200:203], v[18:21]
	v_mfma_f32_16x16x32_bf16 v[6:9], v[168:171], v[208:211], v[6:9]
	v_mfma_f32_16x16x32_bf16 v[2:5], v[176:179], v[208:211], v[2:5]
	s_setprio 0
	s_barrier
	s_add_i32 s41, s41, 2
	s_add_u32 s39, s39, 0x100
	s_addc_u32 s40, s40, 0
	s_cmp_gt_u32 s41, 41
	s_mov_b64 s[4:5], s[0:1]
	s_cbranch_scc0 .LBB0_289
	s_and_b64 vcc, exec, s[26:27]
	s_cbranch_vccz .LBB0_292
	s_barrier

;     __host__ __device__ bool next(int i, Unit& u) const { if (!b.next(i >> 1, u)) return false; u.sel = i & 1; return true; }
; #define PG8_STAGE(bufoff, gbase, voff) do { _Pragma("unroll") for (int _i = 0; _i < 2; ++_i) \
;         __builtin_amdgcn_global_load_lds((const unsigned*)((const char*)(gbase) + (voff)[_i]), (PG8_LAS unsigned*)(lds + (bufoff) + ldsw + _i * 8192), 16, 0, 0); } while (0)
; #define PG8_LDA(dst, b, h) do { _Pragma("unroll") for (int m = 0; m < 4; ++m) _Pragma("unroll") for (int k = 0; k < 2; ++k) dst[m][k] = *(const PG8_LAS bf16x8*)(lds + PG8_SA(b, h) + aoff + m * 2048 + k * 1024); } while (0)
; #define PG8_LDB(dst, b, h) do { _Pragma("unroll") for (int n = 0; n < 2; ++n) _Pragma("unroll") for (int k = 0; k < 2; ++k) dst[n][k] = *(const PG8_LAS bf16x8*)(lds + PG8_SB(b, h) + boff + n * 2048 + k * 1024); } while (0)
; #define PG8_WAIT_V(n) asm volatile("s_waitcnt vmcnt(" #n ")" ::: "memory")
; #define PG8_WAIT_L(n) asm volatile("s_waitcnt lgkmcnt(" #n ")" ::: "memory")
; #define PG8_BAR __builtin_amdgcn_s_barrier()
; #define PG8_SCHED __builtin_amdgcn_sched_barrier(0)
;     __host__ __device__ bool next(int i, Unit& u) const {
;         const long L = (long)i * G + c; if (L >= nwg) return false;
;         int wgid = (int)L; { const int q = nwg / NXCD, r = nwg % NXCD, xcd = wgid % NXCD, off = wgid / NXCD; wgid = (xcd < r ? xcd * (q + 1) : r * (q + 1) + (xcd - r) * q) + off; }
;         const int nig = WGM * nN, gid = wgid / nig, fm = gid * WGM, gsz = (nM - fm) < WGM ? (nM - fm) : WGM;
;         u.pm = fm + ((wgid % nig) % gsz); u.pn = (wgid % nig) / gsz; u.sel = 0; return true;
; template <class Epi, class Sched, bool ALIGN_EPI = false, bool SP2 = false>
; __device__ __forceinline__ void gemm_phase(PG8_LAS unsigned char* lds, const Gemm g, const Sched& S, const Epi& E) {
;     ...
;         const bool has_next = S.next(ui + 1, nxt);
;         const char* nA = has_next ? PG8_ABASE(nxt) : cA; const char* nB = has_next ? PG8_BBASE(nxt) : cB;
;     ...
;             PG8_LDB(B0, 0, 0); PG8_LDB(B1, 0, 1); PG8_SCHED; PG8_LDA(At, 0, 0); PG8_STAGE(PG8_SA(1, 1), a1 + hstep, voffA);
;             PG8_WAIT_V(8); PG8_WAIT_L(0); PG8_BAR; PG8_MMA(0, 0, At, B0); PG8_MMA(0, 1, At, B1); PG8_BAR; PG8_SCHED;
;             if constexpr (Epi::PREFETCH) { if (t == tpf) E.prefetch(cur, wid, lane); }
.LBB0_435:
	s_ashr_i32 s5, s4, 31
	s_lshl_b32 s8, s6, 8
	s_lshl_b64 s[28:29], s[4:5], 14
	s_ashr_i32 s5, s4, 5
	s_ashr_i32 s9, s8, 31
	s_add_u32 s52, s14, s28
	s_mul_hi_i32 s54, s5, 0x6800
	s_mulk_i32 s5, 0x6800
	s_addc_u32 s53, s88, s29
	s_add_u32 s5, s77, s5
	s_addc_u32 s55, s78, s54
	s_lshl_b64 s[28:29], s[8:9], 2
	s_add_u32 s54, s5, s28
	s_addc_u32 s55, s55, s29
	s_add_u32 s5, s56, 0x100
	v_lshl_add_u64 v[196:197], s[10:11], 0, v[188:189]
	v_lshl_add_u64 v[198:199], s[10:11], 0, v[190:191]
	s_addc_u32 s9, s57, 0
	s_mov_b32 s28, 0
	s_mov_b64 s[56:57], 0
	ds_read_b128 v[162:165], v208
	ds_read_b128 v[166:169], v208 offset:1024
	ds_read_b128 v[170:173], v208 offset:2048
	ds_read_b128 v[174:177], v208 offset:3072
	ds_read_b128 v[146:149], v209
	ds_read_b128 v[150:153], v209 offset:1024
	ds_read_b128 v[154:157], v209 offset:2048
	ds_read_b128 v[158:161], v209 offset:3072
	v_lshl_add_u64 v[42:43], v[196:197], 0, s[56:57]
	s_add_i32 m0, s69, 0xc000
	ds_read_b128 v[212:215], v210
	ds_read_b128 v[216:219], v210 offset:1024
	ds_read_b128 v[222:225], v210 offset:2048
	ds_read_b128 v[226:229], v210 offset:3072
	ds_read_b128 v[230:233], v210 offset:4096
	ds_read_b128 v[234:237], v210 offset:5120
	ds_read_b128 v[238:241], v210 offset:6144
	ds_read_b128 v[242:245], v210 offset:7168
	global_load_lds_dwordx4 v[42:43], off
	v_lshl_add_u64 v[42:43], v[198:199], 0, s[56:57]
	s_add_i32 m0, s69, 0xe000
	s_nop 0
	global_load_lds_dwordx4 v[42:43], off
	s_add_i32 s15, s15, 1
	s_mul_i32 s2, s15, s86
	s_mul_hi_u32 s3, s15, s33
	s_add_i32 s3, s3, s2
	s_mul_i32 s2, s15, s33
	v_readlane_b32 s98, v254, 12
	s_add_u32 s100, s2, s98
	s_addc_u32 s101, s3, s87
	v_cmp_lt_i64_e64 s[2:3], s[100:101], v[192:193]
	s_ashr_i32 s98, s100, 31
	s_lshr_b32 s98, s98, 29
	s_add_i32 s98, s100, s98
	s_ashr_i32 s7, s98, 3
	s_and_b32 s98, s98, -8
	s_sub_i32 s98, s100, s98
	s_cmp_lt_i32 s98, 0
	s_movk_i32 s100, 0x1a1
	s_cselect_b32 s100, s100, 0x1a0
	s_mul_i32 s98, s98, s100
	s_add_i32 s98, s98, s7
	s_mul_hi_i32 s7, s98, 0x4ec4ec4f
	s_lshr_b32 s100, s7, 31
	s_ashr_i32 s7, s7, 4
	s_add_i32 s7, s7, s100
	s_lshl_b32 s100, s7, 1
	s_mul_i32 s7, s7, 52
	s_sub_i32 s98, s98, s7
	s_lshr_b32 s44, s98, 1
	s_and_b32 s98, s98, 1
	s_add_i32 s46, s100, s98
	s_ashr_i32 s47, s46, 31
	s_lshl_b64 s[100:101], s[46:47], 19
	s_add_u32 s48, s64, s100
	s_addc_u32 s49, s65, s101
	s_and_b64 s[100:101], s[2:3], exec
	s_cselect_b32 s7, s49, s65
	s_cselect_b32 s31, s48, s64
	s_ashr_i32 s45, s44, 31
	s_lshl_b64 s[100:101], s[44:45], 19
	s_add_u32 s50, s66, s100
	s_addc_u32 s51, s67, s101
	s_and_b64 s[100:101], s[2:3], exec
	s_cselect_b32 s45, s51, s67
	s_cselect_b32 s47, s50, s66
	s_waitcnt vmcnt(8) lgkmcnt(0)
	s_setprio 1
	s_barrier
	v_mfma_f32_16x16x32_bf16 v[42:45], v[162:165], v[212:215], 0
	v_mfma_f32_16x16x32_bf16 v[46:49], v[170:173], v[212:215], 0
	v_mfma_f32_16x16x32_bf16 v[50:53], v[162:165], v[222:225], 0
	v_mfma_f32_16x16x32_bf16 v[54:57], v[170:173], v[222:225], 0
	v_mfma_f32_16x16x32_bf16 v[110:113], v[162:165], v[230:233], 0
	v_mfma_f32_16x16x32_bf16 v[106:109], v[170:173], v[230:233], 0
	v_mfma_f32_16x16x32_bf16 v[94:97], v[162:165], v[238:241], 0
	v_mfma_f32_16x16x32_bf16 v[90:93], v[170:173], v[238:241], 0
	v_mfma_f32_16x16x32_bf16 v[42:45], v[166:169], v[216:219], v[42:45]
	v_mfma_f32_16x16x32_bf16 v[46:49], v[174:177], v[216:219], v[46:49]
	v_mfma_f32_16x16x32_bf16 v[50:53], v[166:169], v[226:229], v[50:53]
	v_mfma_f32_16x16x32_bf16 v[54:57], v[174:177], v[226:229], v[54:57]
	v_mfma_f32_16x16x32_bf16 v[110:113], v[166:169], v[234:237], v[110:113]
	v_mfma_f32_16x16x32_bf16 v[106:109], v[174:177], v[234:237], v[106:109]
	v_mfma_f32_16x16x32_bf16 v[94:97], v[166:169], v[242:245], v[94:97]
	v_mfma_f32_16x16x32_bf16 v[90:93], v[174:177], v[242:245], v[90:93]
	v_mfma_f32_16x16x32_bf16 v[122:125], v[146:149], v[212:215], 0
	v_mfma_f32_16x16x32_bf16 v[134:137], v[150:153], v[216:219], v[122:125]
	v_mfma_f32_16x16x32_bf16 v[122:125], v[154:157], v[212:215], 0
	v_mfma_f32_16x16x32_bf16 v[118:121], v[146:149], v[222:225], 0
	v_mfma_f32_16x16x32_bf16 v[114:117], v[154:157], v[222:225], 0
	v_mfma_f32_16x16x32_bf16 v[102:105], v[146:149], v[230:233], 0
	v_mfma_f32_16x16x32_bf16 v[98:101], v[154:157], v[230:233], 0
	v_mfma_f32_16x16x32_bf16 v[86:89], v[146:149], v[238:241], 0
	v_mfma_f32_16x16x32_bf16 v[82:85], v[154:157], v[238:241], 0
	v_mfma_f32_16x16x32_bf16 v[130:133], v[158:161], v[216:219], v[122:125]
	v_mfma_f32_16x16x32_bf16 v[118:121], v[150:153], v[226:229], v[118:121]
	v_mfma_f32_16x16x32_bf16 v[114:117], v[158:161], v[226:229], v[114:117]
	v_mfma_f32_16x16x32_bf16 v[102:105], v[150:153], v[234:237], v[102:105]
	v_mfma_f32_16x16x32_bf16 v[98:101], v[158:161], v[234:237], v[98:101]
	v_mfma_f32_16x16x32_bf16 v[86:89], v[150:153], v[242:245], v[86:89]
	v_mfma_f32_16x16x32_bf16 v[82:85], v[158:161], v[242:245], v[82:85]
	s_setprio 0
	s_barrier
	s_cmp_lg_u32 s63, s28
	s_cbranch_scc1 .Lpz3_a
	v_mov_b32_e32 v186, v207
	s_add_i32 m0, s62, 0x20000
	v_lshl_add_u64 v[122:123], s[52:53], 0, v[186:187]
	s_mov_b64 s[58:59], 0x400
	global_load_lds_dwordx4 v186, s[52:53]
	v_lshl_add_u64 v[122:123], v[122:123], 0, s[58:59]
	s_add_i32 m0, s62, 0x20400
	s_andn2_b64 vcc, exec, s[40:41]
	global_load_lds_dwordx4 v[122:123], off
	s_cbranch_vccnz .Lpz3_a
	v_lshl_add_u64 v[122:123], s[54:55], 0, v[186:187]
	s_mov_b32 m0, s30
	s_nop 0
	global_load_lds_dwordx4 v[122:123], off
	s_branch .Lpz3_a
; #define PG8_STAGE(bufoff, gbase, voff) do { _Pragma("unroll") for (int _i = 0; _i < 2; ++_i) \
;         __builtin_amdgcn_global_load_lds((const unsigned*)((const char*)(gbase) + (voff)[_i]), (PG8_LAS unsigned*)(lds + (bufoff) + ldsw + _i * 8192), 16, 0, 0); } while (0)
; #define PG8_LDA(dst, b, h) do { _Pragma("unroll") for (int m = 0; m < 4; ++m) _Pragma("unroll") for (int k = 0; k < 2; ++k) dst[m][k] = *(const PG8_LAS bf16x8*)(lds + PG8_SA(b, h) + aoff + m * 2048 + k * 1024); } while (0)
; #define PG8_MMA(ai, bj, At, Bt) do { __builtin_amdgcn_s_setprio(1); _Pragma("unroll") for (int m = 0; m < 4; ++m) _Pragma("unroll") for (int n = 0; n < 2; ++n) _Pragma("unroll") for (int k = 0; k < 2; ++k) \
;         acc[ai][bj][m][n] = __builtin_amdgcn_mfma_f32_16x16x32_bf16(Bt[n][k], At[m][k], acc[ai][bj][m][n], 0, 0, 0); __builtin_amdgcn_s_setprio(0); } while (0)
; #define PG8_WAIT_V(n) asm volatile("s_waitcnt vmcnt(" #n ")" ::: "memory")
; #define PG8_WAIT_L(n) asm volatile("s_waitcnt lgkmcnt(" #n ")" ::: "memory")
; #define PG8_BAR __builtin_amdgcn_s_barrier()
; #define PG8_SCHED __builtin_amdgcn_sched_barrier(0)
; template <class Epi, class Sched, bool ALIGN_EPI = false, bool SP2 = false>
; __device__ __forceinline__ void gemm_phase(PG8_LAS unsigned char* lds, const Gemm g, const Sched& S, const Epi& E) {
;     ...
;             PG8_LDA(At, 0, 1); PG8_STAGE(PG8_SB(0, 0), b2, voffB); PG8_STAGE(PG8_SB(0, 1), b2 + hstep, voffB); PG8_STAGE(PG8_SA(0, 0), a2, voffA);
;             PG8_WAIT_V(8); PG8_WAIT_L(0); PG8_BAR; PG8_MMA(1, 0, At, B0); PG8_MMA(1, 1, At, B1); PG8_BAR; PG8_SCHED;
.Lpz3_a:
	s_add_u32 s29, s10, s56
	s_addc_u32 s58, s11, s57
	s_add_u32 s29, s29, 0x100
	s_addc_u32 s58, s58, 0
	s_add_u32 vcc_lo, s5, s56
	s_addc_u32 s59, s9, s57
	s_cmpk_eq_i32 s56, 0x700
	s_cselect_b32 s61, s7, s58
	s_cselect_b32 s59, s45, s59
	s_cselect_b32 s58, s47, vcc_lo
	s_mov_b32 m0, s70
	s_cselect_b32 s60, s31, s29
	v_lshl_add_u64 v[204:205], s[58:59], 0, v[180:181]
	s_add_u32 vcc_lo, s58, 0x40000
	ds_read_b128 v[122:125], v210 offset:16384
	ds_read_b128 v[126:129], v210 offset:17408
	ds_read_b128 v[138:141], v210 offset:18432
	ds_read_b128 v[142:145], v210 offset:19456
	ds_read_b128 v[212:215], v210 offset:20480
	ds_read_b128 v[216:219], v210 offset:21504
	ds_read_b128 v[222:225], v210 offset:22528
	ds_read_b128 v[226:229], v210 offset:23552
	global_load_lds_dwordx4 v[204:205], off
	v_lshl_add_u64 v[246:247], s[58:59], 0, v[184:185]
	s_mov_b32 m0, s71
	s_addc_u32 vcc_hi, s59, 0
	global_load_lds_dwordx4 v[246:247], off
	v_lshl_add_u64 v[230:231], vcc, 0, v[180:181]
	s_mov_b32 m0, s72
	v_lshl_add_u64 v[248:249], s[60:61], 0, v[178:179]
	global_load_lds_dwordx4 v[230:231], off
	v_lshl_add_u64 v[230:231], vcc, 0, v[184:185]
	s_mov_b32 m0, s73
	v_lshl_add_u64 v[250:251], s[60:61], 0, v[182:183]
	global_load_lds_dwordx4 v[230:231], off
	s_mov_b32 m0, s69
	s_nop 0
	global_load_lds_dwordx4 v[248:249], off
	s_mov_b32 m0, s74
	s_nop 0
	global_load_lds_dwordx4 v[250:251], off
	s_waitcnt vmcnt(8) lgkmcnt(0)
	s_setprio 1
	s_barrier
	v_mfma_f32_16x16x32_bf16 v[78:81], v[162:165], v[122:125], 0
	v_mfma_f32_16x16x32_bf16 v[74:77], v[170:173], v[122:125], 0
	v_mfma_f32_16x16x32_bf16 v[62:65], v[162:165], v[138:141], 0
	v_mfma_f32_16x16x32_bf16 v[58:61], v[170:173], v[138:141], 0
	v_mfma_f32_16x16x32_bf16 v[30:33], v[162:165], v[212:215], 0
	v_mfma_f32_16x16x32_bf16 v[26:29], v[170:173], v[212:215], 0
	v_mfma_f32_16x16x32_bf16 v[14:17], v[162:165], v[222:225], 0
	v_mfma_f32_16x16x32_bf16 v[10:13], v[170:173], v[222:225], 0
	v_mfma_f32_16x16x32_bf16 v[78:81], v[166:169], v[126:129], v[78:81]
	v_mfma_f32_16x16x32_bf16 v[74:77], v[174:177], v[126:129], v[74:77]
	v_mfma_f32_16x16x32_bf16 v[62:65], v[166:169], v[142:145], v[62:65]
	v_mfma_f32_16x16x32_bf16 v[58:61], v[174:177], v[142:145], v[58:61]
	v_mfma_f32_16x16x32_bf16 v[30:33], v[166:169], v[216:219], v[30:33]
	v_mfma_f32_16x16x32_bf16 v[26:29], v[174:177], v[216:219], v[26:29]
	v_mfma_f32_16x16x32_bf16 v[14:17], v[166:169], v[226:229], v[14:17]
	v_mfma_f32_16x16x32_bf16 v[10:13], v[174:177], v[226:229], v[10:13]
	v_mfma_f32_16x16x32_bf16 v[70:73], v[146:149], v[122:125], 0
	v_mfma_f32_16x16x32_bf16 v[66:69], v[154:157], v[122:125], 0
	v_mfma_f32_16x16x32_bf16 v[38:41], v[146:149], v[138:141], 0
	v_mfma_f32_16x16x32_bf16 v[34:37], v[154:157], v[138:141], 0
	v_mfma_f32_16x16x32_bf16 v[22:25], v[146:149], v[212:215], 0
	v_mfma_f32_16x16x32_bf16 v[18:21], v[154:157], v[212:215], 0
	v_mfma_f32_16x16x32_bf16 v[6:9], v[146:149], v[222:225], 0
	v_mfma_f32_16x16x32_bf16 v[2:5], v[154:157], v[222:225], 0
	v_mfma_f32_16x16x32_bf16 v[70:73], v[150:153], v[126:129], v[70:73]
	v_mfma_f32_16x16x32_bf16 v[66:69], v[158:161], v[126:129], v[66:69]
	v_mfma_f32_16x16x32_bf16 v[38:41], v[150:153], v[142:145], v[38:41]
	v_mfma_f32_16x16x32_bf16 v[34:37], v[158:161], v[142:145], v[34:37]
	v_mfma_f32_16x16x32_bf16 v[22:25], v[150:153], v[216:219], v[22:25]
	v_mfma_f32_16x16x32_bf16 v[18:21], v[158:161], v[216:219], v[18:21]
	v_mfma_f32_16x16x32_bf16 v[6:9], v[150:153], v[226:229], v[6:9]
	v_mfma_f32_16x16x32_bf16 v[2:5], v[158:161], v[226:229], v[2:5]
	s_setprio 0
	s_barrier
	s_branch .Lpz3_mid
.LBB0_438:
	s_add_u32 s29, s10, s56
	s_addc_u32 s58, s11, s57
	s_add_u32 s29, s29, 0x100
	s_addc_u32 s58, s58, 0
	s_add_u32 vcc_lo, s5, s56
	s_addc_u32 s59, s9, s57
	s_cmpk_eq_i32 s56, 0x700
	s_cselect_b32 s61, s7, s58
	s_cselect_b32 s59, s45, s59
	s_cselect_b32 s58, s47, vcc_lo
	s_mov_b32 m0, s70
	s_cselect_b32 s60, s31, s29
	v_lshl_add_u64 v[204:205], s[58:59], 0, v[180:181]
	s_add_u32 vcc_lo, s58, 0x40000
	ds_read_b128 v[122:125], v210 offset:16384
	ds_read_b128 v[126:129], v210 offset:17408
	ds_read_b128 v[138:141], v210 offset:18432
	ds_read_b128 v[142:145], v210 offset:19456
	ds_read_b128 v[212:215], v210 offset:20480
	ds_read_b128 v[216:219], v210 offset:21504
	ds_read_b128 v[222:225], v210 offset:22528
	ds_read_b128 v[226:229], v210 offset:23552
	global_load_lds_dwordx4 v[204:205], off
	v_lshl_add_u64 v[246:247], s[58:59], 0, v[184:185]
	s_mov_b32 m0, s71
	s_addc_u32 vcc_hi, s59, 0
	global_load_lds_dwordx4 v[246:247], off
	v_lshl_add_u64 v[230:231], vcc, 0, v[180:181]
	s_mov_b32 m0, s72
	v_lshl_add_u64 v[248:249], s[60:61], 0, v[178:179]
	global_load_lds_dwordx4 v[230:231], off
	v_lshl_add_u64 v[230:231], vcc, 0, v[184:185]
	s_mov_b32 m0, s73
	v_lshl_add_u64 v[250:251], s[60:61], 0, v[182:183]
	global_load_lds_dwordx4 v[230:231], off
	s_mov_b32 m0, s69
	s_nop 0
	global_load_lds_dwordx4 v[248:249], off
	s_mov_b32 m0, s74
	s_nop 0
	global_load_lds_dwordx4 v[250:251], off
	s_waitcnt vmcnt(8) lgkmcnt(0)
	s_setprio 1
	s_barrier
; #define PG8_STAGE(bufoff, gbase, voff) do { _Pragma("unroll") for (int _i = 0; _i < 2; ++_i) \
;         __builtin_amdgcn_global_load_lds((const unsigned*)((const char*)(gbase) + (voff)[_i]), (PG8_LAS unsigned*)(lds + (bufoff) + ldsw + _i * 8192), 16, 0, 0); } while (0)
; #define PG8_LDA(dst, b, h) do { _Pragma("unroll") for (int m = 0; m < 4; ++m) _Pragma("unroll") for (int k = 0; k < 2; ++k) dst[m][k] = *(const PG8_LAS bf16x8*)(lds + PG8_SA(b, h) + aoff + m * 2048 + k * 1024); } while (0)
; #define PG8_LDB(dst, b, h) do { _Pragma("unroll") for (int n = 0; n < 2; ++n) _Pragma("unroll") for (int k = 0; k < 2; ++k) dst[n][k] = *(const PG8_LAS bf16x8*)(lds + PG8_SB(b, h) + boff + n * 2048 + k * 1024); } while (0)
; #define PG8_MMA(ai, bj, At, Bt) do { __builtin_amdgcn_s_setprio(1); _Pragma("unroll") for (int m = 0; m < 4; ++m) _Pragma("unroll") for (int n = 0; n < 2; ++n) _Pragma("unroll") for (int k = 0; k < 2; ++k) \
;         acc[ai][bj][m][n] = __builtin_amdgcn_mfma_f32_16x16x32_bf16(Bt[n][k], At[m][k], acc[ai][bj][m][n], 0, 0, 0); __builtin_amdgcn_s_setprio(0); } while (0)
; #define PG8_WAIT_V(n) asm volatile("s_waitcnt vmcnt(" #n ")" ::: "memory")
; #define PG8_WAIT_L(n) asm volatile("s_waitcnt lgkmcnt(" #n ")" ::: "memory")
; #define PG8_BAR __builtin_amdgcn_s_barrier()
; #define PG8_SCHED __builtin_amdgcn_sched_barrier(0)
; template <class Epi, class Sched, bool ALIGN_EPI = false, bool SP2 = false>
; __device__ __forceinline__ void gemm_phase(PG8_LAS unsigned char* lds, const Gemm g, const Sched& S, const Epi& E) {
;     ...
;             PG8_WAIT_V(8); PG8_WAIT_L(0); PG8_BAR; PG8_MMA(1, 0, At, B0); PG8_MMA(1, 1, At, B1); PG8_BAR; PG8_SCHED;
;             PG8_LDB(B0, 1, 0); PG8_LDB(B1, 1, 1); PG8_SCHED; PG8_LDA(At, 1, 0); PG8_STAGE(PG8_SA(0, 1), a2 + hstep, voffA);
;             PG8_WAIT_V(8); PG8_WAIT_L(0); PG8_BAR; PG8_MMA(0, 0, At, B0); PG8_MMA(0, 1, At, B1); PG8_BAR; PG8_SCHED;
	v_mfma_f32_16x16x32_bf16 v[78:81], v[162:165], v[122:125], v[78:81]
	v_mfma_f32_16x16x32_bf16 v[74:77], v[170:173], v[122:125], v[74:77]
	v_mfma_f32_16x16x32_bf16 v[62:65], v[162:165], v[138:141], v[62:65]
	v_mfma_f32_16x16x32_bf16 v[58:61], v[170:173], v[138:141], v[58:61]
	v_mfma_f32_16x16x32_bf16 v[30:33], v[162:165], v[212:215], v[30:33]
	v_mfma_f32_16x16x32_bf16 v[26:29], v[170:173], v[212:215], v[26:29]
	v_mfma_f32_16x16x32_bf16 v[14:17], v[162:165], v[222:225], v[14:17]
	v_mfma_f32_16x16x32_bf16 v[10:13], v[170:173], v[222:225], v[10:13]
	v_mfma_f32_16x16x32_bf16 v[78:81], v[166:169], v[126:129], v[78:81]
	v_mfma_f32_16x16x32_bf16 v[74:77], v[174:177], v[126:129], v[74:77]
	v_mfma_f32_16x16x32_bf16 v[62:65], v[166:169], v[142:145], v[62:65]
	v_mfma_f32_16x16x32_bf16 v[58:61], v[174:177], v[142:145], v[58:61]
	v_mfma_f32_16x16x32_bf16 v[30:33], v[166:169], v[216:219], v[30:33]
	v_mfma_f32_16x16x32_bf16 v[26:29], v[174:177], v[216:219], v[26:29]
	v_mfma_f32_16x16x32_bf16 v[14:17], v[166:169], v[226:229], v[14:17]
	v_mfma_f32_16x16x32_bf16 v[10:13], v[174:177], v[226:229], v[10:13]
	v_mfma_f32_16x16x32_bf16 v[70:73], v[146:149], v[122:125], v[70:73]
	v_mfma_f32_16x16x32_bf16 v[66:69], v[154:157], v[122:125], v[66:69]
	v_mfma_f32_16x16x32_bf16 v[38:41], v[146:149], v[138:141], v[38:41]
	v_mfma_f32_16x16x32_bf16 v[34:37], v[154:157], v[138:141], v[34:37]
	v_mfma_f32_16x16x32_bf16 v[22:25], v[146:149], v[212:215], v[22:25]
	v_mfma_f32_16x16x32_bf16 v[18:21], v[154:157], v[212:215], v[18:21]
	v_mfma_f32_16x16x32_bf16 v[6:9], v[146:149], v[222:225], v[6:9]
	v_mfma_f32_16x16x32_bf16 v[2:5], v[154:157], v[222:225], v[2:5]
	v_mfma_f32_16x16x32_bf16 v[70:73], v[150:153], v[126:129], v[70:73]
	v_mfma_f32_16x16x32_bf16 v[66:69], v[158:161], v[126:129], v[66:69]
	v_mfma_f32_16x16x32_bf16 v[38:41], v[150:153], v[142:145], v[38:41]
	v_mfma_f32_16x16x32_bf16 v[34:37], v[158:161], v[142:145], v[34:37]
	v_mfma_f32_16x16x32_bf16 v[22:25], v[150:153], v[216:219], v[22:25]
	v_mfma_f32_16x16x32_bf16 v[18:21], v[158:161], v[216:219], v[18:21]
	v_mfma_f32_16x16x32_bf16 v[6:9], v[150:153], v[226:229], v[6:9]
	v_mfma_f32_16x16x32_bf16 v[2:5], v[158:161], v[226:229], v[2:5]
	s_setprio 0
	s_barrier
.Lpz3_mid:
	s_add_i32 s29, 0, 0x18000
	v_add_u32_e32 v122, s29, v203
	s_add_i32 vcc_lo, 0, 0x1c000
	ds_read_b128 v[146:149], v122
	ds_read_b128 v[150:153], v122 offset:1024
	ds_read_b128 v[154:157], v122 offset:2048
	ds_read_b128 v[158:161], v122 offset:3072
	v_add_u32_e32 v122, vcc_lo, v203
	ds_read_b128 v[162:165], v122
	ds_read_b128 v[166:169], v122 offset:1024
	ds_read_b128 v[170:173], v122 offset:2048
	ds_read_b128 v[174:177], v122 offset:3072
	s_add_u32 s60, s60, 0x40000
	s_addc_u32 s61, s61, 0
	s_mov_b32 m0, s75
	v_lshl_add_u64 v[122:123], s[60:61], 0, v[178:179]
	ds_read_b128 v[212:215], v210 offset:32768
	ds_read_b128 v[216:219], v210 offset:33792
	ds_read_b128 v[222:225], v210 offset:34816
	ds_read_b128 v[226:229], v210 offset:35840
	ds_read_b128 v[230:233], v210 offset:36864
	ds_read_b128 v[234:237], v210 offset:37888
	ds_read_b128 v[238:241], v210 offset:38912
	ds_read_b128 v[242:245], v210 offset:39936
	global_load_lds_dwordx4 v[122:123], off
	v_lshl_add_u64 v[122:123], s[60:61], 0, v[182:183]
	s_mov_b32 m0, s76
	s_nop 0
	global_load_lds_dwordx4 v[122:123], off
	s_waitcnt vmcnt(8) lgkmcnt(0)
	s_setprio 1
	s_barrier
	v_mfma_f32_16x16x32_bf16 v[42:45], v[146:149], v[212:215], v[42:45]
	v_mfma_f32_16x16x32_bf16 v[142:145], v[150:153], v[216:219], v[42:45]
	v_mfma_f32_16x16x32_bf16 v[42:45], v[154:157], v[212:215], v[46:49]
	v_mfma_f32_16x16x32_bf16 v[138:141], v[158:161], v[216:219], v[42:45]
	v_mfma_f32_16x16x32_bf16 v[42:45], v[146:149], v[222:225], v[50:53]
	v_mfma_f32_16x16x32_bf16 v[126:129], v[150:153], v[226:229], v[42:45]
	v_mfma_f32_16x16x32_bf16 v[42:45], v[154:157], v[222:225], v[54:57]
	v_mfma_f32_16x16x32_bf16 v[122:125], v[158:161], v[226:229], v[42:45]
	v_mfma_f32_16x16x32_bf16 v[42:45], v[146:149], v[230:233], v[110:113]
	v_mfma_f32_16x16x32_bf16 v[110:113], v[150:153], v[234:237], v[42:45]
	v_mfma_f32_16x16x32_bf16 v[42:45], v[154:157], v[230:233], v[106:109]
	v_mfma_f32_16x16x32_bf16 v[106:109], v[158:161], v[234:237], v[42:45]
	v_mfma_f32_16x16x32_bf16 v[42:45], v[146:149], v[238:241], v[94:97]
	v_mfma_f32_16x16x32_bf16 v[94:97], v[150:153], v[242:245], v[42:45]
	v_mfma_f32_16x16x32_bf16 v[42:45], v[154:157], v[238:241], v[90:93]
	v_mfma_f32_16x16x32_bf16 v[90:93], v[158:161], v[242:245], v[42:45]
	v_mfma_f32_16x16x32_bf16 v[42:45], v[162:165], v[212:215], v[134:137]
	v_mfma_f32_16x16x32_bf16 v[134:137], v[166:169], v[216:219], v[42:45]
	v_mfma_f32_16x16x32_bf16 v[42:45], v[170:173], v[212:215], v[130:133]
	v_mfma_f32_16x16x32_bf16 v[130:133], v[174:177], v[216:219], v[42:45]
	v_mfma_f32_16x16x32_bf16 v[42:45], v[162:165], v[222:225], v[118:121]
	v_mfma_f32_16x16x32_bf16 v[118:121], v[166:169], v[226:229], v[42:45]
	v_mfma_f32_16x16x32_bf16 v[42:45], v[170:173], v[222:225], v[114:117]
	v_mfma_f32_16x16x32_bf16 v[114:117], v[174:177], v[226:229], v[42:45]
	v_mfma_f32_16x16x32_bf16 v[42:45], v[162:165], v[230:233], v[102:105]
	v_mfma_f32_16x16x32_bf16 v[102:105], v[166:169], v[234:237], v[42:45]
	v_mfma_f32_16x16x32_bf16 v[42:45], v[170:173], v[230:233], v[98:101]
	v_mfma_f32_16x16x32_bf16 v[98:101], v[174:177], v[234:237], v[42:45]
	v_mfma_f32_16x16x32_bf16 v[42:45], v[162:165], v[238:241], v[86:89]
	v_mfma_f32_16x16x32_bf16 v[86:89], v[166:169], v[242:245], v[42:45]
	v_mfma_f32_16x16x32_bf16 v[42:45], v[170:173], v[238:241], v[82:85]
	v_mfma_f32_16x16x32_bf16 v[82:85], v[174:177], v[242:245], v[42:45]
	s_setprio 0
	s_barrier
; #define PG8_STAGE(bufoff, gbase, voff) do { _Pragma("unroll") for (int _i = 0; _i < 2; ++_i) \
;         __builtin_amdgcn_global_load_lds((const unsigned*)((const char*)(gbase) + (voff)[_i]), (PG8_LAS unsigned*)(lds + (bufoff) + ldsw + _i * 8192), 16, 0, 0); } while (0)
; #define PG8_LDA(dst, b, h) do { _Pragma("unroll") for (int m = 0; m < 4; ++m) _Pragma("unroll") for (int k = 0; k < 2; ++k) dst[m][k] = *(const PG8_LAS bf16x8*)(lds + PG8_SA(b, h) + aoff + m * 2048 + k * 1024); } while (0)
; #define PG8_MMA(ai, bj, At, Bt) do { __builtin_amdgcn_s_setprio(1); _Pragma("unroll") for (int m = 0; m < 4; ++m) _Pragma("unroll") for (int n = 0; n < 2; ++n) _Pragma("unroll") for (int k = 0; k < 2; ++k) \
;         acc[ai][bj][m][n] = __builtin_amdgcn_mfma_f32_16x16x32_bf16(Bt[n][k], At[m][k], acc[ai][bj][m][n], 0, 0, 0); __builtin_amdgcn_s_setprio(0); } while (0)
; #define PG8_WAIT_V(n) asm volatile("s_waitcnt vmcnt(" #n ")" ::: "memory")
; #define PG8_WAIT_L(n) asm volatile("s_waitcnt lgkmcnt(" #n ")" ::: "memory")
; #define PG8_BAR __builtin_amdgcn_s_barrier()
; #define PG8_SCHED __builtin_amdgcn_sched_barrier(0)
; template <class Epi, class Sched, bool ALIGN_EPI = false, bool SP2 = false>
; __device__ __forceinline__ void gemm_phase(PG8_LAS unsigned char* lds, const Gemm g, const Sched& S, const Epi& E) {
;     ...
;         for (int t = 0; t < nt; t += 2) {
;             const bool last = (t == nt - 2);
;     ...
;             PG8_LDA(At, 1, 1); PG8_STAGE(PG8_SB(1, 0), b3, voffB); PG8_STAGE(PG8_SB(1, 1), b3 + hstep, voffB); PG8_STAGE(PG8_SA(1, 0), a3, voffA);
;             PG8_WAIT_V(8); PG8_WAIT_L(0); PG8_BAR; PG8_MMA(1, 0, At, B0); PG8_MMA(1, 1, At, B1); PG8_BAR; PG8_SCHED;
	s_add_i32 s29, s29, s68
	v_lshl_add_u64 v[204:205], v[204:205], 0, s[38:39]
	s_mov_b32 m0, s29
	s_nop 1
	ds_read_b128 v[42:45], v210 offset:49152
	ds_read_b128 v[46:49], v210 offset:50176
	ds_read_b128 v[50:53], v210 offset:51200
	ds_read_b128 v[54:57], v210 offset:52224
	ds_read_b128 v[212:215], v210 offset:53248
	ds_read_b128 v[216:219], v210 offset:54272
	ds_read_b128 v[222:225], v210 offset:55296
	ds_read_b128 v[226:229], v210 offset:56320
	global_load_lds_dwordx4 v[204:205], off
	s_add_i32 m0, s29, 0x2000
	s_add_u32 s58, s58, 0x40080
	v_lshl_add_u64 v[204:205], v[246:247], 0, s[38:39]
	s_addc_u32 s59, s59, 0
	s_add_i32 s29, vcc_lo, s68
	global_load_lds_dwordx4 v[204:205], off
	v_lshl_add_u64 v[204:205], s[58:59], 0, v[180:181]
	s_mov_b32 m0, s29
	s_nop 0
	global_load_lds_dwordx4 v[204:205], off
	v_lshl_add_u64 v[204:205], s[58:59], 0, v[184:185]
	s_add_i32 m0, s29, 0x2000
	s_nop 0
	global_load_lds_dwordx4 v[204:205], off
	v_lshl_add_u64 v[204:205], v[248:249], 0, s[38:39]
	s_mov_b32 m0, s81
	s_nop 0
	global_load_lds_dwordx4 v[204:205], off
	v_lshl_add_u64 v[204:205], v[250:251], 0, s[38:39]
	s_mov_b32 m0, s82
	s_nop 0
	global_load_lds_dwordx4 v[204:205], off
	s_waitcnt vmcnt(8) lgkmcnt(0)
	s_setprio 1
	s_barrier
	v_mfma_f32_16x16x32_bf16 v[78:81], v[146:149], v[42:45], v[78:81]
	v_mfma_f32_16x16x32_bf16 v[74:77], v[154:157], v[42:45], v[74:77]
	v_mfma_f32_16x16x32_bf16 v[62:65], v[146:149], v[50:53], v[62:65]
	v_mfma_f32_16x16x32_bf16 v[58:61], v[154:157], v[50:53], v[58:61]
	v_mfma_f32_16x16x32_bf16 v[30:33], v[146:149], v[212:215], v[30:33]
	v_mfma_f32_16x16x32_bf16 v[26:29], v[154:157], v[212:215], v[26:29]
	v_mfma_f32_16x16x32_bf16 v[14:17], v[146:149], v[222:225], v[14:17]
	v_mfma_f32_16x16x32_bf16 v[10:13], v[154:157], v[222:225], v[10:13]
	v_mfma_f32_16x16x32_bf16 v[78:81], v[150:153], v[46:49], v[78:81]
	v_mfma_f32_16x16x32_bf16 v[74:77], v[158:161], v[46:49], v[74:77]
	v_mfma_f32_16x16x32_bf16 v[62:65], v[150:153], v[54:57], v[62:65]
	v_mfma_f32_16x16x32_bf16 v[58:61], v[158:161], v[54:57], v[58:61]
	v_mfma_f32_16x16x32_bf16 v[30:33], v[150:153], v[216:219], v[30:33]
	v_mfma_f32_16x16x32_bf16 v[26:29], v[158:161], v[216:219], v[26:29]
	v_mfma_f32_16x16x32_bf16 v[14:17], v[150:153], v[226:229], v[14:17]
	v_mfma_f32_16x16x32_bf16 v[10:13], v[158:161], v[226:229], v[10:13]
	v_mfma_f32_16x16x32_bf16 v[70:73], v[162:165], v[42:45], v[70:73]
	v_mfma_f32_16x16x32_bf16 v[42:45], v[170:173], v[42:45], v[66:69]
	v_mfma_f32_16x16x32_bf16 v[38:41], v[162:165], v[50:53], v[38:41]
	v_mfma_f32_16x16x32_bf16 v[34:37], v[170:173], v[50:53], v[34:37]
	v_mfma_f32_16x16x32_bf16 v[22:25], v[162:165], v[212:215], v[22:25]
	v_mfma_f32_16x16x32_bf16 v[18:21], v[170:173], v[212:215], v[18:21]
	v_mfma_f32_16x16x32_bf16 v[6:9], v[162:165], v[222:225], v[6:9]
	v_mfma_f32_16x16x32_bf16 v[2:5], v[170:173], v[222:225], v[2:5]
	v_mfma_f32_16x16x32_bf16 v[70:73], v[166:169], v[46:49], v[70:73]
	v_mfma_f32_16x16x32_bf16 v[66:69], v[174:177], v[46:49], v[42:45]
	v_mfma_f32_16x16x32_bf16 v[38:41], v[166:169], v[54:57], v[38:41]
	v_mfma_f32_16x16x32_bf16 v[34:37], v[174:177], v[54:57], v[34:37]
	v_mfma_f32_16x16x32_bf16 v[22:25], v[166:169], v[216:219], v[22:25]
	v_mfma_f32_16x16x32_bf16 v[18:21], v[174:177], v[216:219], v[18:21]
	v_mfma_f32_16x16x32_bf16 v[6:9], v[166:169], v[226:229], v[6:9]
	v_mfma_f32_16x16x32_bf16 v[2:5], v[174:177], v[226:229], v[2:5]
	s_setprio 0
	s_barrier
	s_add_i32 s29, s28, 2
	s_add_u32 s56, s56, 0x100
	s_addc_u32 s57, s57, 0
	s_cmp_gt_u32 s28, 13
	s_mov_b32 s28, s29
	s_cbranch_scc1 .LBB0_442
; #define PG8_STAGE(bufoff, gbase, voff) do { _Pragma("unroll") for (int _i = 0; _i < 2; ++_i) \
;         __builtin_amdgcn_global_load_lds((const unsigned*)((const char*)(gbase) + (voff)[_i]), (PG8_LAS unsigned*)(lds + (bufoff) + ldsw + _i * 8192), 16, 0, 0); } while (0)
; #define PG8_LDA(dst, b, h) do { _Pragma("unroll") for (int m = 0; m < 4; ++m) _Pragma("unroll") for (int k = 0; k < 2; ++k) dst[m][k] = *(const PG8_LAS bf16x8*)(lds + PG8_SA(b, h) + aoff + m * 2048 + k * 1024); } while (0)
; #define PG8_LDB(dst, b, h) do { _Pragma("unroll") for (int n = 0; n < 2; ++n) _Pragma("unroll") for (int k = 0; k < 2; ++k) dst[n][k] = *(const PG8_LAS bf16x8*)(lds + PG8_SB(b, h) + boff + n * 2048 + k * 1024); } while (0)
; #define PG8_MMA(ai, bj, At, Bt) do { __builtin_amdgcn_s_setprio(1); _Pragma("unroll") for (int m = 0; m < 4; ++m) _Pragma("unroll") for (int n = 0; n < 2; ++n) _Pragma("unroll") for (int k = 0; k < 2; ++k) \
;         acc[ai][bj][m][n] = __builtin_amdgcn_mfma_f32_16x16x32_bf16(Bt[n][k], At[m][k], acc[ai][bj][m][n], 0, 0, 0); __builtin_amdgcn_s_setprio(0); } while (0)
; #define PG8_WAIT_V(n) asm volatile("s_waitcnt vmcnt(" #n ")" ::: "memory")
; #define PG8_WAIT_L(n) asm volatile("s_waitcnt lgkmcnt(" #n ")" ::: "memory")
; #define PG8_BAR __builtin_amdgcn_s_barrier()
; #define PG8_SCHED __builtin_amdgcn_sched_barrier(0)
;     __device__ __forceinline__ void prefetch(const Unit& u, int wid, int lane) const { epi_prefetch(scr, ssq, bias + (size_t)(u.pm >> 5) * NGU + u.pn * BM, u, wid, lane); }
;     __device__ __forceinline__ void prefetch(const Unit& u, int wid, int lane) const { epi_prefetch(scr, ssq, bias + (size_t)(u.pm >> 5) * DIN + u.pn * BM, u, wid, lane); }
; template <class Epi, class Sched, bool ALIGN_EPI = false, bool SP2 = false>
; __device__ __forceinline__ void gemm_phase(PG8_LAS unsigned char* lds, const Gemm g, const Sched& S, const Epi& E) {
;     ...
;             PG8_LDB(B0, 0, 0); PG8_LDB(B1, 0, 1); PG8_SCHED; PG8_LDA(At, 0, 0); PG8_STAGE(PG8_SA(1, 1), a1 + hstep, voffA);
;             PG8_WAIT_V(8); PG8_WAIT_L(0); PG8_BAR; PG8_MMA(0, 0, At, B0); PG8_MMA(0, 1, At, B1); PG8_BAR; PG8_SCHED;
;             if constexpr (Epi::PREFETCH) { if (t == tpf) E.prefetch(cur, wid, lane); }
.LBB0_439:
	ds_read_b128 v[162:165], v208
	ds_read_b128 v[166:169], v208 offset:1024
	ds_read_b128 v[170:173], v208 offset:2048
	ds_read_b128 v[174:177], v208 offset:3072
	ds_read_b128 v[146:149], v209
	ds_read_b128 v[150:153], v209 offset:1024
	ds_read_b128 v[154:157], v209 offset:2048
	ds_read_b128 v[158:161], v209 offset:3072
	v_lshl_add_u64 v[42:43], v[196:197], 0, s[56:57]
	s_add_i32 m0, s69, 0xc000
	ds_read_b128 v[212:215], v210
	ds_read_b128 v[216:219], v210 offset:1024
	ds_read_b128 v[222:225], v210 offset:2048
	ds_read_b128 v[226:229], v210 offset:3072
	ds_read_b128 v[230:233], v210 offset:4096
	ds_read_b128 v[234:237], v210 offset:5120
	ds_read_b128 v[238:241], v210 offset:6144
	ds_read_b128 v[242:245], v210 offset:7168
	global_load_lds_dwordx4 v[42:43], off
	v_lshl_add_u64 v[42:43], v[198:199], 0, s[56:57]
	s_add_i32 m0, s69, 0xe000
	s_nop 0
	global_load_lds_dwordx4 v[42:43], off
	s_waitcnt vmcnt(8) lgkmcnt(0)
	s_setprio 1
	s_barrier
	v_mfma_f32_16x16x32_bf16 v[42:45], v[162:165], v[212:215], v[142:145]
	v_mfma_f32_16x16x32_bf16 v[46:49], v[170:173], v[212:215], v[138:141]
	v_mfma_f32_16x16x32_bf16 v[50:53], v[162:165], v[222:225], v[126:129]
	v_mfma_f32_16x16x32_bf16 v[54:57], v[170:173], v[222:225], v[122:125]
	v_mfma_f32_16x16x32_bf16 v[110:113], v[162:165], v[230:233], v[110:113]
	v_mfma_f32_16x16x32_bf16 v[106:109], v[170:173], v[230:233], v[106:109]
	v_mfma_f32_16x16x32_bf16 v[94:97], v[162:165], v[238:241], v[94:97]
	v_mfma_f32_16x16x32_bf16 v[90:93], v[170:173], v[238:241], v[90:93]
	v_mfma_f32_16x16x32_bf16 v[42:45], v[166:169], v[216:219], v[42:45]
	v_mfma_f32_16x16x32_bf16 v[46:49], v[174:177], v[216:219], v[46:49]
	v_mfma_f32_16x16x32_bf16 v[50:53], v[166:169], v[226:229], v[50:53]
	v_mfma_f32_16x16x32_bf16 v[54:57], v[174:177], v[226:229], v[54:57]
	v_mfma_f32_16x16x32_bf16 v[110:113], v[166:169], v[234:237], v[110:113]
	v_mfma_f32_16x16x32_bf16 v[106:109], v[174:177], v[234:237], v[106:109]
	v_mfma_f32_16x16x32_bf16 v[94:97], v[166:169], v[242:245], v[94:97]
	v_mfma_f32_16x16x32_bf16 v[90:93], v[174:177], v[242:245], v[90:93]
	v_mfma_f32_16x16x32_bf16 v[122:125], v[146:149], v[212:215], v[134:137]
	v_mfma_f32_16x16x32_bf16 v[134:137], v[150:153], v[216:219], v[122:125]
	v_mfma_f32_16x16x32_bf16 v[122:125], v[154:157], v[212:215], v[130:133]
	v_mfma_f32_16x16x32_bf16 v[118:121], v[146:149], v[222:225], v[118:121]
	v_mfma_f32_16x16x32_bf16 v[114:117], v[154:157], v[222:225], v[114:117]
	v_mfma_f32_16x16x32_bf16 v[102:105], v[146:149], v[230:233], v[102:105]
	v_mfma_f32_16x16x32_bf16 v[98:101], v[154:157], v[230:233], v[98:101]
	v_mfma_f32_16x16x32_bf16 v[86:89], v[146:149], v[238:241], v[86:89]
	v_mfma_f32_16x16x32_bf16 v[82:85], v[154:157], v[238:241], v[82:85]
	v_mfma_f32_16x16x32_bf16 v[130:133], v[158:161], v[216:219], v[122:125]
	v_mfma_f32_16x16x32_bf16 v[118:121], v[150:153], v[226:229], v[118:121]
	v_mfma_f32_16x16x32_bf16 v[114:117], v[158:161], v[226:229], v[114:117]
	v_mfma_f32_16x16x32_bf16 v[102:105], v[150:153], v[234:237], v[102:105]
	v_mfma_f32_16x16x32_bf16 v[98:101], v[158:161], v[234:237], v[98:101]
	v_mfma_f32_16x16x32_bf16 v[86:89], v[150:153], v[242:245], v[86:89]
	v_mfma_f32_16x16x32_bf16 v[82:85], v[158:161], v[242:245], v[82:85]
	s_setprio 0
	s_barrier
	s_cmp_lg_u32 s63, s28
	s_cbranch_scc1 .LBB0_438
	v_mov_b32_e32 v186, v207
	s_add_i32 m0, s62, 0x20000
	v_lshl_add_u64 v[122:123], s[52:53], 0, v[186:187]
	s_mov_b64 s[58:59], 0x400
	global_load_lds_dwordx4 v186, s[52:53]
	v_lshl_add_u64 v[122:123], v[122:123], 0, s[58:59]
	s_add_i32 m0, s62, 0x20400
	s_andn2_b64 vcc, exec, s[40:41]
	global_load_lds_dwordx4 v[122:123], off
	s_cbranch_vccnz .LBB0_438
	v_lshl_add_u64 v[122:123], s[54:55], 0, v[186:187]
	s_mov_b32 m0, s30
	s_nop 0
	global_load_lds_dwordx4 v[122:123], off
	s_branch .LBB0_438

; #define PG8_STAGE(bufoff, gbase, voff) do { _Pragma("unroll") for (int _i = 0; _i < 2; ++_i) \
;         __builtin_amdgcn_global_load_lds((const unsigned*)((const char*)(gbase) + (voff)[_i]), (PG8_LAS unsigned*)(lds + (bufoff) + ldsw + _i * 8192), 16, 0, 0); } while (0)
; #define PG8_LDA(dst, b, h) do { _Pragma("unroll") for (int m = 0; m < 4; ++m) _Pragma("unroll") for (int k = 0; k < 2; ++k) dst[m][k] = *(const PG8_LAS bf16x8*)(lds + PG8_SA(b, h) + aoff + m * 2048 + k * 1024); } while (0)
; #define PG8_LDB(dst, b, h) do { _Pragma("unroll") for (int n = 0; n < 2; ++n) _Pragma("unroll") for (int k = 0; k < 2; ++k) dst[n][k] = *(const PG8_LAS bf16x8*)(lds + PG8_SB(b, h) + boff + n * 2048 + k * 1024); } while (0)
; #define PG8_MMA(ai, bj, At, Bt) do { __builtin_amdgcn_s_setprio(1); _Pragma("unroll") for (int m = 0; m < 4; ++m) _Pragma("unroll") for (int n = 0; n < 2; ++n) _Pragma("unroll") for (int k = 0; k < 2; ++k) \
;         acc[ai][bj][m][n] = __builtin_amdgcn_mfma_f32_16x16x32_bf16(Bt[n][k], At[m][k], acc[ai][bj][m][n], 0, 0, 0); __builtin_amdgcn_s_setprio(0); } while (0)
; #define PG8_WAIT_V(n) asm volatile("s_waitcnt vmcnt(" #n ")" ::: "memory")
; #define PG8_WAIT_L(n) asm volatile("s_waitcnt lgkmcnt(" #n ")" ::: "memory")
; #define PG8_BAR __builtin_amdgcn_s_barrier()
; #define PG8_SCHED __builtin_amdgcn_sched_barrier(0)
;     __device__ __forceinline__ void prefetch(const Unit& u, int wid, int lane) const { epi_prefetch(scr, ssq, bias + (size_t)(u.pm >> 5) * NGU + u.pn * BM, u, wid, lane); }
;     __device__ __forceinline__ void prefetch(const Unit& u, int wid, int lane) const { epi_prefetch(scr, ssq, bias + (size_t)(u.pm >> 5) * DIN + u.pn * BM, u, wid, lane); }
; template <class Epi, class Sched, bool ALIGN_EPI = false, bool SP2 = false>
; __device__ __forceinline__ void gemm_phase(PG8_LAS unsigned char* lds, const Gemm g, const Sched& S, const Epi& E) {
;     ...
;             PG8_LDB(B0, 0, 0); PG8_LDB(B1, 0, 1); PG8_SCHED; PG8_LDA(At, 0, 0); PG8_STAGE(PG8_SA(1, 1), a1 + hstep, voffA);
;             PG8_WAIT_V(8); PG8_WAIT_L(0); PG8_BAR; PG8_MMA(0, 0, At, B0); PG8_MMA(0, 1, At, B1); PG8_BAR; PG8_SCHED;
;             if constexpr (Epi::PREFETCH) { if (t == tpf) E.prefetch(cur, wid, lane); }
;             PG8_LDA(At, 0, 1); PG8_STAGE(PG8_SB(0, 0), b2, voffB); PG8_STAGE(PG8_SB(0, 1), b2 + hstep, voffB); PG8_STAGE(PG8_SA(0, 0), a2, voffA);
.LBB0_723:
	v_add_u32_e32 v2, s67, v177
	ds_read_b128 v[134:137], v2
	ds_read_b128 v[138:141], v2 offset:1024
	ds_read_b128 v[142:145], v2 offset:2048
	ds_read_b128 v[146:149], v2 offset:3072
	v_add_u32_e32 v2, s68, v177
	ds_read_b128 v[150:153], v2
	ds_read_b128 v[170:173], v2 offset:1024
	ds_read_b128 v[180:183], v2 offset:2048
	ds_read_b128 v[184:187], v2 offset:3072
	s_add_u32 s28, s0, 0xfffc0080
	s_addc_u32 s29, s1, -1
	s_cmp_eq_u32 s43, 12
	s_cselect_b32 s37, s23, s29
	s_cselect_b32 s36, s39, s28
	s_cselect_b32 s29, s21, s42
	s_cselect_b32 s28, s40, s41
	v_lshl_add_u64 v[4:5], s[0:1], 0, v[162:163]
	s_add_i32 m0, s31, 0xc000
	ds_read_b128 v[188:191], v178
	ds_read_b128 v[192:195], v178 offset:1024
	ds_read_b128 v[196:199], v178 offset:2048
	ds_read_b128 v[200:203], v178 offset:3072
	ds_read_b128 v[204:207], v178 offset:4096
	ds_read_b128 v[208:211], v178 offset:5120
	ds_read_b128 v[212:215], v178 offset:6144
	ds_read_b128 v[216:219], v178 offset:7168
	global_load_lds_dwordx4 v[4:5], off
	v_lshl_add_u64 v[4:5], s[0:1], 0, v[164:165]
	s_add_i32 m0, s31, 0xe000
	s_nop 0
	global_load_lds_dwordx4 v[4:5], off
	s_waitcnt vmcnt(8) lgkmcnt(0)
	s_setprio 1
	s_barrier
	v_mfma_f32_16x16x32_bf16 v[130:133], v[134:137], v[188:191], v[130:133]
	v_mfma_f32_16x16x32_bf16 v[126:129], v[142:145], v[188:191], v[126:129]
	v_mfma_f32_16x16x32_bf16 v[122:125], v[134:137], v[196:199], v[122:125]
	v_mfma_f32_16x16x32_bf16 v[118:121], v[142:145], v[196:199], v[118:121]
	v_mfma_f32_16x16x32_bf16 v[114:117], v[134:137], v[204:207], v[114:117]
	v_mfma_f32_16x16x32_bf16 v[110:113], v[142:145], v[204:207], v[110:113]
	v_mfma_f32_16x16x32_bf16 v[106:109], v[134:137], v[212:215], v[106:109]
	v_mfma_f32_16x16x32_bf16 v[102:105], v[142:145], v[212:215], v[102:105]
	v_mfma_f32_16x16x32_bf16 v[130:133], v[138:141], v[192:195], v[130:133]
	v_mfma_f32_16x16x32_bf16 v[126:129], v[146:149], v[192:195], v[126:129]
	v_mfma_f32_16x16x32_bf16 v[122:125], v[138:141], v[200:203], v[122:125]
	v_mfma_f32_16x16x32_bf16 v[118:121], v[146:149], v[200:203], v[118:121]
	v_mfma_f32_16x16x32_bf16 v[114:117], v[138:141], v[208:211], v[114:117]
	v_mfma_f32_16x16x32_bf16 v[110:113], v[146:149], v[208:211], v[110:113]
	v_mfma_f32_16x16x32_bf16 v[106:109], v[138:141], v[216:219], v[106:109]
	v_mfma_f32_16x16x32_bf16 v[102:105], v[146:149], v[216:219], v[102:105]
	v_mfma_f32_16x16x32_bf16 v[98:101], v[150:153], v[188:191], v[98:101]
	v_mfma_f32_16x16x32_bf16 v[94:97], v[180:183], v[188:191], v[94:97]
	v_mfma_f32_16x16x32_bf16 v[90:93], v[150:153], v[196:199], v[90:93]
	v_mfma_f32_16x16x32_bf16 v[86:89], v[180:183], v[196:199], v[86:89]
	v_mfma_f32_16x16x32_bf16 v[82:85], v[150:153], v[204:207], v[82:85]
	v_mfma_f32_16x16x32_bf16 v[78:81], v[180:183], v[204:207], v[78:81]
	v_mfma_f32_16x16x32_bf16 v[74:77], v[150:153], v[212:215], v[74:77]
	v_mfma_f32_16x16x32_bf16 v[70:73], v[180:183], v[212:215], v[70:73]
	v_mfma_f32_16x16x32_bf16 v[98:101], v[170:173], v[192:195], v[98:101]
	v_mfma_f32_16x16x32_bf16 v[94:97], v[184:187], v[192:195], v[94:97]
	v_mfma_f32_16x16x32_bf16 v[90:93], v[170:173], v[200:203], v[90:93]
	v_mfma_f32_16x16x32_bf16 v[86:89], v[184:187], v[200:203], v[86:89]
	v_mfma_f32_16x16x32_bf16 v[82:85], v[170:173], v[208:211], v[82:85]
	v_mfma_f32_16x16x32_bf16 v[78:81], v[184:187], v[208:211], v[78:81]
	v_mfma_f32_16x16x32_bf16 v[74:77], v[170:173], v[216:219], v[74:77]
	v_mfma_f32_16x16x32_bf16 v[70:73], v[184:187], v[216:219], v[70:73]
	s_setprio 0
	s_barrier
	s_add_i32 s71, s67, s48
	v_lshl_add_u64 v[174:175], s[28:29], 0, v[156:157]
	s_mov_b32 m0, s71
	ds_read_b128 v[188:191], v178 offset:16384
	ds_read_b128 v[192:195], v178 offset:17408
	ds_read_b128 v[196:199], v178 offset:18432
	ds_read_b128 v[200:203], v178 offset:19456
	ds_read_b128 v[204:207], v178 offset:20480
	ds_read_b128 v[208:211], v178 offset:21504
	ds_read_b128 v[212:215], v178 offset:22528
	ds_read_b128 v[216:219], v178 offset:23552
	global_load_lds_dwordx4 v[174:175], off
	s_add_i32 m0, s71, 0x2000
	s_add_u32 s72, s28, 0x40000
	v_lshl_add_u64 v[222:223], s[28:29], 0, v[160:161]
	s_addc_u32 s73, s29, 0
	s_add_i32 s71, s68, s48
	global_load_lds_dwordx4 v[222:223], off
	v_lshl_add_u64 v[4:5], s[72:73], 0, v[156:157]
	s_mov_b32 m0, s71
	v_lshl_add_u64 v[224:225], s[36:37], 0, v[154:155]
	global_load_lds_dwordx4 v[4:5], off
	v_lshl_add_u64 v[4:5], s[72:73], 0, v[160:161]
	s_add_i32 m0, s71, 0x2000
	v_lshl_add_u64 v[226:227], s[36:37], 0, v[158:159]
	global_load_lds_dwordx4 v[4:5], off
	s_mov_b32 m0, s31
	s_nop 0
	global_load_lds_dwordx4 v[224:225], off
	s_mov_b32 m0, s35
	s_nop 0
	global_load_lds_dwordx4 v[226:227], off
	s_waitcnt vmcnt(8) lgkmcnt(0)
	s_setprio 1
	s_barrier
; #define PG8_STAGE(bufoff, gbase, voff) do { _Pragma("unroll") for (int _i = 0; _i < 2; ++_i) \
;         __builtin_amdgcn_global_load_lds((const unsigned*)((const char*)(gbase) + (voff)[_i]), (PG8_LAS unsigned*)(lds + (bufoff) + ldsw + _i * 8192), 16, 0, 0); } while (0)
; #define PG8_LDA(dst, b, h) do { _Pragma("unroll") for (int m = 0; m < 4; ++m) _Pragma("unroll") for (int k = 0; k < 2; ++k) dst[m][k] = *(const PG8_LAS bf16x8*)(lds + PG8_SA(b, h) + aoff + m * 2048 + k * 1024); } while (0)
; #define PG8_LDB(dst, b, h) do { _Pragma("unroll") for (int n = 0; n < 2; ++n) _Pragma("unroll") for (int k = 0; k < 2; ++k) dst[n][k] = *(const PG8_LAS bf16x8*)(lds + PG8_SB(b, h) + boff + n * 2048 + k * 1024); } while (0)
; #define PG8_MMA(ai, bj, At, Bt) do { __builtin_amdgcn_s_setprio(1); _Pragma("unroll") for (int m = 0; m < 4; ++m) _Pragma("unroll") for (int n = 0; n < 2; ++n) _Pragma("unroll") for (int k = 0; k < 2; ++k) \
;         acc[ai][bj][m][n] = __builtin_amdgcn_mfma_f32_16x16x32_bf16(Bt[n][k], At[m][k], acc[ai][bj][m][n], 0, 0, 0); __builtin_amdgcn_s_setprio(0); } while (0)
; #define PG8_WAIT_V(n) asm volatile("s_waitcnt vmcnt(" #n ")" ::: "memory")
; #define PG8_WAIT_L(n) asm volatile("s_waitcnt lgkmcnt(" #n ")" ::: "memory")
; #define PG8_BAR __builtin_amdgcn_s_barrier()
; #define PG8_SCHED __builtin_amdgcn_sched_barrier(0)
; template <class Epi, class Sched, bool ALIGN_EPI = false, bool SP2 = false>
; __device__ __forceinline__ void gemm_phase(PG8_LAS unsigned char* lds, const Gemm g, const Sched& S, const Epi& E) {
;     ...
;             PG8_WAIT_V(8); PG8_WAIT_L(0); PG8_BAR; PG8_MMA(1, 0, At, B0); PG8_MMA(1, 1, At, B1); PG8_BAR; PG8_SCHED;
;             PG8_LDB(B0, 1, 0); PG8_LDB(B1, 1, 1); PG8_SCHED; PG8_LDA(At, 1, 0); PG8_STAGE(PG8_SA(0, 1), a2 + hstep, voffA);
;             PG8_WAIT_V(8); PG8_WAIT_L(0); PG8_BAR; PG8_MMA(0, 0, At, B0); PG8_MMA(0, 1, At, B1); PG8_BAR; PG8_SCHED;
	v_mfma_f32_16x16x32_bf16 v[66:69], v[134:137], v[188:191], v[66:69]
	v_mfma_f32_16x16x32_bf16 v[62:65], v[142:145], v[188:191], v[62:65]
	v_mfma_f32_16x16x32_bf16 v[58:61], v[134:137], v[196:199], v[58:61]
	v_mfma_f32_16x16x32_bf16 v[54:57], v[142:145], v[196:199], v[54:57]
	v_mfma_f32_16x16x32_bf16 v[50:53], v[134:137], v[204:207], v[50:53]
	v_mfma_f32_16x16x32_bf16 v[46:49], v[142:145], v[204:207], v[46:49]
	v_mfma_f32_16x16x32_bf16 v[42:45], v[134:137], v[212:215], v[42:45]
	v_mfma_f32_16x16x32_bf16 v[38:41], v[142:145], v[212:215], v[38:41]
	v_mfma_f32_16x16x32_bf16 v[66:69], v[138:141], v[192:195], v[66:69]
	v_mfma_f32_16x16x32_bf16 v[62:65], v[146:149], v[192:195], v[62:65]
	v_mfma_f32_16x16x32_bf16 v[58:61], v[138:141], v[200:203], v[58:61]
	v_mfma_f32_16x16x32_bf16 v[54:57], v[146:149], v[200:203], v[54:57]
	v_mfma_f32_16x16x32_bf16 v[50:53], v[138:141], v[208:211], v[50:53]
	v_mfma_f32_16x16x32_bf16 v[46:49], v[146:149], v[208:211], v[46:49]
	v_mfma_f32_16x16x32_bf16 v[42:45], v[138:141], v[216:219], v[42:45]
	v_mfma_f32_16x16x32_bf16 v[38:41], v[146:149], v[216:219], v[38:41]
	v_mfma_f32_16x16x32_bf16 v[34:37], v[150:153], v[188:191], v[34:37]
	v_mfma_f32_16x16x32_bf16 v[30:33], v[180:183], v[188:191], v[30:33]
	v_mfma_f32_16x16x32_bf16 v[26:29], v[150:153], v[196:199], v[26:29]
	v_mfma_f32_16x16x32_bf16 v[22:25], v[180:183], v[196:199], v[22:25]
	v_mfma_f32_16x16x32_bf16 v[18:21], v[150:153], v[204:207], v[18:21]
	v_mfma_f32_16x16x32_bf16 v[14:17], v[180:183], v[204:207], v[14:17]
	v_mfma_f32_16x16x32_bf16 v[10:13], v[150:153], v[212:215], v[10:13]
	v_mfma_f32_16x16x32_bf16 v[4:7], v[180:183], v[212:215], v[6:9]
	v_mfma_f32_16x16x32_bf16 v[34:37], v[170:173], v[192:195], v[34:37]
	v_mfma_f32_16x16x32_bf16 v[30:33], v[184:187], v[192:195], v[30:33]
	v_mfma_f32_16x16x32_bf16 v[26:29], v[170:173], v[200:203], v[26:29]
	v_mfma_f32_16x16x32_bf16 v[22:25], v[184:187], v[200:203], v[22:25]
	v_mfma_f32_16x16x32_bf16 v[18:21], v[170:173], v[208:211], v[18:21]
	v_mfma_f32_16x16x32_bf16 v[14:17], v[184:187], v[208:211], v[14:17]
	v_mfma_f32_16x16x32_bf16 v[10:13], v[170:173], v[216:219], v[10:13]
	v_mfma_f32_16x16x32_bf16 v[4:7], v[184:187], v[216:219], v[4:7]
	s_setprio 0
	s_barrier
	s_add_i32 s71, 0, 0x18000
	v_add_u32_e32 v2, s71, v177
	s_add_i32 s72, 0, 0x1c000
	ds_read_b128 v[134:137], v2
	ds_read_b128 v[138:141], v2 offset:1024
	ds_read_b128 v[142:145], v2 offset:2048
	ds_read_b128 v[146:149], v2 offset:3072
	v_add_u32_e32 v2, s72, v177
	ds_read_b128 v[150:153], v2
	ds_read_b128 v[170:173], v2 offset:1024
	ds_read_b128 v[180:183], v2 offset:2048
	ds_read_b128 v[184:187], v2 offset:3072
	s_add_u32 s36, s36, 0x40000
	s_addc_u32 s37, s37, 0
	s_mov_b32 m0, s49
	v_lshl_add_u64 v[8:9], s[36:37], 0, v[154:155]
	ds_read_b128 v[188:191], v178 offset:32768
	ds_read_b128 v[192:195], v178 offset:33792
	ds_read_b128 v[196:199], v178 offset:34816
	ds_read_b128 v[200:203], v178 offset:35840
	ds_read_b128 v[204:207], v178 offset:36864
	ds_read_b128 v[208:211], v178 offset:37888
	ds_read_b128 v[212:215], v178 offset:38912
	ds_read_b128 v[216:219], v178 offset:39936
	global_load_lds_dwordx4 v[8:9], off
	v_lshl_add_u64 v[8:9], s[36:37], 0, v[158:159]
	s_mov_b32 m0, s50
	s_nop 0
	global_load_lds_dwordx4 v[8:9], off
	s_waitcnt vmcnt(8) lgkmcnt(0)
	s_setprio 1
	s_barrier
	v_mfma_f32_16x16x32_bf16 v[130:133], v[134:137], v[188:191], v[130:133]
	v_mfma_f32_16x16x32_bf16 v[126:129], v[142:145], v[188:191], v[126:129]
	v_mfma_f32_16x16x32_bf16 v[122:125], v[134:137], v[196:199], v[122:125]
	v_mfma_f32_16x16x32_bf16 v[118:121], v[142:145], v[196:199], v[118:121]
	v_mfma_f32_16x16x32_bf16 v[114:117], v[134:137], v[204:207], v[114:117]
	v_mfma_f32_16x16x32_bf16 v[110:113], v[142:145], v[204:207], v[110:113]
	v_mfma_f32_16x16x32_bf16 v[106:109], v[134:137], v[212:215], v[106:109]
	v_mfma_f32_16x16x32_bf16 v[102:105], v[142:145], v[212:215], v[102:105]
	v_mfma_f32_16x16x32_bf16 v[130:133], v[138:141], v[192:195], v[130:133]
	v_mfma_f32_16x16x32_bf16 v[126:129], v[146:149], v[192:195], v[126:129]
	v_mfma_f32_16x16x32_bf16 v[122:125], v[138:141], v[200:203], v[122:125]
	v_mfma_f32_16x16x32_bf16 v[118:121], v[146:149], v[200:203], v[118:121]
	v_mfma_f32_16x16x32_bf16 v[114:117], v[138:141], v[208:211], v[114:117]
	v_mfma_f32_16x16x32_bf16 v[110:113], v[146:149], v[208:211], v[110:113]
	v_mfma_f32_16x16x32_bf16 v[106:109], v[138:141], v[216:219], v[106:109]
	v_mfma_f32_16x16x32_bf16 v[102:105], v[146:149], v[216:219], v[102:105]
	v_mfma_f32_16x16x32_bf16 v[98:101], v[150:153], v[188:191], v[98:101]
	v_mfma_f32_16x16x32_bf16 v[94:97], v[180:183], v[188:191], v[94:97]
	v_mfma_f32_16x16x32_bf16 v[90:93], v[150:153], v[196:199], v[90:93]
	v_mfma_f32_16x16x32_bf16 v[86:89], v[180:183], v[196:199], v[86:89]
	v_mfma_f32_16x16x32_bf16 v[82:85], v[150:153], v[204:207], v[82:85]
	v_mfma_f32_16x16x32_bf16 v[78:81], v[180:183], v[204:207], v[78:81]
	v_mfma_f32_16x16x32_bf16 v[74:77], v[150:153], v[212:215], v[74:77]
	v_mfma_f32_16x16x32_bf16 v[70:73], v[180:183], v[212:215], v[70:73]
	v_mfma_f32_16x16x32_bf16 v[98:101], v[170:173], v[192:195], v[98:101]
	v_mfma_f32_16x16x32_bf16 v[94:97], v[184:187], v[192:195], v[94:97]
	v_mfma_f32_16x16x32_bf16 v[90:93], v[170:173], v[200:203], v[90:93]
	v_mfma_f32_16x16x32_bf16 v[86:89], v[184:187], v[200:203], v[86:89]
	v_mfma_f32_16x16x32_bf16 v[82:85], v[170:173], v[208:211], v[82:85]
	v_mfma_f32_16x16x32_bf16 v[78:81], v[184:187], v[208:211], v[78:81]
	v_mfma_f32_16x16x32_bf16 v[74:77], v[170:173], v[216:219], v[74:77]
	v_mfma_f32_16x16x32_bf16 v[70:73], v[184:187], v[216:219], v[70:73]
	s_setprio 0
	s_barrier
; #define PG8_STAGE(bufoff, gbase, voff) do { _Pragma("unroll") for (int _i = 0; _i < 2; ++_i) \
;         __builtin_amdgcn_global_load_lds((const unsigned*)((const char*)(gbase) + (voff)[_i]), (PG8_LAS unsigned*)(lds + (bufoff) + ldsw + _i * 8192), 16, 0, 0); } while (0)
; #define PG8_LDA(dst, b, h) do { _Pragma("unroll") for (int m = 0; m < 4; ++m) _Pragma("unroll") for (int k = 0; k < 2; ++k) dst[m][k] = *(const PG8_LAS bf16x8*)(lds + PG8_SA(b, h) + aoff + m * 2048 + k * 1024); } while (0)
; #define PG8_MMA(ai, bj, At, Bt) do { __builtin_amdgcn_s_setprio(1); _Pragma("unroll") for (int m = 0; m < 4; ++m) _Pragma("unroll") for (int n = 0; n < 2; ++n) _Pragma("unroll") for (int k = 0; k < 2; ++k) \
;         acc[ai][bj][m][n] = __builtin_amdgcn_mfma_f32_16x16x32_bf16(Bt[n][k], At[m][k], acc[ai][bj][m][n], 0, 0, 0); __builtin_amdgcn_s_setprio(0); } while (0)
; #define PG8_WAIT_V(n) asm volatile("s_waitcnt vmcnt(" #n ")" ::: "memory")
; #define PG8_WAIT_L(n) asm volatile("s_waitcnt lgkmcnt(" #n ")" ::: "memory")
; #define PG8_BAR __builtin_amdgcn_s_barrier()
; #define PG8_SCHED __builtin_amdgcn_sched_barrier(0)
; template <class Epi, class Sched, bool ALIGN_EPI = false, bool SP2 = false>
; __device__ __forceinline__ void gemm_phase(PG8_LAS unsigned char* lds, const Gemm g, const Sched& S, const Epi& E) {
;     ...
;         for (int t = 0; t < nt; t += 2) {
;             const bool last = (t == nt - 2);
;     ...
;             PG8_LDA(At, 1, 1); PG8_STAGE(PG8_SB(1, 0), b3, voffB); PG8_STAGE(PG8_SB(1, 1), b3 + hstep, voffB); PG8_STAGE(PG8_SA(1, 0), a3, voffA);
;             PG8_WAIT_V(8); PG8_WAIT_L(0); PG8_BAR; PG8_MMA(1, 0, At, B0); PG8_MMA(1, 1, At, B1); PG8_BAR; PG8_SCHED;
	s_add_i32 s36, s71, s48
	v_lshl_add_u64 v[8:9], v[174:175], 0, s[14:15]
	s_mov_b32 m0, s36
	ds_read_b128 v[188:191], v178 offset:49152
	ds_read_b128 v[192:195], v178 offset:50176
	ds_read_b128 v[196:199], v178 offset:51200
	ds_read_b128 v[200:203], v178 offset:52224
	ds_read_b128 v[204:207], v178 offset:53248
	ds_read_b128 v[208:211], v178 offset:54272
	ds_read_b128 v[212:215], v178 offset:55296
	ds_read_b128 v[216:219], v178 offset:56320
	global_load_lds_dwordx4 v[8:9], off
	s_add_i32 m0, s36, 0x2000
	s_add_u32 s28, s28, 0x40080
	v_lshl_add_u64 v[8:9], v[222:223], 0, s[14:15]
	s_addc_u32 s29, s29, 0
	s_add_i32 s36, s72, s48
	global_load_lds_dwordx4 v[8:9], off
	v_lshl_add_u64 v[8:9], s[28:29], 0, v[156:157]
	s_mov_b32 m0, s36
	s_nop 0
	global_load_lds_dwordx4 v[8:9], off
	v_lshl_add_u64 v[8:9], s[28:29], 0, v[160:161]
	s_add_i32 m0, s36, 0x2000
	s_nop 0
	global_load_lds_dwordx4 v[8:9], off
	v_lshl_add_u64 v[8:9], v[224:225], 0, s[14:15]
	s_mov_b32 m0, s58
	s_nop 0
	global_load_lds_dwordx4 v[8:9], off
	v_lshl_add_u64 v[8:9], v[226:227], 0, s[14:15]
	s_mov_b32 m0, s59
	s_nop 0
	global_load_lds_dwordx4 v[8:9], off
	s_waitcnt vmcnt(8) lgkmcnt(0)
	s_setprio 1
	s_barrier
	v_mfma_f32_16x16x32_bf16 v[66:69], v[134:137], v[188:191], v[66:69]
	v_mfma_f32_16x16x32_bf16 v[62:65], v[142:145], v[188:191], v[62:65]
	v_mfma_f32_16x16x32_bf16 v[58:61], v[134:137], v[196:199], v[58:61]
	v_mfma_f32_16x16x32_bf16 v[54:57], v[142:145], v[196:199], v[54:57]
	v_mfma_f32_16x16x32_bf16 v[50:53], v[134:137], v[204:207], v[50:53]
	v_mfma_f32_16x16x32_bf16 v[46:49], v[142:145], v[204:207], v[46:49]
	v_mfma_f32_16x16x32_bf16 v[42:45], v[134:137], v[212:215], v[42:45]
	v_mfma_f32_16x16x32_bf16 v[38:41], v[142:145], v[212:215], v[38:41]
	v_mfma_f32_16x16x32_bf16 v[66:69], v[138:141], v[192:195], v[66:69]
	v_mfma_f32_16x16x32_bf16 v[62:65], v[146:149], v[192:195], v[62:65]
	v_mfma_f32_16x16x32_bf16 v[58:61], v[138:141], v[200:203], v[58:61]
	v_mfma_f32_16x16x32_bf16 v[54:57], v[146:149], v[200:203], v[54:57]
	v_mfma_f32_16x16x32_bf16 v[50:53], v[138:141], v[208:211], v[50:53]
	v_mfma_f32_16x16x32_bf16 v[46:49], v[146:149], v[208:211], v[46:49]
	v_mfma_f32_16x16x32_bf16 v[42:45], v[138:141], v[216:219], v[42:45]
	v_mfma_f32_16x16x32_bf16 v[38:41], v[146:149], v[216:219], v[38:41]
	v_mfma_f32_16x16x32_bf16 v[34:37], v[150:153], v[188:191], v[34:37]
	v_mfma_f32_16x16x32_bf16 v[30:33], v[180:183], v[188:191], v[30:33]
	v_mfma_f32_16x16x32_bf16 v[26:29], v[150:153], v[196:199], v[26:29]
	v_mfma_f32_16x16x32_bf16 v[22:25], v[180:183], v[196:199], v[22:25]
	v_mfma_f32_16x16x32_bf16 v[18:21], v[150:153], v[204:207], v[18:21]
	v_mfma_f32_16x16x32_bf16 v[14:17], v[180:183], v[204:207], v[14:17]
	v_mfma_f32_16x16x32_bf16 v[8:11], v[150:153], v[212:215], v[10:13]
	v_mfma_f32_16x16x32_bf16 v[4:7], v[180:183], v[212:215], v[4:7]
	v_mfma_f32_16x16x32_bf16 v[34:37], v[170:173], v[192:195], v[34:37]
	v_mfma_f32_16x16x32_bf16 v[30:33], v[184:187], v[192:195], v[30:33]
	v_mfma_f32_16x16x32_bf16 v[26:29], v[170:173], v[200:203], v[26:29]
	v_mfma_f32_16x16x32_bf16 v[22:25], v[184:187], v[200:203], v[22:25]
	v_mfma_f32_16x16x32_bf16 v[18:21], v[170:173], v[208:211], v[18:21]
	v_mfma_f32_16x16x32_bf16 v[14:17], v[184:187], v[208:211], v[14:17]
	v_mfma_f32_16x16x32_bf16 v[10:13], v[170:173], v[216:219], v[8:11]
	v_mfma_f32_16x16x32_bf16 v[6:9], v[184:187], v[216:219], v[4:7]
	s_setprio 0
	s_barrier
	s_add_i32 s43, s43, 2
	s_add_u32 s0, s0, 0x100
	s_addc_u32 s1, s1, 0
	s_add_u32 s41, s41, 0x100
	s_addc_u32 s42, s42, 0
	s_cmp_gt_u32 s43, 13
	s_cbranch_scc0 .LBB0_723
	s_and_b64 vcc, exec, s[16:17]
	s_cbranch_vccz .LBB0_726
	s_barrier

; #define PG8_STAGE(bufoff, gbase, voff) do { _Pragma("unroll") for (int _i = 0; _i < 2; ++_i) \
;         __builtin_amdgcn_global_load_lds((const unsigned*)((const char*)(gbase) + (voff)[_i]), (PG8_LAS unsigned*)(lds + (bufoff) + ldsw + _i * 8192), 16, 0, 0); } while (0)
; #define PG8_LDA(dst, b, h) do { _Pragma("unroll") for (int m = 0; m < 4; ++m) _Pragma("unroll") for (int k = 0; k < 2; ++k) dst[m][k] = *(const PG8_LAS bf16x8*)(lds + PG8_SA(b, h) + aoff + m * 2048 + k * 1024); } while (0)
; #define PG8_LDB(dst, b, h) do { _Pragma("unroll") for (int n = 0; n < 2; ++n) _Pragma("unroll") for (int k = 0; k < 2; ++k) dst[n][k] = *(const PG8_LAS bf16x8*)(lds + PG8_SB(b, h) + boff + n * 2048 + k * 1024); } while (0)
; #define PG8_MMA(ai, bj, At, Bt) do { __builtin_amdgcn_s_setprio(1); _Pragma("unroll") for (int m = 0; m < 4; ++m) _Pragma("unroll") for (int n = 0; n < 2; ++n) _Pragma("unroll") for (int k = 0; k < 2; ++k) \
;         acc[ai][bj][m][n] = __builtin_amdgcn_mfma_f32_16x16x32_bf16(Bt[n][k], At[m][k], acc[ai][bj][m][n], 0, 0, 0); __builtin_amdgcn_s_setprio(0); } while (0)
; #define PG8_WAIT_V(n) asm volatile("s_waitcnt vmcnt(" #n ")" ::: "memory")
; #define PG8_WAIT_L(n) asm volatile("s_waitcnt lgkmcnt(" #n ")" ::: "memory")
; #define PG8_BAR __builtin_amdgcn_s_barrier()
; #define PG8_SCHED __builtin_amdgcn_sched_barrier(0)
; template <class Epi, class Sched, bool ALIGN_EPI = false, bool SP2 = false>
; __device__ __forceinline__ void gemm_phase(PG8_LAS unsigned char* lds, const Gemm g, const Sched& S, const Epi& E) {
;     ...
;     f32x4 acc[2][2][4][2];
; #pragma unroll
;     for (int a = 0; a < 2; ++a)
; #pragma unroll
;         for (int b = 0; b < 2; ++b)
; #pragma unroll
;             for (int m = 0; m < 4; ++m)
; #pragma unroll
;                 for (int n = 0; n < 2; ++n) acc[a][b][m][n] = (f32x4){0.f, 0.f, 0.f, 0.f};
;     ...
;             PG8_LDB(B0, 0, 0); PG8_LDB(B1, 0, 1); PG8_SCHED; PG8_LDA(At, 0, 0); PG8_STAGE(PG8_SA(1, 1), a1 + hstep, voffA);
;             PG8_WAIT_V(8); PG8_WAIT_L(0); PG8_BAR; PG8_MMA(0, 0, At, B0); PG8_MMA(0, 1, At, B1); PG8_BAR; PG8_SCHED;
;             if constexpr (Epi::PREFETCH) { if (t == tpf) E.prefetch(cur, wid, lane); }
;             PG8_LDA(At, 0, 1); PG8_STAGE(PG8_SB(0, 0), b2, voffB); PG8_STAGE(PG8_SB(0, 1), b2 + hstep, voffB); PG8_STAGE(PG8_SA(0, 0), a2, voffA);
.LBB0_837:
	s_ashr_i32 s29, s28, 31
	s_lshl_b64 s[30:31], s[28:29], 19
	s_add_u32 s30, s46, s30
	s_addc_u32 s31, s47, s31
	s_and_b64 s[34:35], s[2:3], exec
	s_cselect_b32 s1, s31, s5
	s_cselect_b32 s29, s30, s4
	s_ashr_i32 s27, s26, 31
	s_lshl_b64 s[34:35], s[26:27], 19
	s_add_u32 s34, s48, s34
	s_addc_u32 s35, s49, s35
	s_and_b64 s[36:37], s[2:3], exec
	s_cselect_b32 s27, s35, s7
	s_cselect_b32 s38, s34, s6
	s_add_u32 s4, s4, 0x40080
	s_addc_u32 s5, s5, 0
	s_add_u32 s39, s6, 0x100
	s_addc_u32 s40, s7, 0
	s_mov_b32 s41, -2
	s_waitcnt lgkmcnt(0)
	ds_read_b128 v[50:53], v214
	ds_read_b128 v[54:57], v214 offset:1024
	ds_read_b128 v[66:69], v214 offset:2048
	ds_read_b128 v[70:73], v214 offset:3072
	ds_read_b128 v[146:149], v215
	ds_read_b128 v[150:153], v215 offset:1024
	ds_read_b128 v[172:175], v215 offset:2048
	ds_read_b128 v[176:179], v215 offset:3072
	s_add_u32 s6, s4, 0xfffc0080
	s_addc_u32 s7, s5, -1
	s_cmp_eq_u32 s41, 12
	s_cselect_b32 s37, s1, s7
	s_cselect_b32 s36, s29, s6
	s_cselect_b32 s7, s27, s40
	s_cselect_b32 s6, s38, s39
	v_lshl_add_u64 v[218:219], s[4:5], 0, v[164:165]
	s_add_i32 m0, s51, 0xc000
	ds_read_b128 v[180:183], v216
	ds_read_b128 v[184:187], v216 offset:1024
	ds_read_b128 v[188:191], v216 offset:2048
	ds_read_b128 v[192:195], v216 offset:3072
	ds_read_b128 v[196:199], v216 offset:4096
	ds_read_b128 v[200:203], v216 offset:5120
	ds_read_b128 v[204:207], v216 offset:6144
	ds_read_b128 v[208:211], v216 offset:7168
	global_load_lds_dwordx4 v[218:219], off
	v_lshl_add_u64 v[218:219], s[4:5], 0, v[166:167]
	s_add_i32 m0, s51, 0xe000
	s_nop 0
	global_load_lds_dwordx4 v[218:219], off
	s_waitcnt vmcnt(8) lgkmcnt(0)
	s_setprio 1
	s_barrier
	v_mfma_f32_16x16x32_bf16 v[142:145], v[50:53], v[180:183], 0
	v_mfma_f32_16x16x32_bf16 v[138:141], v[66:69], v[180:183], 0
	v_mfma_f32_16x16x32_bf16 v[126:129], v[50:53], v[188:191], 0
	v_mfma_f32_16x16x32_bf16 v[122:125], v[66:69], v[188:191], 0
	v_mfma_f32_16x16x32_bf16 v[110:113], v[50:53], v[196:199], 0
	v_mfma_f32_16x16x32_bf16 v[106:109], v[66:69], v[196:199], 0
	v_mfma_f32_16x16x32_bf16 v[94:97], v[50:53], v[204:207], 0
	v_mfma_f32_16x16x32_bf16 v[90:93], v[66:69], v[204:207], 0
	v_mfma_f32_16x16x32_bf16 v[142:145], v[54:57], v[184:187], v[142:145]
	v_mfma_f32_16x16x32_bf16 v[138:141], v[70:73], v[184:187], v[138:141]
	v_mfma_f32_16x16x32_bf16 v[126:129], v[54:57], v[192:195], v[126:129]
	v_mfma_f32_16x16x32_bf16 v[122:125], v[70:73], v[192:195], v[122:125]
	v_mfma_f32_16x16x32_bf16 v[110:113], v[54:57], v[200:203], v[110:113]
	v_mfma_f32_16x16x32_bf16 v[106:109], v[70:73], v[200:203], v[106:109]
	v_mfma_f32_16x16x32_bf16 v[94:97], v[54:57], v[208:211], v[94:97]
	v_mfma_f32_16x16x32_bf16 v[90:93], v[70:73], v[208:211], v[90:93]
	v_mfma_f32_16x16x32_bf16 v[134:137], v[146:149], v[180:183], 0
	v_mfma_f32_16x16x32_bf16 v[130:133], v[172:175], v[180:183], 0
	v_mfma_f32_16x16x32_bf16 v[118:121], v[146:149], v[188:191], 0
	v_mfma_f32_16x16x32_bf16 v[114:117], v[172:175], v[188:191], 0
	v_mfma_f32_16x16x32_bf16 v[102:105], v[146:149], v[196:199], 0
	v_mfma_f32_16x16x32_bf16 v[98:101], v[172:175], v[196:199], 0
	v_mfma_f32_16x16x32_bf16 v[86:89], v[146:149], v[204:207], 0
	v_mfma_f32_16x16x32_bf16 v[82:85], v[172:175], v[204:207], 0
	v_mfma_f32_16x16x32_bf16 v[134:137], v[150:153], v[184:187], v[134:137]
	v_mfma_f32_16x16x32_bf16 v[130:133], v[176:179], v[184:187], v[130:133]
	v_mfma_f32_16x16x32_bf16 v[118:121], v[150:153], v[192:195], v[118:121]
	v_mfma_f32_16x16x32_bf16 v[114:117], v[176:179], v[192:195], v[114:117]
	v_mfma_f32_16x16x32_bf16 v[102:105], v[150:153], v[200:203], v[102:105]
	v_mfma_f32_16x16x32_bf16 v[98:101], v[176:179], v[200:203], v[98:101]
	v_mfma_f32_16x16x32_bf16 v[86:89], v[150:153], v[208:211], v[86:89]
	v_mfma_f32_16x16x32_bf16 v[82:85], v[176:179], v[208:211], v[82:85]
	s_setprio 0
	s_barrier
	s_add_i32 s42, s68, s50
	v_lshl_add_u64 v[218:219], s[6:7], 0, v[156:157]
	s_mov_b32 m0, s42
	ds_read_b128 v[180:183], v216 offset:16384
	ds_read_b128 v[184:187], v216 offset:17408
	ds_read_b128 v[188:191], v216 offset:18432
	ds_read_b128 v[192:195], v216 offset:19456
	ds_read_b128 v[196:199], v216 offset:20480
	ds_read_b128 v[200:203], v216 offset:21504
	ds_read_b128 v[204:207], v216 offset:22528
	ds_read_b128 v[208:211], v216 offset:23552
	global_load_lds_dwordx4 v[218:219], off
	s_add_i32 m0, s42, 0x2000
	s_add_u32 s42, s6, 0x40000
	v_lshl_add_u64 v[222:223], s[6:7], 0, v[160:161]
	s_addc_u32 s43, s7, 0
	s_add_i32 s44, s69, s50
	global_load_lds_dwordx4 v[222:223], off
	v_lshl_add_u64 v[224:225], s[42:43], 0, v[156:157]
	s_mov_b32 m0, s44
	v_lshl_add_u64 v[226:227], s[36:37], 0, v[158:159]
	global_load_lds_dwordx4 v[224:225], off
	v_lshl_add_u64 v[224:225], s[42:43], 0, v[160:161]
	s_add_i32 m0, s44, 0x2000
	s_nop 0
	global_load_lds_dwordx4 v[224:225], off
	v_lshl_add_u64 v[224:225], s[36:37], 0, v[154:155]
	s_mov_b32 m0, s51
	s_nop 0
	global_load_lds_dwordx4 v[224:225], off
	s_mov_b32 m0, s52
	s_nop 0
	global_load_lds_dwordx4 v[226:227], off
	s_waitcnt vmcnt(8) lgkmcnt(0)
	s_setprio 1
	s_barrier
; #define PG8_STAGE(bufoff, gbase, voff) do { _Pragma("unroll") for (int _i = 0; _i < 2; ++_i) \
;         __builtin_amdgcn_global_load_lds((const unsigned*)((const char*)(gbase) + (voff)[_i]), (PG8_LAS unsigned*)(lds + (bufoff) + ldsw + _i * 8192), 16, 0, 0); } while (0)
; #define PG8_LDA(dst, b, h) do { _Pragma("unroll") for (int m = 0; m < 4; ++m) _Pragma("unroll") for (int k = 0; k < 2; ++k) dst[m][k] = *(const PG8_LAS bf16x8*)(lds + PG8_SA(b, h) + aoff + m * 2048 + k * 1024); } while (0)
; #define PG8_LDB(dst, b, h) do { _Pragma("unroll") for (int n = 0; n < 2; ++n) _Pragma("unroll") for (int k = 0; k < 2; ++k) dst[n][k] = *(const PG8_LAS bf16x8*)(lds + PG8_SB(b, h) + boff + n * 2048 + k * 1024); } while (0)
; #define PG8_MMA(ai, bj, At, Bt) do { __builtin_amdgcn_s_setprio(1); _Pragma("unroll") for (int m = 0; m < 4; ++m) _Pragma("unroll") for (int n = 0; n < 2; ++n) _Pragma("unroll") for (int k = 0; k < 2; ++k) \
;         acc[ai][bj][m][n] = __builtin_amdgcn_mfma_f32_16x16x32_bf16(Bt[n][k], At[m][k], acc[ai][bj][m][n], 0, 0, 0); __builtin_amdgcn_s_setprio(0); } while (0)
; #define PG8_WAIT_V(n) asm volatile("s_waitcnt vmcnt(" #n ")" ::: "memory")
; #define PG8_WAIT_L(n) asm volatile("s_waitcnt lgkmcnt(" #n ")" ::: "memory")
; #define PG8_BAR __builtin_amdgcn_s_barrier()
; #define PG8_SCHED __builtin_amdgcn_sched_barrier(0)
;     __device__ __forceinline__ void prefetch(const Unit& u, int wid, int lane) const { epi_prefetch(scr, ssq, bias + (size_t)(u.pm >> 5) * NGU + u.pn * BM, u, wid, lane); }
;     __device__ __forceinline__ void prefetch(const Unit& u, int wid, int lane) const { epi_prefetch(scr, ssq, bias + (size_t)(u.pm >> 5) * DIN + u.pn * BM, u, wid, lane); }
; template <class Epi, class Sched, bool ALIGN_EPI = false, bool SP2 = false>
; __device__ __forceinline__ void gemm_phase(PG8_LAS unsigned char* lds, const Gemm g, const Sched& S, const Epi& E) {
;     ...
;             PG8_LDB(B0, 0, 0); PG8_LDB(B1, 0, 1); PG8_SCHED; PG8_LDA(At, 0, 0); PG8_STAGE(PG8_SA(1, 1), a1 + hstep, voffA);
;             PG8_WAIT_V(8); PG8_WAIT_L(0); PG8_BAR; PG8_MMA(0, 0, At, B0); PG8_MMA(0, 1, At, B1); PG8_BAR; PG8_SCHED;
;             if constexpr (Epi::PREFETCH) { if (t == tpf) E.prefetch(cur, wid, lane); }
;     ...
;             PG8_WAIT_V(8); PG8_WAIT_L(0); PG8_BAR; PG8_MMA(1, 0, At, B0); PG8_MMA(1, 1, At, B1); PG8_BAR; PG8_SCHED;
	v_mfma_f32_16x16x32_bf16 v[78:81], v[50:53], v[180:183], 0
	v_mfma_f32_16x16x32_bf16 v[74:77], v[66:69], v[180:183], 0
	v_mfma_f32_16x16x32_bf16 v[46:49], v[50:53], v[188:191], 0
	v_mfma_f32_16x16x32_bf16 v[42:45], v[66:69], v[188:191], 0
	v_mfma_f32_16x16x32_bf16 v[30:33], v[50:53], v[196:199], 0
	v_mfma_f32_16x16x32_bf16 v[26:29], v[66:69], v[196:199], 0
	v_mfma_f32_16x16x32_bf16 v[14:17], v[50:53], v[204:207], 0
	v_mfma_f32_16x16x32_bf16 v[10:13], v[66:69], v[204:207], 0
	v_mfma_f32_16x16x32_bf16 v[78:81], v[54:57], v[184:187], v[78:81]
	v_mfma_f32_16x16x32_bf16 v[74:77], v[70:73], v[184:187], v[74:77]
	v_mfma_f32_16x16x32_bf16 v[46:49], v[54:57], v[192:195], v[46:49]
	v_mfma_f32_16x16x32_bf16 v[42:45], v[70:73], v[192:195], v[42:45]
	v_mfma_f32_16x16x32_bf16 v[30:33], v[54:57], v[200:203], v[30:33]
	v_mfma_f32_16x16x32_bf16 v[26:29], v[70:73], v[200:203], v[26:29]
	v_mfma_f32_16x16x32_bf16 v[14:17], v[54:57], v[208:211], v[14:17]
	v_mfma_f32_16x16x32_bf16 v[10:13], v[70:73], v[208:211], v[10:13]
	v_mfma_f32_16x16x32_bf16 v[38:41], v[146:149], v[188:191], 0
	v_mfma_f32_16x16x32_bf16 v[34:37], v[172:175], v[188:191], 0
	v_mfma_f32_16x16x32_bf16 v[22:25], v[146:149], v[196:199], 0
	v_mfma_f32_16x16x32_bf16 v[18:21], v[172:175], v[196:199], 0
	v_mfma_f32_16x16x32_bf16 v[6:9], v[146:149], v[204:207], 0
	v_mfma_f32_16x16x32_bf16 v[2:5], v[172:175], v[204:207], 0
	v_mfma_f32_16x16x32_bf16 v[50:53], v[146:149], v[180:183], 0
	v_mfma_f32_16x16x32_bf16 v[54:57], v[172:175], v[180:183], 0
	v_mfma_f32_16x16x32_bf16 v[38:41], v[150:153], v[192:195], v[38:41]
	v_mfma_f32_16x16x32_bf16 v[34:37], v[176:179], v[192:195], v[34:37]
	v_mfma_f32_16x16x32_bf16 v[22:25], v[150:153], v[200:203], v[22:25]
	v_mfma_f32_16x16x32_bf16 v[18:21], v[176:179], v[200:203], v[18:21]
	v_mfma_f32_16x16x32_bf16 v[6:9], v[150:153], v[208:211], v[6:9]
	v_mfma_f32_16x16x32_bf16 v[2:5], v[176:179], v[208:211], v[2:5]
	v_mfma_f32_16x16x32_bf16 v[50:53], v[150:153], v[184:187], v[50:53]
	v_mfma_f32_16x16x32_bf16 v[54:57], v[176:179], v[184:187], v[54:57]
	s_setprio 0
	s_barrier
	s_branch .Lpz4_mid
.LBB0_838:
	ds_read_b128 v[50:53], v214
	ds_read_b128 v[54:57], v214 offset:1024
	ds_read_b128 v[66:69], v214 offset:2048
	ds_read_b128 v[70:73], v214 offset:3072
	ds_read_b128 v[146:149], v215
	ds_read_b128 v[150:153], v215 offset:1024
	ds_read_b128 v[172:175], v215 offset:2048
	ds_read_b128 v[176:179], v215 offset:3072
	s_add_u32 s6, s4, 0xfffc0080
	s_addc_u32 s7, s5, -1
	s_cmp_eq_u32 s41, 12
	s_cselect_b32 s37, s1, s7
	s_cselect_b32 s36, s29, s6
	s_cselect_b32 s7, s27, s40
	s_cselect_b32 s6, s38, s39
	v_lshl_add_u64 v[218:219], s[4:5], 0, v[164:165]
	s_add_i32 m0, s51, 0xc000
	ds_read_b128 v[180:183], v216
	ds_read_b128 v[184:187], v216 offset:1024
	ds_read_b128 v[188:191], v216 offset:2048
	ds_read_b128 v[192:195], v216 offset:3072
	ds_read_b128 v[196:199], v216 offset:4096
	ds_read_b128 v[200:203], v216 offset:5120
	ds_read_b128 v[204:207], v216 offset:6144
	ds_read_b128 v[208:211], v216 offset:7168
	global_load_lds_dwordx4 v[218:219], off
	v_lshl_add_u64 v[218:219], s[4:5], 0, v[166:167]
	s_add_i32 m0, s51, 0xe000
	s_nop 0
	global_load_lds_dwordx4 v[218:219], off
	s_waitcnt vmcnt(8) lgkmcnt(0)
	s_setprio 1
	s_barrier
	v_mfma_f32_16x16x32_bf16 v[142:145], v[50:53], v[180:183], v[142:145]
	v_mfma_f32_16x16x32_bf16 v[138:141], v[66:69], v[180:183], v[138:141]
	v_mfma_f32_16x16x32_bf16 v[126:129], v[50:53], v[188:191], v[126:129]
	v_mfma_f32_16x16x32_bf16 v[122:125], v[66:69], v[188:191], v[122:125]
	v_mfma_f32_16x16x32_bf16 v[110:113], v[50:53], v[196:199], v[110:113]
	v_mfma_f32_16x16x32_bf16 v[106:109], v[66:69], v[196:199], v[106:109]
	v_mfma_f32_16x16x32_bf16 v[94:97], v[50:53], v[204:207], v[94:97]
	v_mfma_f32_16x16x32_bf16 v[90:93], v[66:69], v[204:207], v[90:93]
	v_mfma_f32_16x16x32_bf16 v[142:145], v[54:57], v[184:187], v[142:145]
	v_mfma_f32_16x16x32_bf16 v[138:141], v[70:73], v[184:187], v[138:141]
	v_mfma_f32_16x16x32_bf16 v[126:129], v[54:57], v[192:195], v[126:129]
	v_mfma_f32_16x16x32_bf16 v[122:125], v[70:73], v[192:195], v[122:125]
	v_mfma_f32_16x16x32_bf16 v[110:113], v[54:57], v[200:203], v[110:113]
	v_mfma_f32_16x16x32_bf16 v[106:109], v[70:73], v[200:203], v[106:109]
	v_mfma_f32_16x16x32_bf16 v[94:97], v[54:57], v[208:211], v[94:97]
	v_mfma_f32_16x16x32_bf16 v[90:93], v[70:73], v[208:211], v[90:93]
	v_mfma_f32_16x16x32_bf16 v[134:137], v[146:149], v[180:183], v[134:137]
	v_mfma_f32_16x16x32_bf16 v[130:133], v[172:175], v[180:183], v[130:133]
	v_mfma_f32_16x16x32_bf16 v[118:121], v[146:149], v[188:191], v[118:121]
	v_mfma_f32_16x16x32_bf16 v[114:117], v[172:175], v[188:191], v[114:117]
	v_mfma_f32_16x16x32_bf16 v[102:105], v[146:149], v[196:199], v[102:105]
	v_mfma_f32_16x16x32_bf16 v[98:101], v[172:175], v[196:199], v[98:101]
	v_mfma_f32_16x16x32_bf16 v[86:89], v[146:149], v[204:207], v[86:89]
	v_mfma_f32_16x16x32_bf16 v[82:85], v[172:175], v[204:207], v[82:85]
	v_mfma_f32_16x16x32_bf16 v[134:137], v[150:153], v[184:187], v[134:137]
	v_mfma_f32_16x16x32_bf16 v[130:133], v[176:179], v[184:187], v[130:133]
	v_mfma_f32_16x16x32_bf16 v[118:121], v[150:153], v[192:195], v[118:121]
	v_mfma_f32_16x16x32_bf16 v[114:117], v[176:179], v[192:195], v[114:117]
	v_mfma_f32_16x16x32_bf16 v[102:105], v[150:153], v[200:203], v[102:105]
	v_mfma_f32_16x16x32_bf16 v[98:101], v[176:179], v[200:203], v[98:101]
	v_mfma_f32_16x16x32_bf16 v[86:89], v[150:153], v[208:211], v[86:89]
	v_mfma_f32_16x16x32_bf16 v[82:85], v[176:179], v[208:211], v[82:85]
	s_setprio 0
	s_barrier
; #define PG8_STAGE(bufoff, gbase, voff) do { _Pragma("unroll") for (int _i = 0; _i < 2; ++_i) \
;         __builtin_amdgcn_global_load_lds((const unsigned*)((const char*)(gbase) + (voff)[_i]), (PG8_LAS unsigned*)(lds + (bufoff) + ldsw + _i * 8192), 16, 0, 0); } while (0)
; #define PG8_LDA(dst, b, h) do { _Pragma("unroll") for (int m = 0; m < 4; ++m) _Pragma("unroll") for (int k = 0; k < 2; ++k) dst[m][k] = *(const PG8_LAS bf16x8*)(lds + PG8_SA(b, h) + aoff + m * 2048 + k * 1024); } while (0)
; #define PG8_LDB(dst, b, h) do { _Pragma("unroll") for (int n = 0; n < 2; ++n) _Pragma("unroll") for (int k = 0; k < 2; ++k) dst[n][k] = *(const PG8_LAS bf16x8*)(lds + PG8_SB(b, h) + boff + n * 2048 + k * 1024); } while (0)
; #define PG8_MMA(ai, bj, At, Bt) do { __builtin_amdgcn_s_setprio(1); _Pragma("unroll") for (int m = 0; m < 4; ++m) _Pragma("unroll") for (int n = 0; n < 2; ++n) _Pragma("unroll") for (int k = 0; k < 2; ++k) \
;         acc[ai][bj][m][n] = __builtin_amdgcn_mfma_f32_16x16x32_bf16(Bt[n][k], At[m][k], acc[ai][bj][m][n], 0, 0, 0); __builtin_amdgcn_s_setprio(0); } while (0)
; #define PG8_WAIT_V(n) asm volatile("s_waitcnt vmcnt(" #n ")" ::: "memory")
; #define PG8_WAIT_L(n) asm volatile("s_waitcnt lgkmcnt(" #n ")" ::: "memory")
; #define PG8_BAR __builtin_amdgcn_s_barrier()
; #define PG8_SCHED __builtin_amdgcn_sched_barrier(0)
; template <class Epi, class Sched, bool ALIGN_EPI = false, bool SP2 = false>
; __device__ __forceinline__ void gemm_phase(PG8_LAS unsigned char* lds, const Gemm g, const Sched& S, const Epi& E) {
;     ...
;             PG8_LDA(At, 0, 1); PG8_STAGE(PG8_SB(0, 0), b2, voffB); PG8_STAGE(PG8_SB(0, 1), b2 + hstep, voffB); PG8_STAGE(PG8_SA(0, 0), a2, voffA);
;             PG8_WAIT_V(8); PG8_WAIT_L(0); PG8_BAR; PG8_MMA(1, 0, At, B0); PG8_MMA(1, 1, At, B1); PG8_BAR; PG8_SCHED;
;             PG8_LDB(B0, 1, 0); PG8_LDB(B1, 1, 1); PG8_SCHED; PG8_LDA(At, 1, 0); PG8_STAGE(PG8_SA(0, 1), a2 + hstep, voffA);
;             PG8_WAIT_V(8); PG8_WAIT_L(0); PG8_BAR; PG8_MMA(0, 0, At, B0); PG8_MMA(0, 1, At, B1); PG8_BAR; PG8_SCHED;
	s_add_i32 s42, s68, s50
	v_lshl_add_u64 v[218:219], s[6:7], 0, v[156:157]
	s_mov_b32 m0, s42
	ds_read_b128 v[180:183], v216 offset:16384
	ds_read_b128 v[184:187], v216 offset:17408
	ds_read_b128 v[188:191], v216 offset:18432
	ds_read_b128 v[192:195], v216 offset:19456
	ds_read_b128 v[196:199], v216 offset:20480
	ds_read_b128 v[200:203], v216 offset:21504
	ds_read_b128 v[204:207], v216 offset:22528
	ds_read_b128 v[208:211], v216 offset:23552
	global_load_lds_dwordx4 v[218:219], off
	s_add_i32 m0, s42, 0x2000
	s_add_u32 s42, s6, 0x40000
	v_lshl_add_u64 v[222:223], s[6:7], 0, v[160:161]
	s_addc_u32 s43, s7, 0
	s_add_i32 s44, s69, s50
	global_load_lds_dwordx4 v[222:223], off
	v_lshl_add_u64 v[224:225], s[42:43], 0, v[156:157]
	s_mov_b32 m0, s44
	v_lshl_add_u64 v[226:227], s[36:37], 0, v[158:159]
	global_load_lds_dwordx4 v[224:225], off
	v_lshl_add_u64 v[224:225], s[42:43], 0, v[160:161]
	s_add_i32 m0, s44, 0x2000
	s_nop 0
	global_load_lds_dwordx4 v[224:225], off
	v_lshl_add_u64 v[224:225], s[36:37], 0, v[154:155]
	s_mov_b32 m0, s51
	s_nop 0
	global_load_lds_dwordx4 v[224:225], off
	s_mov_b32 m0, s52
	s_nop 0
	global_load_lds_dwordx4 v[226:227], off
	s_waitcnt vmcnt(8) lgkmcnt(0)
	s_setprio 1
	s_barrier
	v_mfma_f32_16x16x32_bf16 v[78:81], v[50:53], v[180:183], v[78:81]
	v_mfma_f32_16x16x32_bf16 v[74:77], v[66:69], v[180:183], v[74:77]
	v_mfma_f32_16x16x32_bf16 v[46:49], v[50:53], v[188:191], v[46:49]
	v_mfma_f32_16x16x32_bf16 v[42:45], v[66:69], v[188:191], v[42:45]
	v_mfma_f32_16x16x32_bf16 v[30:33], v[50:53], v[196:199], v[30:33]
	v_mfma_f32_16x16x32_bf16 v[26:29], v[66:69], v[196:199], v[26:29]
	v_mfma_f32_16x16x32_bf16 v[14:17], v[50:53], v[204:207], v[14:17]
	v_mfma_f32_16x16x32_bf16 v[10:13], v[66:69], v[204:207], v[10:13]
	v_mfma_f32_16x16x32_bf16 v[78:81], v[54:57], v[184:187], v[78:81]
	v_mfma_f32_16x16x32_bf16 v[74:77], v[70:73], v[184:187], v[74:77]
	v_mfma_f32_16x16x32_bf16 v[46:49], v[54:57], v[192:195], v[46:49]
	v_mfma_f32_16x16x32_bf16 v[42:45], v[70:73], v[192:195], v[42:45]
	v_mfma_f32_16x16x32_bf16 v[30:33], v[54:57], v[200:203], v[30:33]
	v_mfma_f32_16x16x32_bf16 v[26:29], v[70:73], v[200:203], v[26:29]
	v_mfma_f32_16x16x32_bf16 v[14:17], v[54:57], v[208:211], v[14:17]
	v_mfma_f32_16x16x32_bf16 v[10:13], v[70:73], v[208:211], v[10:13]
	v_mfma_f32_16x16x32_bf16 v[38:41], v[146:149], v[188:191], v[38:41]
	v_mfma_f32_16x16x32_bf16 v[34:37], v[172:175], v[188:191], v[34:37]
	v_mfma_f32_16x16x32_bf16 v[22:25], v[146:149], v[196:199], v[22:25]
	v_mfma_f32_16x16x32_bf16 v[18:21], v[172:175], v[196:199], v[18:21]
	v_mfma_f32_16x16x32_bf16 v[6:9], v[146:149], v[204:207], v[6:9]
	v_mfma_f32_16x16x32_bf16 v[2:5], v[172:175], v[204:207], v[2:5]
	v_mfma_f32_16x16x32_bf16 v[50:53], v[146:149], v[180:183], v[62:65]
	v_mfma_f32_16x16x32_bf16 v[54:57], v[172:175], v[180:183], v[58:61]
	v_mfma_f32_16x16x32_bf16 v[38:41], v[150:153], v[192:195], v[38:41]
	v_mfma_f32_16x16x32_bf16 v[34:37], v[176:179], v[192:195], v[34:37]
	v_mfma_f32_16x16x32_bf16 v[22:25], v[150:153], v[200:203], v[22:25]
	v_mfma_f32_16x16x32_bf16 v[18:21], v[176:179], v[200:203], v[18:21]
	v_mfma_f32_16x16x32_bf16 v[6:9], v[150:153], v[208:211], v[6:9]
	v_mfma_f32_16x16x32_bf16 v[2:5], v[176:179], v[208:211], v[2:5]
	v_mfma_f32_16x16x32_bf16 v[50:53], v[150:153], v[184:187], v[50:53]
	v_mfma_f32_16x16x32_bf16 v[54:57], v[176:179], v[184:187], v[54:57]
	s_setprio 0
	s_barrier
.Lpz4_mid:
	s_add_i32 s42, 0, 0x18000
	s_add_i32 s43, 0, 0x1c000
	v_add_u32_e32 v70, s42, v213
	v_add_u32_e32 v162, s43, v213
	ds_read_b128 v[58:61], v70
	ds_read_b128 v[62:65], v70 offset:1024
	ds_read_b128 v[66:69], v70 offset:2048
	ds_read_b128 v[70:73], v70 offset:3072
	ds_read_b128 v[146:149], v162
	ds_read_b128 v[150:153], v162 offset:1024
	ds_read_b128 v[172:175], v162 offset:2048
	ds_read_b128 v[176:179], v162 offset:3072
	s_add_u32 s36, s36, 0x40000
	s_addc_u32 s37, s37, 0
	s_mov_b32 m0, s53
	v_lshl_add_u64 v[228:229], s[36:37], 0, v[154:155]
	ds_read_b128 v[180:183], v216 offset:32768
	ds_read_b128 v[184:187], v216 offset:33792
	ds_read_b128 v[188:191], v216 offset:34816
	ds_read_b128 v[192:195], v216 offset:35840
	ds_read_b128 v[196:199], v216 offset:36864
	ds_read_b128 v[200:203], v216 offset:37888
	ds_read_b128 v[204:207], v216 offset:38912
	ds_read_b128 v[208:211], v216 offset:39936
	global_load_lds_dwordx4 v[228:229], off
	v_lshl_add_u64 v[228:229], s[36:37], 0, v[158:159]
	s_mov_b32 m0, s54
	s_nop 0
	global_load_lds_dwordx4 v[228:229], off
	s_waitcnt vmcnt(8) lgkmcnt(0)
	s_setprio 1
	s_barrier
; #define PG8_STAGE(bufoff, gbase, voff) do { _Pragma("unroll") for (int _i = 0; _i < 2; ++_i) \
;         __builtin_amdgcn_global_load_lds((const unsigned*)((const char*)(gbase) + (voff)[_i]), (PG8_LAS unsigned*)(lds + (bufoff) + ldsw + _i * 8192), 16, 0, 0); } while (0)
; #define PG8_LDA(dst, b, h) do { _Pragma("unroll") for (int m = 0; m < 4; ++m) _Pragma("unroll") for (int k = 0; k < 2; ++k) dst[m][k] = *(const PG8_LAS bf16x8*)(lds + PG8_SA(b, h) + aoff + m * 2048 + k * 1024); } while (0)
; #define PG8_MMA(ai, bj, At, Bt) do { __builtin_amdgcn_s_setprio(1); _Pragma("unroll") for (int m = 0; m < 4; ++m) _Pragma("unroll") for (int n = 0; n < 2; ++n) _Pragma("unroll") for (int k = 0; k < 2; ++k) \
;         acc[ai][bj][m][n] = __builtin_amdgcn_mfma_f32_16x16x32_bf16(Bt[n][k], At[m][k], acc[ai][bj][m][n], 0, 0, 0); __builtin_amdgcn_s_setprio(0); } while (0)
; #define PG8_WAIT_V(n) asm volatile("s_waitcnt vmcnt(" #n ")" ::: "memory")
; #define PG8_WAIT_L(n) asm volatile("s_waitcnt lgkmcnt(" #n ")" ::: "memory")
; #define PG8_BAR __builtin_amdgcn_s_barrier()
; #define PG8_SCHED __builtin_amdgcn_sched_barrier(0)
; template <class Epi, class Sched, bool ALIGN_EPI = false, bool SP2 = false>
; __device__ __forceinline__ void gemm_phase(PG8_LAS unsigned char* lds, const Gemm g, const Sched& S, const Epi& E) {
;     ...
;         for (int t = 0; t < nt; t += 2) {
;             const bool last = (t == nt - 2);
;     ...
;             PG8_WAIT_V(8); PG8_WAIT_L(0); PG8_BAR; PG8_MMA(0, 0, At, B0); PG8_MMA(0, 1, At, B1); PG8_BAR; PG8_SCHED;
;             PG8_LDA(At, 1, 1); PG8_STAGE(PG8_SB(1, 0), b3, voffB); PG8_STAGE(PG8_SB(1, 1), b3 + hstep, voffB); PG8_STAGE(PG8_SA(1, 0), a3, voffA);
;             PG8_WAIT_V(8); PG8_WAIT_L(0); PG8_BAR; PG8_MMA(1, 0, At, B0); PG8_MMA(1, 1, At, B1); PG8_BAR; PG8_SCHED;
	v_mfma_f32_16x16x32_bf16 v[142:145], v[58:61], v[180:183], v[142:145]
	v_mfma_f32_16x16x32_bf16 v[138:141], v[66:69], v[180:183], v[138:141]
	v_mfma_f32_16x16x32_bf16 v[126:129], v[58:61], v[188:191], v[126:129]
	v_mfma_f32_16x16x32_bf16 v[122:125], v[66:69], v[188:191], v[122:125]
	v_mfma_f32_16x16x32_bf16 v[110:113], v[58:61], v[196:199], v[110:113]
	v_mfma_f32_16x16x32_bf16 v[106:109], v[66:69], v[196:199], v[106:109]
	v_mfma_f32_16x16x32_bf16 v[94:97], v[58:61], v[204:207], v[94:97]
	v_mfma_f32_16x16x32_bf16 v[90:93], v[66:69], v[204:207], v[90:93]
	v_mfma_f32_16x16x32_bf16 v[142:145], v[62:65], v[184:187], v[142:145]
	v_mfma_f32_16x16x32_bf16 v[138:141], v[70:73], v[184:187], v[138:141]
	v_mfma_f32_16x16x32_bf16 v[126:129], v[62:65], v[192:195], v[126:129]
	v_mfma_f32_16x16x32_bf16 v[122:125], v[70:73], v[192:195], v[122:125]
	v_mfma_f32_16x16x32_bf16 v[110:113], v[62:65], v[200:203], v[110:113]
	v_mfma_f32_16x16x32_bf16 v[106:109], v[70:73], v[200:203], v[106:109]
	v_mfma_f32_16x16x32_bf16 v[94:97], v[62:65], v[208:211], v[94:97]
	v_mfma_f32_16x16x32_bf16 v[90:93], v[70:73], v[208:211], v[90:93]
	v_mfma_f32_16x16x32_bf16 v[134:137], v[146:149], v[180:183], v[134:137]
	v_mfma_f32_16x16x32_bf16 v[130:133], v[172:175], v[180:183], v[130:133]
	v_mfma_f32_16x16x32_bf16 v[118:121], v[146:149], v[188:191], v[118:121]
	v_mfma_f32_16x16x32_bf16 v[114:117], v[172:175], v[188:191], v[114:117]
	v_mfma_f32_16x16x32_bf16 v[102:105], v[146:149], v[196:199], v[102:105]
	v_mfma_f32_16x16x32_bf16 v[98:101], v[172:175], v[196:199], v[98:101]
	v_mfma_f32_16x16x32_bf16 v[86:89], v[146:149], v[204:207], v[86:89]
	v_mfma_f32_16x16x32_bf16 v[82:85], v[172:175], v[204:207], v[82:85]
	v_mfma_f32_16x16x32_bf16 v[134:137], v[150:153], v[184:187], v[134:137]
	v_mfma_f32_16x16x32_bf16 v[130:133], v[176:179], v[184:187], v[130:133]
	v_mfma_f32_16x16x32_bf16 v[118:121], v[150:153], v[192:195], v[118:121]
	v_mfma_f32_16x16x32_bf16 v[114:117], v[176:179], v[192:195], v[114:117]
	v_mfma_f32_16x16x32_bf16 v[102:105], v[150:153], v[200:203], v[102:105]
	v_mfma_f32_16x16x32_bf16 v[98:101], v[176:179], v[200:203], v[98:101]
	v_mfma_f32_16x16x32_bf16 v[86:89], v[150:153], v[208:211], v[86:89]
	v_mfma_f32_16x16x32_bf16 v[82:85], v[176:179], v[208:211], v[82:85]
	s_setprio 0
	s_barrier
	s_add_i32 s36, s42, s50
	v_lshl_add_u64 v[218:219], v[218:219], 0, s[20:21]
	s_mov_b32 m0, s36
	ds_read_b128 v[180:183], v216 offset:49152
	ds_read_b128 v[184:187], v216 offset:50176
	ds_read_b128 v[188:191], v216 offset:51200
	ds_read_b128 v[192:195], v216 offset:52224
	ds_read_b128 v[196:199], v216 offset:53248
	ds_read_b128 v[200:203], v216 offset:54272
	ds_read_b128 v[204:207], v216 offset:55296
	ds_read_b128 v[208:211], v216 offset:56320
	global_load_lds_dwordx4 v[218:219], off
	s_add_i32 m0, s36, 0x2000
	s_add_u32 s6, s6, 0x40080
	v_lshl_add_u64 v[218:219], v[222:223], 0, s[20:21]
	s_addc_u32 s7, s7, 0
	s_add_i32 s36, s43, s50
	global_load_lds_dwordx4 v[218:219], off
	v_lshl_add_u64 v[218:219], s[6:7], 0, v[156:157]
	s_mov_b32 m0, s36
	s_nop 0
	global_load_lds_dwordx4 v[218:219], off
	v_lshl_add_u64 v[218:219], s[6:7], 0, v[160:161]
	s_add_i32 m0, s36, 0x2000
	s_nop 0
	global_load_lds_dwordx4 v[218:219], off
	v_lshl_add_u64 v[218:219], v[224:225], 0, s[20:21]
	s_mov_b32 m0, s63
	s_nop 0
	global_load_lds_dwordx4 v[218:219], off
	v_lshl_add_u64 v[218:219], v[226:227], 0, s[20:21]
	s_mov_b32 m0, s64
	s_nop 0
	global_load_lds_dwordx4 v[218:219], off
	s_waitcnt vmcnt(8) lgkmcnt(0)
	s_setprio 1
	s_barrier
	v_mfma_f32_16x16x32_bf16 v[78:81], v[58:61], v[180:183], v[78:81]
	v_mfma_f32_16x16x32_bf16 v[74:77], v[66:69], v[180:183], v[74:77]
	v_mfma_f32_16x16x32_bf16 v[46:49], v[58:61], v[188:191], v[46:49]
	v_mfma_f32_16x16x32_bf16 v[42:45], v[66:69], v[188:191], v[42:45]
	v_mfma_f32_16x16x32_bf16 v[30:33], v[58:61], v[196:199], v[30:33]
	v_mfma_f32_16x16x32_bf16 v[26:29], v[66:69], v[196:199], v[26:29]
	v_mfma_f32_16x16x32_bf16 v[14:17], v[58:61], v[204:207], v[14:17]
	v_mfma_f32_16x16x32_bf16 v[10:13], v[66:69], v[204:207], v[10:13]
	v_mfma_f32_16x16x32_bf16 v[78:81], v[62:65], v[184:187], v[78:81]
	v_mfma_f32_16x16x32_bf16 v[74:77], v[70:73], v[184:187], v[74:77]
	v_mfma_f32_16x16x32_bf16 v[46:49], v[62:65], v[192:195], v[46:49]
	v_mfma_f32_16x16x32_bf16 v[42:45], v[70:73], v[192:195], v[42:45]
	v_mfma_f32_16x16x32_bf16 v[30:33], v[62:65], v[200:203], v[30:33]
	v_mfma_f32_16x16x32_bf16 v[26:29], v[70:73], v[200:203], v[26:29]
	v_mfma_f32_16x16x32_bf16 v[14:17], v[62:65], v[208:211], v[14:17]
	v_mfma_f32_16x16x32_bf16 v[10:13], v[70:73], v[208:211], v[10:13]
	v_mfma_f32_16x16x32_bf16 v[50:53], v[146:149], v[180:183], v[50:53]
	v_mfma_f32_16x16x32_bf16 v[62:65], v[150:153], v[184:187], v[50:53]
	v_mfma_f32_16x16x32_bf16 v[50:53], v[172:175], v[180:183], v[54:57]
	v_mfma_f32_16x16x32_bf16 v[38:41], v[146:149], v[188:191], v[38:41]
	v_mfma_f32_16x16x32_bf16 v[34:37], v[172:175], v[188:191], v[34:37]
	v_mfma_f32_16x16x32_bf16 v[22:25], v[146:149], v[196:199], v[22:25]
	v_mfma_f32_16x16x32_bf16 v[18:21], v[172:175], v[196:199], v[18:21]
	v_mfma_f32_16x16x32_bf16 v[6:9], v[146:149], v[204:207], v[6:9]
	v_mfma_f32_16x16x32_bf16 v[2:5], v[172:175], v[204:207], v[2:5]
	v_mfma_f32_16x16x32_bf16 v[58:61], v[176:179], v[184:187], v[50:53]
	v_mfma_f32_16x16x32_bf16 v[38:41], v[150:153], v[192:195], v[38:41]
	v_mfma_f32_16x16x32_bf16 v[34:37], v[176:179], v[192:195], v[34:37]
	v_mfma_f32_16x16x32_bf16 v[22:25], v[150:153], v[200:203], v[22:25]
	v_mfma_f32_16x16x32_bf16 v[18:21], v[176:179], v[200:203], v[18:21]
	v_mfma_f32_16x16x32_bf16 v[6:9], v[150:153], v[208:211], v[6:9]
	v_mfma_f32_16x16x32_bf16 v[2:5], v[176:179], v[208:211], v[2:5]
	s_setprio 0
	s_barrier
	s_add_i32 s41, s41, 2
	s_add_u32 s4, s4, 0x100
	s_addc_u32 s5, s5, 0
	s_add_u32 s39, s39, 0x100
	s_addc_u32 s40, s40, 0
	s_cmp_gt_u32 s41, 13
	s_cbranch_scc0 .LBB0_838
	s_and_b64 vcc, exec, s[22:23]
	s_cbranch_vccz .LBB0_841
	s_barrier

;     __host__ __device__ bool next(int i, Unit& u) const { if (!b.next(i >> 1, u)) return false; u.sel = i & 1; return true; }
; #define PG8_STAGE(bufoff, gbase, voff) do { _Pragma("unroll") for (int _i = 0; _i < 2; ++_i) \
;         __builtin_amdgcn_global_load_lds((const unsigned*)((const char*)(gbase) + (voff)[_i]), (PG8_LAS unsigned*)(lds + (bufoff) + ldsw + _i * 8192), 16, 0, 0); } while (0)
; #define PG8_LDA(dst, b, h) do { _Pragma("unroll") for (int m = 0; m < 4; ++m) _Pragma("unroll") for (int k = 0; k < 2; ++k) dst[m][k] = *(const PG8_LAS bf16x8*)(lds + PG8_SA(b, h) + aoff + m * 2048 + k * 1024); } while (0)
; #define PG8_LDB(dst, b, h) do { _Pragma("unroll") for (int n = 0; n < 2; ++n) _Pragma("unroll") for (int k = 0; k < 2; ++k) dst[n][k] = *(const PG8_LAS bf16x8*)(lds + PG8_SB(b, h) + boff + n * 2048 + k * 1024); } while (0)
; #define PG8_WAIT_V(n) asm volatile("s_waitcnt vmcnt(" #n ")" ::: "memory")
; #define PG8_WAIT_L(n) asm volatile("s_waitcnt lgkmcnt(" #n ")" ::: "memory")
; #define PG8_BAR __builtin_amdgcn_s_barrier()
; #define PG8_SCHED __builtin_amdgcn_sched_barrier(0)
;     __host__ __device__ bool next(int i, Unit& u) const {
;         const long L = (long)i * G + c; if (L >= nwg) return false;
;         int wgid = (int)L; { const int q = nwg / NXCD, r = nwg % NXCD, xcd = wgid % NXCD, off = wgid / NXCD; wgid = (xcd < r ? xcd * (q + 1) : r * (q + 1) + (xcd - r) * q) + off; }
;         const int nig = WGM * nN, gid = wgid / nig, fm = gid * WGM, gsz = (nM - fm) < WGM ? (nM - fm) : WGM;
;         u.pm = fm + ((wgid % nig) % gsz); u.pn = (wgid % nig) / gsz; u.sel = 0; return true;
; template <class Epi, class Sched, bool ALIGN_EPI = false, bool SP2 = false>
; __device__ __forceinline__ void gemm_phase(PG8_LAS unsigned char* lds, const Gemm g, const Sched& S, const Epi& E) {
;     ...
;         const bool has_next = S.next(ui + 1, nxt);
;         const char* nA = has_next ? PG8_ABASE(nxt) : cA; const char* nB = has_next ? PG8_BBASE(nxt) : cB;
;     ...
;             PG8_LDB(B0, 0, 0); PG8_LDB(B1, 0, 1); PG8_SCHED; PG8_LDA(At, 0, 0); PG8_STAGE(PG8_SA(1, 1), a1 + hstep, voffA);
;             PG8_WAIT_V(8); PG8_WAIT_L(0); PG8_BAR; PG8_MMA(0, 0, At, B0); PG8_MMA(0, 1, At, B1); PG8_BAR; PG8_SCHED;
;             if constexpr (Epi::PREFETCH) { if (t == tpf) E.prefetch(cur, wid, lane); }
.LBB0_982:
	s_ashr_i32 s29, s28, 31
	s_lshl_b32 s34, s34, 8
	s_lshl_b64 s[36:37], s[28:29], 14
	s_ashr_i32 s29, s28, 5
	s_ashr_i32 s35, s34, 31
	s_add_u32 s36, s10, s36
	s_mul_hi_i32 s38, s29, 0x5800
	s_mulk_i32 s29, 0x5800
	s_addc_u32 s37, s69, s37
	s_add_u32 s29, s62, s29
	s_addc_u32 s42, s63, s38
	s_lshl_b64 s[38:39], s[34:35], 2
	s_add_u32 s38, s29, s38
	s_addc_u32 s39, s42, s39
	s_add_u32 s29, s40, 0x100
	v_lshl_add_u64 v[188:189], s[30:31], 0, v[180:181]
	v_lshl_add_u64 v[190:191], s[30:31], 0, v[182:183]
	s_addc_u32 s35, s41, 0
	s_mov_b32 s83, 0
	s_mov_b64 s[40:41], 0
	ds_read_b128 v[154:157], v195
	ds_read_b128 v[158:161], v195 offset:1024
	ds_read_b128 v[162:165], v195 offset:2048
	ds_read_b128 v[166:169], v195 offset:3072
	ds_read_b128 v[138:141], v196
	ds_read_b128 v[142:145], v196 offset:1024
	ds_read_b128 v[146:149], v196 offset:2048
	ds_read_b128 v[150:153], v196 offset:3072
	v_lshl_add_u64 v[98:99], v[188:189], 0, s[40:41]
	s_add_i32 m0, s54, 0xc000
	ds_read_b128 v[200:203], v197
	ds_read_b128 v[204:207], v197 offset:1024
	ds_read_b128 v[208:211], v197 offset:2048
	ds_read_b128 v[212:215], v197 offset:3072
	ds_read_b128 v[216:219], v197 offset:4096
	ds_read_b128 v[220:223], v197 offset:5120
	ds_read_b128 v[224:227], v197 offset:6144
	ds_read_b128 v[228:231], v197 offset:7168
	global_load_lds_dwordx4 v[98:99], off
	v_lshl_add_u64 v[98:99], v[190:191], 0, s[40:41]
	s_add_i32 m0, s54, 0xe000
	s_nop 0
	global_load_lds_dwordx4 v[98:99], off
	s_add_i32 s11, s11, 1
	s_mul_i32 s2, s11, s68
	s_mul_hi_u32 s3, s11, s33
	s_add_i32 s3, s3, s2
	s_mul_i32 s2, s11, s33
	s_add_u32 s24, s2, s87
	s_addc_u32 s25, s3, s52
	v_cmp_lt_i64_e64 s[2:3], s[24:25], v[184:185]
	s_ashr_i32 s20, s24, 31
	s_lshr_b32 s20, s20, 29
	s_add_i32 s20, s24, s20
	s_ashr_i32 s21, s20, 3
	s_and_b32 s20, s20, -8
	s_sub_i32 s20, s24, s20
	s_cmp_lt_i32 s20, 0
	s_cselect_b32 s22, s53, 0x160
	s_mul_i32 s20, s20, s22
	s_add_i32 s20, s20, s21
	s_mul_hi_i32 s21, s20, 0x2e8ba2e9
	s_lshr_b32 s22, s21, 31
	s_ashr_i32 s21, s21, 3
	s_add_i32 s21, s21, s22
	s_lshl_b32 s22, s21, 1
	s_mul_i32 s21, s21, 44
	s_sub_i32 s21, s20, s21
	s_lshr_b32 s20, s21, 1
	s_and_b32 s21, s21, 1
	s_add_i32 s22, s22, s21
	s_ashr_i32 s23, s22, 31
	s_lshl_b64 s[24:25], s[22:23], 19
	s_add_u32 s24, s47, s24
	s_addc_u32 s25, s48, s25
	s_and_b64 s[26:27], s[2:3], exec
	s_cselect_b32 s23, s25, s48
	s_cselect_b32 s81, s24, s47
	s_ashr_i32 s21, s20, 31
	s_lshl_b64 s[26:27], s[20:21], 19
	s_add_u32 s26, s49, s26
	s_addc_u32 s27, s50, s27
	s_and_b64 s[98:99], s[2:3], exec
	s_cselect_b32 s21, s27, s50
	s_cselect_b32 s82, s26, s49
	s_waitcnt vmcnt(8) lgkmcnt(0)
	s_setprio 1
	s_barrier
	v_mfma_f32_16x16x32_bf16 v[98:101], v[154:157], v[200:203], 0
	v_mfma_f32_16x16x32_bf16 v[106:109], v[162:165], v[200:203], 0
	v_mfma_f32_16x16x32_bf16 v[118:121], v[154:157], v[208:211], 0
	v_mfma_f32_16x16x32_bf16 v[114:117], v[162:165], v[208:211], 0
	v_mfma_f32_16x16x32_bf16 v[94:97], v[154:157], v[216:219], 0
	v_mfma_f32_16x16x32_bf16 v[90:93], v[162:165], v[216:219], 0
	v_mfma_f32_16x16x32_bf16 v[78:81], v[154:157], v[224:227], 0
	v_mfma_f32_16x16x32_bf16 v[74:77], v[162:165], v[224:227], 0
	v_mfma_f32_16x16x32_bf16 v[98:101], v[158:161], v[204:207], v[98:101]
	v_mfma_f32_16x16x32_bf16 v[106:109], v[166:169], v[204:207], v[106:109]
	v_mfma_f32_16x16x32_bf16 v[118:121], v[158:161], v[212:215], v[118:121]
	v_mfma_f32_16x16x32_bf16 v[114:117], v[166:169], v[212:215], v[114:117]
	v_mfma_f32_16x16x32_bf16 v[94:97], v[158:161], v[220:223], v[94:97]
	v_mfma_f32_16x16x32_bf16 v[90:93], v[166:169], v[220:223], v[90:93]
	v_mfma_f32_16x16x32_bf16 v[78:81], v[158:161], v[228:231], v[78:81]
	v_mfma_f32_16x16x32_bf16 v[74:77], v[166:169], v[228:231], v[74:77]
	v_mfma_f32_16x16x32_bf16 v[126:129], v[138:141], v[200:203], 0
	v_mfma_f32_16x16x32_bf16 v[122:125], v[146:149], v[200:203], 0
	v_mfma_f32_16x16x32_bf16 v[110:113], v[138:141], v[208:211], 0
	v_mfma_f32_16x16x32_bf16 v[102:105], v[146:149], v[208:211], 0
	v_mfma_f32_16x16x32_bf16 v[86:89], v[138:141], v[216:219], 0
	v_mfma_f32_16x16x32_bf16 v[82:85], v[146:149], v[216:219], 0
	v_mfma_f32_16x16x32_bf16 v[70:73], v[138:141], v[224:227], 0
	v_mfma_f32_16x16x32_bf16 v[66:69], v[146:149], v[224:227], 0
	v_mfma_f32_16x16x32_bf16 v[126:129], v[142:145], v[204:207], v[126:129]
	v_mfma_f32_16x16x32_bf16 v[122:125], v[150:153], v[204:207], v[122:125]
	v_mfma_f32_16x16x32_bf16 v[110:113], v[142:145], v[212:215], v[110:113]
	v_mfma_f32_16x16x32_bf16 v[102:105], v[150:153], v[212:215], v[102:105]
	v_mfma_f32_16x16x32_bf16 v[86:89], v[142:145], v[220:223], v[86:89]
	v_mfma_f32_16x16x32_bf16 v[82:85], v[150:153], v[220:223], v[82:85]
	v_mfma_f32_16x16x32_bf16 v[70:73], v[142:145], v[228:231], v[70:73]
	v_mfma_f32_16x16x32_bf16 v[66:69], v[150:153], v[228:231], v[66:69]
	s_setprio 0
	s_barrier
	s_cmp_lg_u32 s46, s83
	s_cbranch_scc1 .Lpz5_a
	v_mov_b32_e32 v178, v194
	s_add_i32 m0, s79, 0x20000
	v_lshl_add_u64 v[130:131], s[36:37], 0, v[178:179]
	global_load_lds_dwordx4 v178, s[36:37]
	v_lshl_add_u64 v[130:131], v[130:131], 0, s[18:19]
	s_add_i32 m0, s79, 0x20400
	s_andn2_b64 vcc, exec, s[14:15]
	global_load_lds_dwordx4 v[130:131], off
	s_cbranch_vccnz .Lpz5_a
	v_lshl_add_u64 v[130:131], s[38:39], 0, v[178:179]
	s_add_i32 m0, 0, 0x24000
	s_nop 0
	global_load_lds_dwordx4 v[130:131], off
	s_branch .Lpz5_a
; #define PG8_STAGE(bufoff, gbase, voff) do { _Pragma("unroll") for (int _i = 0; _i < 2; ++_i) \
;         __builtin_amdgcn_global_load_lds((const unsigned*)((const char*)(gbase) + (voff)[_i]), (PG8_LAS unsigned*)(lds + (bufoff) + ldsw + _i * 8192), 16, 0, 0); } while (0)
; #define PG8_LDA(dst, b, h) do { _Pragma("unroll") for (int m = 0; m < 4; ++m) _Pragma("unroll") for (int k = 0; k < 2; ++k) dst[m][k] = *(const PG8_LAS bf16x8*)(lds + PG8_SA(b, h) + aoff + m * 2048 + k * 1024); } while (0)
; #define PG8_MMA(ai, bj, At, Bt) do { __builtin_amdgcn_s_setprio(1); _Pragma("unroll") for (int m = 0; m < 4; ++m) _Pragma("unroll") for (int n = 0; n < 2; ++n) _Pragma("unroll") for (int k = 0; k < 2; ++k) \
;         acc[ai][bj][m][n] = __builtin_amdgcn_mfma_f32_16x16x32_bf16(Bt[n][k], At[m][k], acc[ai][bj][m][n], 0, 0, 0); __builtin_amdgcn_s_setprio(0); } while (0)
; #define PG8_WAIT_V(n) asm volatile("s_waitcnt vmcnt(" #n ")" ::: "memory")
; #define PG8_WAIT_L(n) asm volatile("s_waitcnt lgkmcnt(" #n ")" ::: "memory")
; #define PG8_BAR __builtin_amdgcn_s_barrier()
; #define PG8_SCHED __builtin_amdgcn_sched_barrier(0)
; template <class Epi, class Sched, bool ALIGN_EPI = false, bool SP2 = false>
; __device__ __forceinline__ void gemm_phase(PG8_LAS unsigned char* lds, const Gemm g, const Sched& S, const Epi& E) {
;     ...
;             PG8_LDA(At, 0, 1); PG8_STAGE(PG8_SB(0, 0), b2, voffB); PG8_STAGE(PG8_SB(0, 1), b2 + hstep, voffB); PG8_STAGE(PG8_SA(0, 0), a2, voffA);
;             PG8_WAIT_V(8); PG8_WAIT_L(0); PG8_BAR; PG8_MMA(1, 0, At, B0); PG8_MMA(1, 1, At, B1); PG8_BAR; PG8_SCHED;
.Lpz5_a:
	s_add_u32 s42, s30, s40
	s_addc_u32 s43, s31, s41
	s_add_u32 s42, s42, 0x100
	s_addc_u32 s43, s43, 0
	s_add_u32 s84, s29, s40
	s_addc_u32 s85, s35, s41
	s_cmpk_eq_i32 s40, 0x700
	s_cselect_b32 s45, s23, s43
	s_cselect_b32 s44, s81, s42
	s_cselect_b32 s43, s21, s85
	s_cselect_b32 s42, s82, s84
	s_mov_b32 m0, s55
	v_lshl_add_u64 v[232:233], s[42:43], 0, v[174:175]
	s_add_u32 s84, s42, 0x40000
	ds_read_b128 v[130:133], v197 offset:16384
	ds_read_b128 v[134:137], v197 offset:17408
	ds_read_b128 v[200:203], v197 offset:18432
	ds_read_b128 v[204:207], v197 offset:19456
	ds_read_b128 v[208:211], v197 offset:20480
	ds_read_b128 v[212:215], v197 offset:21504
	ds_read_b128 v[216:219], v197 offset:22528
	ds_read_b128 v[220:223], v197 offset:23552
	global_load_lds_dwordx4 v[232:233], off
	v_lshl_add_u64 v[234:235], s[42:43], 0, v[170:171]
	s_mov_b32 m0, s56
	s_addc_u32 s85, s43, 0
	global_load_lds_dwordx4 v[234:235], off
	v_lshl_add_u64 v[224:225], s[84:85], 0, v[174:175]
	s_mov_b32 m0, s57
	v_lshl_add_u64 v[236:237], s[44:45], 0, v[176:177]
	global_load_lds_dwordx4 v[224:225], off
	v_lshl_add_u64 v[224:225], s[84:85], 0, v[170:171]
	s_mov_b32 m0, s58
	v_lshl_add_u64 v[238:239], s[44:45], 0, v[172:173]
	global_load_lds_dwordx4 v[224:225], off
	s_mov_b32 m0, s54
	s_nop 0
	global_load_lds_dwordx4 v[236:237], off
	s_mov_b32 m0, s59
	s_nop 0
	global_load_lds_dwordx4 v[238:239], off
	s_waitcnt vmcnt(8) lgkmcnt(0)
	s_setprio 1
	s_barrier
	v_mfma_f32_16x16x32_bf16 v[62:65], v[154:157], v[130:133], 0
	v_mfma_f32_16x16x32_bf16 v[58:61], v[162:165], v[130:133], 0
	v_mfma_f32_16x16x32_bf16 v[46:49], v[154:157], v[200:203], 0
	v_mfma_f32_16x16x32_bf16 v[42:45], v[162:165], v[200:203], 0
	v_mfma_f32_16x16x32_bf16 v[30:33], v[154:157], v[208:211], 0
	v_mfma_f32_16x16x32_bf16 v[26:29], v[162:165], v[208:211], 0
	v_mfma_f32_16x16x32_bf16 v[14:17], v[154:157], v[216:219], 0
	v_mfma_f32_16x16x32_bf16 v[10:13], v[162:165], v[216:219], 0
	v_mfma_f32_16x16x32_bf16 v[62:65], v[158:161], v[134:137], v[62:65]
	v_mfma_f32_16x16x32_bf16 v[58:61], v[166:169], v[134:137], v[58:61]
	v_mfma_f32_16x16x32_bf16 v[46:49], v[158:161], v[204:207], v[46:49]
	v_mfma_f32_16x16x32_bf16 v[42:45], v[166:169], v[204:207], v[42:45]
	v_mfma_f32_16x16x32_bf16 v[30:33], v[158:161], v[212:215], v[30:33]
	v_mfma_f32_16x16x32_bf16 v[26:29], v[166:169], v[212:215], v[26:29]
	v_mfma_f32_16x16x32_bf16 v[14:17], v[158:161], v[220:223], v[14:17]
	v_mfma_f32_16x16x32_bf16 v[10:13], v[166:169], v[220:223], v[10:13]
	v_mfma_f32_16x16x32_bf16 v[54:57], v[138:141], v[130:133], 0
	v_mfma_f32_16x16x32_bf16 v[50:53], v[146:149], v[130:133], 0
	v_mfma_f32_16x16x32_bf16 v[38:41], v[138:141], v[200:203], 0
	v_mfma_f32_16x16x32_bf16 v[34:37], v[146:149], v[200:203], 0
	v_mfma_f32_16x16x32_bf16 v[22:25], v[138:141], v[208:211], 0
	v_mfma_f32_16x16x32_bf16 v[18:21], v[146:149], v[208:211], 0
	v_mfma_f32_16x16x32_bf16 v[6:9], v[138:141], v[216:219], 0
	v_mfma_f32_16x16x32_bf16 v[2:5], v[146:149], v[216:219], 0
	v_mfma_f32_16x16x32_bf16 v[54:57], v[142:145], v[134:137], v[54:57]
	v_mfma_f32_16x16x32_bf16 v[50:53], v[150:153], v[134:137], v[50:53]
	v_mfma_f32_16x16x32_bf16 v[38:41], v[142:145], v[204:207], v[38:41]
	v_mfma_f32_16x16x32_bf16 v[34:37], v[150:153], v[204:207], v[34:37]
	v_mfma_f32_16x16x32_bf16 v[22:25], v[142:145], v[212:215], v[22:25]
	v_mfma_f32_16x16x32_bf16 v[18:21], v[150:153], v[212:215], v[18:21]
	v_mfma_f32_16x16x32_bf16 v[6:9], v[142:145], v[220:223], v[6:9]
	v_mfma_f32_16x16x32_bf16 v[2:5], v[150:153], v[220:223], v[2:5]
	s_setprio 0
	s_barrier
	s_branch .Lpz5_mid
.LBB0_985:
	s_add_u32 s42, s30, s40
	s_addc_u32 s43, s31, s41
	s_add_u32 s42, s42, 0x100
	s_addc_u32 s43, s43, 0
	s_add_u32 s84, s29, s40
	s_addc_u32 s85, s35, s41
	s_cmpk_eq_i32 s40, 0x700
	s_cselect_b32 s45, s23, s43
	s_cselect_b32 s44, s81, s42
	s_cselect_b32 s43, s21, s85
	s_cselect_b32 s42, s82, s84
	s_mov_b32 m0, s55
	v_lshl_add_u64 v[232:233], s[42:43], 0, v[174:175]
	s_add_u32 s84, s42, 0x40000
	ds_read_b128 v[130:133], v197 offset:16384
	ds_read_b128 v[134:137], v197 offset:17408
	ds_read_b128 v[200:203], v197 offset:18432
	ds_read_b128 v[204:207], v197 offset:19456
	ds_read_b128 v[208:211], v197 offset:20480
	ds_read_b128 v[212:215], v197 offset:21504
	ds_read_b128 v[216:219], v197 offset:22528
	ds_read_b128 v[220:223], v197 offset:23552
	global_load_lds_dwordx4 v[232:233], off
	v_lshl_add_u64 v[234:235], s[42:43], 0, v[170:171]
	s_mov_b32 m0, s56
	s_addc_u32 s85, s43, 0
	global_load_lds_dwordx4 v[234:235], off
	v_lshl_add_u64 v[224:225], s[84:85], 0, v[174:175]
	s_mov_b32 m0, s57
	v_lshl_add_u64 v[236:237], s[44:45], 0, v[176:177]
	global_load_lds_dwordx4 v[224:225], off
	v_lshl_add_u64 v[224:225], s[84:85], 0, v[170:171]
	s_mov_b32 m0, s58
	v_lshl_add_u64 v[238:239], s[44:45], 0, v[172:173]
	global_load_lds_dwordx4 v[224:225], off
	s_mov_b32 m0, s54
	s_nop 0
	global_load_lds_dwordx4 v[236:237], off
	s_mov_b32 m0, s59
	s_nop 0
	global_load_lds_dwordx4 v[238:239], off
	s_waitcnt vmcnt(8) lgkmcnt(0)
	s_setprio 1
	s_barrier
; #define PG8_STAGE(bufoff, gbase, voff) do { _Pragma("unroll") for (int _i = 0; _i < 2; ++_i) \
;         __builtin_amdgcn_global_load_lds((const unsigned*)((const char*)(gbase) + (voff)[_i]), (PG8_LAS unsigned*)(lds + (bufoff) + ldsw + _i * 8192), 16, 0, 0); } while (0)
; #define PG8_LDA(dst, b, h) do { _Pragma("unroll") for (int m = 0; m < 4; ++m) _Pragma("unroll") for (int k = 0; k < 2; ++k) dst[m][k] = *(const PG8_LAS bf16x8*)(lds + PG8_SA(b, h) + aoff + m * 2048 + k * 1024); } while (0)
; #define PG8_LDB(dst, b, h) do { _Pragma("unroll") for (int n = 0; n < 2; ++n) _Pragma("unroll") for (int k = 0; k < 2; ++k) dst[n][k] = *(const PG8_LAS bf16x8*)(lds + PG8_SB(b, h) + boff + n * 2048 + k * 1024); } while (0)
; #define PG8_MMA(ai, bj, At, Bt) do { __builtin_amdgcn_s_setprio(1); _Pragma("unroll") for (int m = 0; m < 4; ++m) _Pragma("unroll") for (int n = 0; n < 2; ++n) _Pragma("unroll") for (int k = 0; k < 2; ++k) \
;         acc[ai][bj][m][n] = __builtin_amdgcn_mfma_f32_16x16x32_bf16(Bt[n][k], At[m][k], acc[ai][bj][m][n], 0, 0, 0); __builtin_amdgcn_s_setprio(0); } while (0)
; #define PG8_WAIT_V(n) asm volatile("s_waitcnt vmcnt(" #n ")" ::: "memory")
; #define PG8_WAIT_L(n) asm volatile("s_waitcnt lgkmcnt(" #n ")" ::: "memory")
; #define PG8_BAR __builtin_amdgcn_s_barrier()
; #define PG8_SCHED __builtin_amdgcn_sched_barrier(0)
; template <class Epi, class Sched, bool ALIGN_EPI = false, bool SP2 = false>
; __device__ __forceinline__ void gemm_phase(PG8_LAS unsigned char* lds, const Gemm g, const Sched& S, const Epi& E) {
;     ...
;             PG8_WAIT_V(8); PG8_WAIT_L(0); PG8_BAR; PG8_MMA(1, 0, At, B0); PG8_MMA(1, 1, At, B1); PG8_BAR; PG8_SCHED;
;             PG8_LDB(B0, 1, 0); PG8_LDB(B1, 1, 1); PG8_SCHED; PG8_LDA(At, 1, 0); PG8_STAGE(PG8_SA(0, 1), a2 + hstep, voffA);
;             PG8_WAIT_V(8); PG8_WAIT_L(0); PG8_BAR; PG8_MMA(0, 0, At, B0); PG8_MMA(0, 1, At, B1); PG8_BAR; PG8_SCHED;
	v_mfma_f32_16x16x32_bf16 v[62:65], v[154:157], v[130:133], v[62:65]
	v_mfma_f32_16x16x32_bf16 v[58:61], v[162:165], v[130:133], v[58:61]
	v_mfma_f32_16x16x32_bf16 v[46:49], v[154:157], v[200:203], v[46:49]
	v_mfma_f32_16x16x32_bf16 v[42:45], v[162:165], v[200:203], v[42:45]
	v_mfma_f32_16x16x32_bf16 v[30:33], v[154:157], v[208:211], v[30:33]
	v_mfma_f32_16x16x32_bf16 v[26:29], v[162:165], v[208:211], v[26:29]
	v_mfma_f32_16x16x32_bf16 v[14:17], v[154:157], v[216:219], v[14:17]
	v_mfma_f32_16x16x32_bf16 v[10:13], v[162:165], v[216:219], v[10:13]
	v_mfma_f32_16x16x32_bf16 v[62:65], v[158:161], v[134:137], v[62:65]
	v_mfma_f32_16x16x32_bf16 v[58:61], v[166:169], v[134:137], v[58:61]
	v_mfma_f32_16x16x32_bf16 v[46:49], v[158:161], v[204:207], v[46:49]
	v_mfma_f32_16x16x32_bf16 v[42:45], v[166:169], v[204:207], v[42:45]
	v_mfma_f32_16x16x32_bf16 v[30:33], v[158:161], v[212:215], v[30:33]
	v_mfma_f32_16x16x32_bf16 v[26:29], v[166:169], v[212:215], v[26:29]
	v_mfma_f32_16x16x32_bf16 v[14:17], v[158:161], v[220:223], v[14:17]
	v_mfma_f32_16x16x32_bf16 v[10:13], v[166:169], v[220:223], v[10:13]
	v_mfma_f32_16x16x32_bf16 v[54:57], v[138:141], v[130:133], v[54:57]
	v_mfma_f32_16x16x32_bf16 v[50:53], v[146:149], v[130:133], v[50:53]
	v_mfma_f32_16x16x32_bf16 v[38:41], v[138:141], v[200:203], v[38:41]
	v_mfma_f32_16x16x32_bf16 v[34:37], v[146:149], v[200:203], v[34:37]
	v_mfma_f32_16x16x32_bf16 v[22:25], v[138:141], v[208:211], v[22:25]
	v_mfma_f32_16x16x32_bf16 v[18:21], v[146:149], v[208:211], v[18:21]
	v_mfma_f32_16x16x32_bf16 v[6:9], v[138:141], v[216:219], v[6:9]
	v_mfma_f32_16x16x32_bf16 v[2:5], v[146:149], v[216:219], v[2:5]
	v_mfma_f32_16x16x32_bf16 v[54:57], v[142:145], v[134:137], v[54:57]
	v_mfma_f32_16x16x32_bf16 v[50:53], v[150:153], v[134:137], v[50:53]
	v_mfma_f32_16x16x32_bf16 v[38:41], v[142:145], v[204:207], v[38:41]
	v_mfma_f32_16x16x32_bf16 v[34:37], v[150:153], v[204:207], v[34:37]
	v_mfma_f32_16x16x32_bf16 v[22:25], v[142:145], v[212:215], v[22:25]
	v_mfma_f32_16x16x32_bf16 v[18:21], v[150:153], v[212:215], v[18:21]
	v_mfma_f32_16x16x32_bf16 v[6:9], v[142:145], v[220:223], v[6:9]
	v_mfma_f32_16x16x32_bf16 v[2:5], v[150:153], v[220:223], v[2:5]
	s_setprio 0
	s_barrier
.Lpz5_mid:
	s_add_i32 s84, 0, 0x18000
	v_add_u32_e32 v130, s84, v193
	s_add_i32 s85, 0, 0x1c000
	ds_read_b128 v[138:141], v130
	ds_read_b128 v[142:145], v130 offset:1024
	ds_read_b128 v[146:149], v130 offset:2048
	ds_read_b128 v[150:153], v130 offset:3072
	v_add_u32_e32 v130, s85, v193
	ds_read_b128 v[154:157], v130
	ds_read_b128 v[158:161], v130 offset:1024
	ds_read_b128 v[162:165], v130 offset:2048
	ds_read_b128 v[166:169], v130 offset:3072
	s_add_u32 s44, s44, 0x40000
	s_addc_u32 s45, s45, 0
	s_mov_b32 m0, s60
	v_lshl_add_u64 v[130:131], s[44:45], 0, v[176:177]
	ds_read_b128 v[200:203], v197 offset:32768
	ds_read_b128 v[204:207], v197 offset:33792
	ds_read_b128 v[208:211], v197 offset:34816
	ds_read_b128 v[212:215], v197 offset:35840
	ds_read_b128 v[216:219], v197 offset:36864
	ds_read_b128 v[220:223], v197 offset:37888
	ds_read_b128 v[224:227], v197 offset:38912
	ds_read_b128 v[228:231], v197 offset:39936
	global_load_lds_dwordx4 v[130:131], off
	v_lshl_add_u64 v[130:131], s[44:45], 0, v[172:173]
	s_mov_b32 m0, s61
	s_nop 0
	global_load_lds_dwordx4 v[130:131], off
	s_waitcnt vmcnt(8) lgkmcnt(0)
	s_setprio 1
	s_barrier
	v_mfma_f32_16x16x32_bf16 v[98:101], v[138:141], v[200:203], v[98:101]
	v_mfma_f32_16x16x32_bf16 v[134:137], v[142:145], v[204:207], v[98:101]
	v_mfma_f32_16x16x32_bf16 v[98:101], v[146:149], v[200:203], v[106:109]
	v_mfma_f32_16x16x32_bf16 v[130:133], v[150:153], v[204:207], v[98:101]
	v_mfma_f32_16x16x32_bf16 v[98:101], v[138:141], v[208:211], v[118:121]
	v_mfma_f32_16x16x32_bf16 v[118:121], v[142:145], v[212:215], v[98:101]
	v_mfma_f32_16x16x32_bf16 v[98:101], v[146:149], v[208:211], v[114:117]
	v_mfma_f32_16x16x32_bf16 v[94:97], v[138:141], v[216:219], v[94:97]
	v_mfma_f32_16x16x32_bf16 v[90:93], v[146:149], v[216:219], v[90:93]
	v_mfma_f32_16x16x32_bf16 v[78:81], v[138:141], v[224:227], v[78:81]
	v_mfma_f32_16x16x32_bf16 v[74:77], v[146:149], v[224:227], v[74:77]
	v_mfma_f32_16x16x32_bf16 v[114:117], v[150:153], v[212:215], v[98:101]
	v_mfma_f32_16x16x32_bf16 v[94:97], v[142:145], v[220:223], v[94:97]
	v_mfma_f32_16x16x32_bf16 v[90:93], v[150:153], v[220:223], v[90:93]
	v_mfma_f32_16x16x32_bf16 v[78:81], v[142:145], v[228:231], v[78:81]
	v_mfma_f32_16x16x32_bf16 v[74:77], v[150:153], v[228:231], v[74:77]
	v_mfma_f32_16x16x32_bf16 v[98:101], v[154:157], v[200:203], v[126:129]
	v_mfma_f32_16x16x32_bf16 v[126:129], v[158:161], v[204:207], v[98:101]
	v_mfma_f32_16x16x32_bf16 v[98:101], v[162:165], v[200:203], v[122:125]
	v_mfma_f32_16x16x32_bf16 v[122:125], v[166:169], v[204:207], v[98:101]
	v_mfma_f32_16x16x32_bf16 v[98:101], v[154:157], v[208:211], v[110:113]
	v_mfma_f32_16x16x32_bf16 v[110:113], v[158:161], v[212:215], v[98:101]
	v_mfma_f32_16x16x32_bf16 v[98:101], v[162:165], v[208:211], v[102:105]
	v_mfma_f32_16x16x32_bf16 v[86:89], v[154:157], v[216:219], v[86:89]
	v_mfma_f32_16x16x32_bf16 v[82:85], v[162:165], v[216:219], v[82:85]
	v_mfma_f32_16x16x32_bf16 v[70:73], v[154:157], v[224:227], v[70:73]
	v_mfma_f32_16x16x32_bf16 v[66:69], v[162:165], v[224:227], v[66:69]
	v_mfma_f32_16x16x32_bf16 v[102:105], v[166:169], v[212:215], v[98:101]
	v_mfma_f32_16x16x32_bf16 v[86:89], v[158:161], v[220:223], v[86:89]
	v_mfma_f32_16x16x32_bf16 v[82:85], v[166:169], v[220:223], v[82:85]
	v_mfma_f32_16x16x32_bf16 v[70:73], v[158:161], v[228:231], v[70:73]
	v_mfma_f32_16x16x32_bf16 v[66:69], v[166:169], v[228:231], v[66:69]
	s_setprio 0
	s_barrier
; #define PG8_STAGE(bufoff, gbase, voff) do { _Pragma("unroll") for (int _i = 0; _i < 2; ++_i) \
;         __builtin_amdgcn_global_load_lds((const unsigned*)((const char*)(gbase) + (voff)[_i]), (PG8_LAS unsigned*)(lds + (bufoff) + ldsw + _i * 8192), 16, 0, 0); } while (0)
; #define PG8_LDA(dst, b, h) do { _Pragma("unroll") for (int m = 0; m < 4; ++m) _Pragma("unroll") for (int k = 0; k < 2; ++k) dst[m][k] = *(const PG8_LAS bf16x8*)(lds + PG8_SA(b, h) + aoff + m * 2048 + k * 1024); } while (0)
; #define PG8_MMA(ai, bj, At, Bt) do { __builtin_amdgcn_s_setprio(1); _Pragma("unroll") for (int m = 0; m < 4; ++m) _Pragma("unroll") for (int n = 0; n < 2; ++n) _Pragma("unroll") for (int k = 0; k < 2; ++k) \
;         acc[ai][bj][m][n] = __builtin_amdgcn_mfma_f32_16x16x32_bf16(Bt[n][k], At[m][k], acc[ai][bj][m][n], 0, 0, 0); __builtin_amdgcn_s_setprio(0); } while (0)
; #define PG8_WAIT_V(n) asm volatile("s_waitcnt vmcnt(" #n ")" ::: "memory")
; #define PG8_WAIT_L(n) asm volatile("s_waitcnt lgkmcnt(" #n ")" ::: "memory")
; #define PG8_BAR __builtin_amdgcn_s_barrier()
; #define PG8_SCHED __builtin_amdgcn_sched_barrier(0)
; template <class Epi, class Sched, bool ALIGN_EPI = false, bool SP2 = false>
; __device__ __forceinline__ void gemm_phase(PG8_LAS unsigned char* lds, const Gemm g, const Sched& S, const Epi& E) {
;     ...
;         for (int t = 0; t < nt; t += 2) {
;             const bool last = (t == nt - 2);
;     ...
;             PG8_LDA(At, 1, 1); PG8_STAGE(PG8_SB(1, 0), b3, voffB); PG8_STAGE(PG8_SB(1, 1), b3 + hstep, voffB); PG8_STAGE(PG8_SA(1, 0), a3, voffA);
;             PG8_WAIT_V(8); PG8_WAIT_L(0); PG8_BAR; PG8_MMA(1, 0, At, B0); PG8_MMA(1, 1, At, B1); PG8_BAR; PG8_SCHED;
	s_add_i32 s44, s84, s51
	v_lshl_add_u64 v[224:225], v[232:233], 0, s[8:9]
	s_mov_b32 m0, s44
	ds_read_b128 v[98:101], v197 offset:49152
	ds_read_b128 v[106:109], v197 offset:50176
	ds_read_b128 v[200:203], v197 offset:51200
	ds_read_b128 v[204:207], v197 offset:52224
	ds_read_b128 v[208:211], v197 offset:53248
	ds_read_b128 v[212:215], v197 offset:54272
	ds_read_b128 v[216:219], v197 offset:55296
	ds_read_b128 v[220:223], v197 offset:56320
	global_load_lds_dwordx4 v[224:225], off
	s_add_i32 m0, s44, 0x2000
	s_add_u32 s42, s42, 0x40080
	v_lshl_add_u64 v[224:225], v[234:235], 0, s[8:9]
	s_addc_u32 s43, s43, 0
	s_add_i32 s44, s85, s51
	global_load_lds_dwordx4 v[224:225], off
	v_lshl_add_u64 v[224:225], s[42:43], 0, v[174:175]
	s_mov_b32 m0, s44
	s_nop 0
	global_load_lds_dwordx4 v[224:225], off
	v_lshl_add_u64 v[224:225], s[42:43], 0, v[170:171]
	s_add_i32 m0, s44, 0x2000
	s_nop 0
	global_load_lds_dwordx4 v[224:225], off
	v_lshl_add_u64 v[224:225], v[236:237], 0, s[8:9]
	s_mov_b32 m0, s65
	s_nop 0
	global_load_lds_dwordx4 v[224:225], off
	v_lshl_add_u64 v[224:225], v[238:239], 0, s[8:9]
	s_mov_b32 m0, s66
	s_nop 0
	global_load_lds_dwordx4 v[224:225], off
	s_waitcnt vmcnt(8) lgkmcnt(0)
	s_setprio 1
	s_barrier
	v_mfma_f32_16x16x32_bf16 v[62:65], v[138:141], v[98:101], v[62:65]
	v_mfma_f32_16x16x32_bf16 v[58:61], v[146:149], v[98:101], v[58:61]
	v_mfma_f32_16x16x32_bf16 v[46:49], v[138:141], v[200:203], v[46:49]
	v_mfma_f32_16x16x32_bf16 v[42:45], v[146:149], v[200:203], v[42:45]
	v_mfma_f32_16x16x32_bf16 v[30:33], v[138:141], v[208:211], v[30:33]
	v_mfma_f32_16x16x32_bf16 v[26:29], v[146:149], v[208:211], v[26:29]
	v_mfma_f32_16x16x32_bf16 v[14:17], v[138:141], v[216:219], v[14:17]
	v_mfma_f32_16x16x32_bf16 v[10:13], v[146:149], v[216:219], v[10:13]
	v_mfma_f32_16x16x32_bf16 v[62:65], v[142:145], v[106:109], v[62:65]
	v_mfma_f32_16x16x32_bf16 v[58:61], v[150:153], v[106:109], v[58:61]
	v_mfma_f32_16x16x32_bf16 v[46:49], v[142:145], v[204:207], v[46:49]
	v_mfma_f32_16x16x32_bf16 v[42:45], v[150:153], v[204:207], v[42:45]
	v_mfma_f32_16x16x32_bf16 v[30:33], v[142:145], v[212:215], v[30:33]
	v_mfma_f32_16x16x32_bf16 v[26:29], v[150:153], v[212:215], v[26:29]
	v_mfma_f32_16x16x32_bf16 v[14:17], v[142:145], v[220:223], v[14:17]
	v_mfma_f32_16x16x32_bf16 v[10:13], v[150:153], v[220:223], v[10:13]
	v_mfma_f32_16x16x32_bf16 v[54:57], v[154:157], v[98:101], v[54:57]
	v_mfma_f32_16x16x32_bf16 v[50:53], v[162:165], v[98:101], v[50:53]
	v_mfma_f32_16x16x32_bf16 v[38:41], v[154:157], v[200:203], v[38:41]
	v_mfma_f32_16x16x32_bf16 v[34:37], v[162:165], v[200:203], v[34:37]
	v_mfma_f32_16x16x32_bf16 v[22:25], v[154:157], v[208:211], v[22:25]
	v_mfma_f32_16x16x32_bf16 v[18:21], v[162:165], v[208:211], v[18:21]
	v_mfma_f32_16x16x32_bf16 v[6:9], v[154:157], v[216:219], v[6:9]
	v_mfma_f32_16x16x32_bf16 v[2:5], v[162:165], v[216:219], v[2:5]
	v_mfma_f32_16x16x32_bf16 v[54:57], v[158:161], v[106:109], v[54:57]
	v_mfma_f32_16x16x32_bf16 v[50:53], v[166:169], v[106:109], v[50:53]
	v_mfma_f32_16x16x32_bf16 v[38:41], v[158:161], v[204:207], v[38:41]
	v_mfma_f32_16x16x32_bf16 v[34:37], v[166:169], v[204:207], v[34:37]
	v_mfma_f32_16x16x32_bf16 v[22:25], v[158:161], v[212:215], v[22:25]
	v_mfma_f32_16x16x32_bf16 v[18:21], v[166:169], v[212:215], v[18:21]
	v_mfma_f32_16x16x32_bf16 v[6:9], v[158:161], v[220:223], v[6:9]
	v_mfma_f32_16x16x32_bf16 v[2:5], v[166:169], v[220:223], v[2:5]
	s_setprio 0
	s_barrier
	s_add_i32 s42, s83, 2
	s_add_u32 s40, s40, 0x100
	s_addc_u32 s41, s41, 0
	s_cmp_gt_u32 s83, 13
	s_mov_b32 s83, s42
	s_cbranch_scc1 .LBB0_989
; #define PG8_STAGE(bufoff, gbase, voff) do { _Pragma("unroll") for (int _i = 0; _i < 2; ++_i) \
;         __builtin_amdgcn_global_load_lds((const unsigned*)((const char*)(gbase) + (voff)[_i]), (PG8_LAS unsigned*)(lds + (bufoff) + ldsw + _i * 8192), 16, 0, 0); } while (0)
; #define PG8_LDA(dst, b, h) do { _Pragma("unroll") for (int m = 0; m < 4; ++m) _Pragma("unroll") for (int k = 0; k < 2; ++k) dst[m][k] = *(const PG8_LAS bf16x8*)(lds + PG8_SA(b, h) + aoff + m * 2048 + k * 1024); } while (0)
; #define PG8_LDB(dst, b, h) do { _Pragma("unroll") for (int n = 0; n < 2; ++n) _Pragma("unroll") for (int k = 0; k < 2; ++k) dst[n][k] = *(const PG8_LAS bf16x8*)(lds + PG8_SB(b, h) + boff + n * 2048 + k * 1024); } while (0)
; #define PG8_MMA(ai, bj, At, Bt) do { __builtin_amdgcn_s_setprio(1); _Pragma("unroll") for (int m = 0; m < 4; ++m) _Pragma("unroll") for (int n = 0; n < 2; ++n) _Pragma("unroll") for (int k = 0; k < 2; ++k) \
;         acc[ai][bj][m][n] = __builtin_amdgcn_mfma_f32_16x16x32_bf16(Bt[n][k], At[m][k], acc[ai][bj][m][n], 0, 0, 0); __builtin_amdgcn_s_setprio(0); } while (0)
; #define PG8_WAIT_V(n) asm volatile("s_waitcnt vmcnt(" #n ")" ::: "memory")
; #define PG8_WAIT_L(n) asm volatile("s_waitcnt lgkmcnt(" #n ")" ::: "memory")
; #define PG8_BAR __builtin_amdgcn_s_barrier()
; #define PG8_SCHED __builtin_amdgcn_sched_barrier(0)
;     __device__ __forceinline__ void prefetch(const Unit& u, int wid, int lane) const { epi_prefetch(scr, ssq, bias + (size_t)(u.pm >> 5) * NGU + u.pn * BM, u, wid, lane); }
;     __device__ __forceinline__ void prefetch(const Unit& u, int wid, int lane) const { epi_prefetch(scr, ssq, bias + (size_t)(u.pm >> 5) * DIN + u.pn * BM, u, wid, lane); }
; template <class Epi, class Sched, bool ALIGN_EPI = false, bool SP2 = false>
; __device__ __forceinline__ void gemm_phase(PG8_LAS unsigned char* lds, const Gemm g, const Sched& S, const Epi& E) {
;     ...
;             PG8_LDB(B0, 0, 0); PG8_LDB(B1, 0, 1); PG8_SCHED; PG8_LDA(At, 0, 0); PG8_STAGE(PG8_SA(1, 1), a1 + hstep, voffA);
;             PG8_WAIT_V(8); PG8_WAIT_L(0); PG8_BAR; PG8_MMA(0, 0, At, B0); PG8_MMA(0, 1, At, B1); PG8_BAR; PG8_SCHED;
;             if constexpr (Epi::PREFETCH) { if (t == tpf) E.prefetch(cur, wid, lane); }
.LBB0_986:
	ds_read_b128 v[154:157], v195
	ds_read_b128 v[158:161], v195 offset:1024
	ds_read_b128 v[162:165], v195 offset:2048
	ds_read_b128 v[166:169], v195 offset:3072
	ds_read_b128 v[138:141], v196
	ds_read_b128 v[142:145], v196 offset:1024
	ds_read_b128 v[146:149], v196 offset:2048
	ds_read_b128 v[150:153], v196 offset:3072
	v_lshl_add_u64 v[98:99], v[188:189], 0, s[40:41]
	s_add_i32 m0, s54, 0xc000
	ds_read_b128 v[200:203], v197
	ds_read_b128 v[204:207], v197 offset:1024
	ds_read_b128 v[208:211], v197 offset:2048
	ds_read_b128 v[212:215], v197 offset:3072
	ds_read_b128 v[216:219], v197 offset:4096
	ds_read_b128 v[220:223], v197 offset:5120
	ds_read_b128 v[224:227], v197 offset:6144
	ds_read_b128 v[228:231], v197 offset:7168
	global_load_lds_dwordx4 v[98:99], off
	v_lshl_add_u64 v[98:99], v[190:191], 0, s[40:41]
	s_add_i32 m0, s54, 0xe000
	s_nop 0
	global_load_lds_dwordx4 v[98:99], off
	s_waitcnt vmcnt(8) lgkmcnt(0)
	s_setprio 1
	s_barrier
	v_mfma_f32_16x16x32_bf16 v[98:101], v[154:157], v[200:203], v[134:137]
	v_mfma_f32_16x16x32_bf16 v[106:109], v[162:165], v[200:203], v[130:133]
	v_mfma_f32_16x16x32_bf16 v[118:121], v[154:157], v[208:211], v[118:121]
	v_mfma_f32_16x16x32_bf16 v[114:117], v[162:165], v[208:211], v[114:117]
	v_mfma_f32_16x16x32_bf16 v[94:97], v[154:157], v[216:219], v[94:97]
	v_mfma_f32_16x16x32_bf16 v[90:93], v[162:165], v[216:219], v[90:93]
	v_mfma_f32_16x16x32_bf16 v[78:81], v[154:157], v[224:227], v[78:81]
	v_mfma_f32_16x16x32_bf16 v[74:77], v[162:165], v[224:227], v[74:77]
	v_mfma_f32_16x16x32_bf16 v[98:101], v[158:161], v[204:207], v[98:101]
	v_mfma_f32_16x16x32_bf16 v[106:109], v[166:169], v[204:207], v[106:109]
	v_mfma_f32_16x16x32_bf16 v[118:121], v[158:161], v[212:215], v[118:121]
	v_mfma_f32_16x16x32_bf16 v[114:117], v[166:169], v[212:215], v[114:117]
	v_mfma_f32_16x16x32_bf16 v[94:97], v[158:161], v[220:223], v[94:97]
	v_mfma_f32_16x16x32_bf16 v[90:93], v[166:169], v[220:223], v[90:93]
	v_mfma_f32_16x16x32_bf16 v[78:81], v[158:161], v[228:231], v[78:81]
	v_mfma_f32_16x16x32_bf16 v[74:77], v[166:169], v[228:231], v[74:77]
	v_mfma_f32_16x16x32_bf16 v[126:129], v[138:141], v[200:203], v[126:129]
	v_mfma_f32_16x16x32_bf16 v[122:125], v[146:149], v[200:203], v[122:125]
	v_mfma_f32_16x16x32_bf16 v[110:113], v[138:141], v[208:211], v[110:113]
	v_mfma_f32_16x16x32_bf16 v[102:105], v[146:149], v[208:211], v[102:105]
	v_mfma_f32_16x16x32_bf16 v[86:89], v[138:141], v[216:219], v[86:89]
	v_mfma_f32_16x16x32_bf16 v[82:85], v[146:149], v[216:219], v[82:85]
	v_mfma_f32_16x16x32_bf16 v[70:73], v[138:141], v[224:227], v[70:73]
	v_mfma_f32_16x16x32_bf16 v[66:69], v[146:149], v[224:227], v[66:69]
	v_mfma_f32_16x16x32_bf16 v[126:129], v[142:145], v[204:207], v[126:129]
	v_mfma_f32_16x16x32_bf16 v[122:125], v[150:153], v[204:207], v[122:125]
	v_mfma_f32_16x16x32_bf16 v[110:113], v[142:145], v[212:215], v[110:113]
	v_mfma_f32_16x16x32_bf16 v[102:105], v[150:153], v[212:215], v[102:105]
	v_mfma_f32_16x16x32_bf16 v[86:89], v[142:145], v[220:223], v[86:89]
	v_mfma_f32_16x16x32_bf16 v[82:85], v[150:153], v[220:223], v[82:85]
	v_mfma_f32_16x16x32_bf16 v[70:73], v[142:145], v[228:231], v[70:73]
	v_mfma_f32_16x16x32_bf16 v[66:69], v[150:153], v[228:231], v[66:69]
	s_setprio 0
	s_barrier
	s_cmp_lg_u32 s46, s83
	s_cbranch_scc1 .LBB0_985
	v_mov_b32_e32 v178, v194
	s_add_i32 m0, s79, 0x20000
	v_lshl_add_u64 v[130:131], s[36:37], 0, v[178:179]
	global_load_lds_dwordx4 v178, s[36:37]
	v_lshl_add_u64 v[130:131], v[130:131], 0, s[18:19]
	s_add_i32 m0, s79, 0x20400
	s_andn2_b64 vcc, exec, s[14:15]
	global_load_lds_dwordx4 v[130:131], off
	s_cbranch_vccnz .LBB0_985
	v_lshl_add_u64 v[130:131], s[38:39], 0, v[178:179]
	s_add_i32 m0, 0, 0x24000
	s_nop 0
	global_load_lds_dwordx4 v[130:131], off
	s_branch .LBB0_985

; #define PG8_STAGE(bufoff, gbase, voff) do { _Pragma("unroll") for (int _i = 0; _i < 2; ++_i) \
;         __builtin_amdgcn_global_load_lds((const unsigned*)((const char*)(gbase) + (voff)[_i]), (PG8_LAS unsigned*)(lds + (bufoff) + ldsw + _i * 8192), 16, 0, 0); } while (0)
; #define PG8_LDA(dst, b, h) do { _Pragma("unroll") for (int m = 0; m < 4; ++m) _Pragma("unroll") for (int k = 0; k < 2; ++k) dst[m][k] = *(const PG8_LAS bf16x8*)(lds + PG8_SA(b, h) + aoff + m * 2048 + k * 1024); } while (0)
; #define PG8_LDB(dst, b, h) do { _Pragma("unroll") for (int n = 0; n < 2; ++n) _Pragma("unroll") for (int k = 0; k < 2; ++k) dst[n][k] = *(const PG8_LAS bf16x8*)(lds + PG8_SB(b, h) + boff + n * 2048 + k * 1024); } while (0)
; #define PG8_MMA(ai, bj, At, Bt) do { __builtin_amdgcn_s_setprio(1); _Pragma("unroll") for (int m = 0; m < 4; ++m) _Pragma("unroll") for (int n = 0; n < 2; ++n) _Pragma("unroll") for (int k = 0; k < 2; ++k) \
;         acc[ai][bj][m][n] = __builtin_amdgcn_mfma_f32_16x16x32_bf16(Bt[n][k], At[m][k], acc[ai][bj][m][n], 0, 0, 0); __builtin_amdgcn_s_setprio(0); } while (0)
; #define PG8_WAIT_V(n) asm volatile("s_waitcnt vmcnt(" #n ")" ::: "memory")
; #define PG8_WAIT_L(n) asm volatile("s_waitcnt lgkmcnt(" #n ")" ::: "memory")
; template <class Epi, class Sched, bool ALIGN_EPI = false, bool SP2 = false>
; __device__ __forceinline__ void gemm_phase(PG8_LAS unsigned char* lds, const Gemm g, const Sched& S, const Epi& E) {
;     ...
;     f32x4 acc[2][2][4][2];
; #pragma unroll
;     for (int a = 0; a < 2; ++a)
; #pragma unroll
;         for (int b = 0; b < 2; ++b)
; #pragma unroll
;             for (int m = 0; m < 4; ++m)
; #pragma unroll
;                 for (int n = 0; n < 2; ++n) acc[a][b][m][n] = (f32x4){0.f, 0.f, 0.f, 0.f};
;     ...
;             PG8_LDB(B0, 0, 0); PG8_LDB(B1, 0, 1); PG8_SCHED; PG8_LDA(At, 0, 0); PG8_STAGE(PG8_SA(1, 1), a1 + hstep, voffA);
;             PG8_WAIT_V(8); PG8_WAIT_L(0); PG8_BAR; PG8_MMA(0, 0, At, B0); PG8_MMA(0, 1, At, B1); PG8_BAR; PG8_SCHED;
;             if constexpr (Epi::PREFETCH) { if (t == tpf) E.prefetch(cur, wid, lane); }
;             PG8_LDA(At, 0, 1); PG8_STAGE(PG8_SB(0, 0), b2, voffB); PG8_STAGE(PG8_SB(0, 1), b2 + hstep, voffB); PG8_STAGE(PG8_SA(0, 0), a2, voffA);
;             PG8_WAIT_V(8); PG8_WAIT_L(0); PG8_BAR; PG8_MMA(1, 0, At, B0); PG8_MMA(1, 1, At, B1); PG8_BAR; PG8_SCHED;
.LBB0_1068:
	s_add_u32 s35, s6, 0x100
	s_addc_u32 s36, s7, 0
	s_mov_b32 s37, -2
	s_waitcnt lgkmcnt(0)
	ds_read_b128 v[130:133], v192
	ds_read_b128 v[134:137], v192 offset:1024
	ds_read_b128 v[156:159], v192 offset:2048
	ds_read_b128 v[160:163], v192 offset:3072
	ds_read_b128 v[164:167], v193
	ds_read_b128 v[168:171], v193 offset:1024
	ds_read_b128 v[172:175], v193 offset:2048
	ds_read_b128 v[176:179], v193 offset:3072
	s_add_u32 s0, s4, 0x200
	s_addc_u32 s1, s5, 0
	s_cmp_eq_u32 s37, 40
	s_cselect_b32 s31, s27, s1
	s_cselect_b32 s30, s26, s0
	s_cselect_b32 s7, s29, s36
	s_cselect_b32 s6, s28, s35
	v_lshl_add_u64 v[188:189], s[4:5], 0, v[148:149]
	s_add_i32 m0, s45, 0xc000
	ds_read_b128 v[180:183], v194
	ds_read_b128 v[184:187], v194 offset:1024
	ds_read_b128 v[196:199], v194 offset:2048
	ds_read_b128 v[200:203], v194 offset:3072
	ds_read_b128 v[204:207], v194 offset:4096
	ds_read_b128 v[208:211], v194 offset:5120
	ds_read_b128 v[212:215], v194 offset:6144
	ds_read_b128 v[216:219], v194 offset:7168
	global_load_lds_dwordx4 v[188:189], off
	v_lshl_add_u64 v[188:189], s[4:5], 0, v[150:151]
	s_add_i32 m0, s45, 0xe000
	s_nop 0
	global_load_lds_dwordx4 v[188:189], off
	s_waitcnt vmcnt(8) lgkmcnt(0)
	s_setprio 1
	s_barrier
	v_mfma_f32_16x16x32_bf16 v[126:129], v[130:133], v[180:183], 0
	v_mfma_f32_16x16x32_bf16 v[122:125], v[156:159], v[180:183], 0
	v_mfma_f32_16x16x32_bf16 v[110:113], v[130:133], v[196:199], 0
	v_mfma_f32_16x16x32_bf16 v[106:109], v[156:159], v[196:199], 0
	v_mfma_f32_16x16x32_bf16 v[94:97], v[130:133], v[204:207], 0
	v_mfma_f32_16x16x32_bf16 v[90:93], v[156:159], v[204:207], 0
	v_mfma_f32_16x16x32_bf16 v[78:81], v[130:133], v[212:215], 0
	v_mfma_f32_16x16x32_bf16 v[74:77], v[156:159], v[212:215], 0
	v_mfma_f32_16x16x32_bf16 v[126:129], v[134:137], v[184:187], v[126:129]
	v_mfma_f32_16x16x32_bf16 v[122:125], v[160:163], v[184:187], v[122:125]
	v_mfma_f32_16x16x32_bf16 v[110:113], v[134:137], v[200:203], v[110:113]
	v_mfma_f32_16x16x32_bf16 v[106:109], v[160:163], v[200:203], v[106:109]
	v_mfma_f32_16x16x32_bf16 v[94:97], v[134:137], v[208:211], v[94:97]
	v_mfma_f32_16x16x32_bf16 v[90:93], v[160:163], v[208:211], v[90:93]
	v_mfma_f32_16x16x32_bf16 v[78:81], v[134:137], v[216:219], v[78:81]
	v_mfma_f32_16x16x32_bf16 v[74:77], v[160:163], v[216:219], v[74:77]
	v_mfma_f32_16x16x32_bf16 v[118:121], v[164:167], v[180:183], 0
	v_mfma_f32_16x16x32_bf16 v[114:117], v[172:175], v[180:183], 0
	v_mfma_f32_16x16x32_bf16 v[102:105], v[164:167], v[196:199], 0
	v_mfma_f32_16x16x32_bf16 v[98:101], v[172:175], v[196:199], 0
	v_mfma_f32_16x16x32_bf16 v[86:89], v[164:167], v[204:207], 0
	v_mfma_f32_16x16x32_bf16 v[82:85], v[172:175], v[204:207], 0
	v_mfma_f32_16x16x32_bf16 v[70:73], v[164:167], v[212:215], 0
	v_mfma_f32_16x16x32_bf16 v[66:69], v[172:175], v[212:215], 0
	v_mfma_f32_16x16x32_bf16 v[118:121], v[168:171], v[184:187], v[118:121]
	v_mfma_f32_16x16x32_bf16 v[114:117], v[176:179], v[184:187], v[114:117]
	v_mfma_f32_16x16x32_bf16 v[102:105], v[168:171], v[200:203], v[102:105]
	v_mfma_f32_16x16x32_bf16 v[98:101], v[176:179], v[200:203], v[98:101]
	v_mfma_f32_16x16x32_bf16 v[86:89], v[168:171], v[208:211], v[86:89]
	v_mfma_f32_16x16x32_bf16 v[82:85], v[176:179], v[208:211], v[82:85]
	v_mfma_f32_16x16x32_bf16 v[70:73], v[168:171], v[216:219], v[70:73]
	v_mfma_f32_16x16x32_bf16 v[66:69], v[176:179], v[216:219], v[66:69]
	s_setprio 0
	s_barrier
	s_add_i32 s4, s61, s44
	v_lshl_add_u64 v[188:189], s[6:7], 0, v[140:141]
	s_mov_b32 m0, s4
	ds_read_b128 v[180:183], v194 offset:16384
	ds_read_b128 v[184:187], v194 offset:17408
	ds_read_b128 v[196:199], v194 offset:18432
	ds_read_b128 v[200:203], v194 offset:19456
	ds_read_b128 v[204:207], v194 offset:20480
	ds_read_b128 v[208:211], v194 offset:21504
	ds_read_b128 v[212:215], v194 offset:22528
	ds_read_b128 v[216:219], v194 offset:23552
	global_load_lds_dwordx4 v[188:189], off
	s_add_i32 m0, s4, 0x2000
	s_add_u32 s4, s6, 0xb0000
	v_lshl_add_u64 v[220:221], s[6:7], 0, v[144:145]
	s_addc_u32 s5, s7, 0
	s_add_i32 s38, s62, s44
	global_load_lds_dwordx4 v[220:221], off
	v_lshl_add_u64 v[222:223], s[4:5], 0, v[140:141]
	s_mov_b32 m0, s38
	v_lshl_add_u64 v[224:225], s[30:31], 0, v[142:143]
	global_load_lds_dwordx4 v[222:223], off
	v_lshl_add_u64 v[222:223], s[4:5], 0, v[144:145]
	s_add_i32 m0, s38, 0x2000
	s_nop 0
	global_load_lds_dwordx4 v[222:223], off
	v_lshl_add_u64 v[222:223], s[30:31], 0, v[138:139]
	s_mov_b32 m0, s45
	s_nop 0
	global_load_lds_dwordx4 v[222:223], off
	s_mov_b32 m0, s46
	s_nop 0
	global_load_lds_dwordx4 v[224:225], off
	s_waitcnt vmcnt(8) lgkmcnt(0)
	s_setprio 1
	s_barrier
	v_mfma_f32_16x16x32_bf16 v[62:65], v[130:133], v[180:183], 0
	v_mfma_f32_16x16x32_bf16 v[58:61], v[156:159], v[180:183], 0
	v_mfma_f32_16x16x32_bf16 v[46:49], v[130:133], v[196:199], 0
	v_mfma_f32_16x16x32_bf16 v[42:45], v[156:159], v[196:199], 0
	v_mfma_f32_16x16x32_bf16 v[30:33], v[130:133], v[204:207], 0
	v_mfma_f32_16x16x32_bf16 v[26:29], v[156:159], v[204:207], 0
	v_mfma_f32_16x16x32_bf16 v[14:17], v[130:133], v[212:215], 0
	v_mfma_f32_16x16x32_bf16 v[10:13], v[156:159], v[212:215], 0
	v_mfma_f32_16x16x32_bf16 v[62:65], v[134:137], v[184:187], v[62:65]
	v_mfma_f32_16x16x32_bf16 v[58:61], v[160:163], v[184:187], v[58:61]
	v_mfma_f32_16x16x32_bf16 v[46:49], v[134:137], v[200:203], v[46:49]
	v_mfma_f32_16x16x32_bf16 v[42:45], v[160:163], v[200:203], v[42:45]
	v_mfma_f32_16x16x32_bf16 v[30:33], v[134:137], v[208:211], v[30:33]
	v_mfma_f32_16x16x32_bf16 v[26:29], v[160:163], v[208:211], v[26:29]
	v_mfma_f32_16x16x32_bf16 v[14:17], v[134:137], v[216:219], v[14:17]
	v_mfma_f32_16x16x32_bf16 v[10:13], v[160:163], v[216:219], v[10:13]
	v_mfma_f32_16x16x32_bf16 v[54:57], v[164:167], v[180:183], 0
	v_mfma_f32_16x16x32_bf16 v[50:53], v[172:175], v[180:183], 0
	v_mfma_f32_16x16x32_bf16 v[38:41], v[164:167], v[196:199], 0
	v_mfma_f32_16x16x32_bf16 v[34:37], v[172:175], v[196:199], 0
	v_mfma_f32_16x16x32_bf16 v[22:25], v[164:167], v[204:207], 0
	v_mfma_f32_16x16x32_bf16 v[18:21], v[172:175], v[204:207], 0
	v_mfma_f32_16x16x32_bf16 v[6:9], v[164:167], v[212:215], 0
	v_mfma_f32_16x16x32_bf16 v[2:5], v[172:175], v[212:215], 0
	v_mfma_f32_16x16x32_bf16 v[54:57], v[168:171], v[184:187], v[54:57]
	v_mfma_f32_16x16x32_bf16 v[50:53], v[176:179], v[184:187], v[50:53]
	v_mfma_f32_16x16x32_bf16 v[38:41], v[168:171], v[200:203], v[38:41]
	v_mfma_f32_16x16x32_bf16 v[34:37], v[176:179], v[200:203], v[34:37]
	v_mfma_f32_16x16x32_bf16 v[22:25], v[168:171], v[208:211], v[22:25]
	v_mfma_f32_16x16x32_bf16 v[18:21], v[176:179], v[208:211], v[18:21]
	v_mfma_f32_16x16x32_bf16 v[6:9], v[168:171], v[216:219], v[6:9]
	v_mfma_f32_16x16x32_bf16 v[2:5], v[176:179], v[216:219], v[2:5]
	s_setprio 0
	s_barrier
	s_branch .Lpz6_mid
; #define PG8_STAGE(bufoff, gbase, voff) do { _Pragma("unroll") for (int _i = 0; _i < 2; ++_i) \
;         __builtin_amdgcn_global_load_lds((const unsigned*)((const char*)(gbase) + (voff)[_i]), (PG8_LAS unsigned*)(lds + (bufoff) + ldsw + _i * 8192), 16, 0, 0); } while (0)
; #define PG8_LDA(dst, b, h) do { _Pragma("unroll") for (int m = 0; m < 4; ++m) _Pragma("unroll") for (int k = 0; k < 2; ++k) dst[m][k] = *(const PG8_LAS bf16x8*)(lds + PG8_SA(b, h) + aoff + m * 2048 + k * 1024); } while (0)
; #define PG8_LDB(dst, b, h) do { _Pragma("unroll") for (int n = 0; n < 2; ++n) _Pragma("unroll") for (int k = 0; k < 2; ++k) dst[n][k] = *(const PG8_LAS bf16x8*)(lds + PG8_SB(b, h) + boff + n * 2048 + k * 1024); } while (0)
; #define PG8_MMA(ai, bj, At, Bt) do { __builtin_amdgcn_s_setprio(1); _Pragma("unroll") for (int m = 0; m < 4; ++m) _Pragma("unroll") for (int n = 0; n < 2; ++n) _Pragma("unroll") for (int k = 0; k < 2; ++k) \
;         acc[ai][bj][m][n] = __builtin_amdgcn_mfma_f32_16x16x32_bf16(Bt[n][k], At[m][k], acc[ai][bj][m][n], 0, 0, 0); __builtin_amdgcn_s_setprio(0); } while (0)
; #define PG8_WAIT_V(n) asm volatile("s_waitcnt vmcnt(" #n ")" ::: "memory")
; template <class Epi, class Sched, bool ALIGN_EPI = false, bool SP2 = false>
; __device__ __forceinline__ void gemm_phase(PG8_LAS unsigned char* lds, const Gemm g, const Sched& S, const Epi& E) {
;     ...
;             const bool last = (t == nt - 2);
;             const char* a1 = cA + (size_t)(t + 1) * kstepA;
;             const char* a2 = last ? nA : cA + (size_t)(t + 2) * kstepA; const char* b2 = last ? nB : cB + (size_t)(t + 2) * kstep;
;             const char* a3 = a2 + kstepA; const char* b3 = b2 + kstep;
;             if (last && has_next) S.a_ready(nxt);
;             if constexpr (SP2) {
;             PG8_LDB(B0, 0, 0); PG8_LDB(B1, 0, 1); PG8_SCHED; PG8_LDA(At, 0, 0); PG8_STAGE(PG8_SA(1, 1), a1 + hstep, voffA);
;             PG8_WAIT_V(8); PG8_WAIT_L(0); PG8_BAR; PG8_MMA(0, 0, At, B0); PG8_MMA(0, 1, At, B1); PG8_BAR; PG8_SCHED;
;             if constexpr (Epi::PREFETCH) { if (t == tpf) E.prefetch(cur, wid, lane); }
;             PG8_LDA(At, 0, 1); PG8_STAGE(PG8_SB(0, 0), b2, voffB); PG8_STAGE(PG8_SB(0, 1), b2 + hstep, voffB); PG8_STAGE(PG8_SA(0, 0), a2, voffA);
;             PG8_WAIT_V(8); PG8_WAIT_L(0); PG8_BAR; PG8_MMA(1, 0, At, B0); PG8_MMA(1, 1, At, B1); PG8_BAR; PG8_SCHED;
.LBB0_1069:
	ds_read_b128 v[130:133], v192
	ds_read_b128 v[134:137], v192 offset:1024
	ds_read_b128 v[156:159], v192 offset:2048
	ds_read_b128 v[160:163], v192 offset:3072
	ds_read_b128 v[164:167], v193
	ds_read_b128 v[168:171], v193 offset:1024
	ds_read_b128 v[172:175], v193 offset:2048
	ds_read_b128 v[176:179], v193 offset:3072
	s_add_u32 s0, s4, 0x200
	s_addc_u32 s1, s5, 0
	s_cmp_eq_u32 s37, 40
	s_cselect_b32 s31, s27, s1
	s_cselect_b32 s30, s26, s0
	s_cselect_b32 s7, s29, s36
	s_cselect_b32 s6, s28, s35
	v_lshl_add_u64 v[188:189], s[4:5], 0, v[148:149]
	s_add_i32 m0, s45, 0xc000
	ds_read_b128 v[180:183], v194
	ds_read_b128 v[184:187], v194 offset:1024
	ds_read_b128 v[196:199], v194 offset:2048
	ds_read_b128 v[200:203], v194 offset:3072
	ds_read_b128 v[204:207], v194 offset:4096
	ds_read_b128 v[208:211], v194 offset:5120
	ds_read_b128 v[212:215], v194 offset:6144
	ds_read_b128 v[216:219], v194 offset:7168
	global_load_lds_dwordx4 v[188:189], off
	v_lshl_add_u64 v[188:189], s[4:5], 0, v[150:151]
	s_add_i32 m0, s45, 0xe000
	s_nop 0
	global_load_lds_dwordx4 v[188:189], off
	s_waitcnt vmcnt(8) lgkmcnt(0)
	s_setprio 1
	s_barrier
	v_mfma_f32_16x16x32_bf16 v[126:129], v[130:133], v[180:183], v[126:129]
	v_mfma_f32_16x16x32_bf16 v[122:125], v[156:159], v[180:183], v[122:125]
	v_mfma_f32_16x16x32_bf16 v[110:113], v[130:133], v[196:199], v[110:113]
	v_mfma_f32_16x16x32_bf16 v[106:109], v[156:159], v[196:199], v[106:109]
	v_mfma_f32_16x16x32_bf16 v[94:97], v[130:133], v[204:207], v[94:97]
	v_mfma_f32_16x16x32_bf16 v[90:93], v[156:159], v[204:207], v[90:93]
	v_mfma_f32_16x16x32_bf16 v[78:81], v[130:133], v[212:215], v[78:81]
	v_mfma_f32_16x16x32_bf16 v[74:77], v[156:159], v[212:215], v[74:77]
	v_mfma_f32_16x16x32_bf16 v[126:129], v[134:137], v[184:187], v[126:129]
	v_mfma_f32_16x16x32_bf16 v[122:125], v[160:163], v[184:187], v[122:125]
	v_mfma_f32_16x16x32_bf16 v[110:113], v[134:137], v[200:203], v[110:113]
	v_mfma_f32_16x16x32_bf16 v[106:109], v[160:163], v[200:203], v[106:109]
	v_mfma_f32_16x16x32_bf16 v[94:97], v[134:137], v[208:211], v[94:97]
	v_mfma_f32_16x16x32_bf16 v[90:93], v[160:163], v[208:211], v[90:93]
	v_mfma_f32_16x16x32_bf16 v[78:81], v[134:137], v[216:219], v[78:81]
	v_mfma_f32_16x16x32_bf16 v[74:77], v[160:163], v[216:219], v[74:77]
	v_mfma_f32_16x16x32_bf16 v[118:121], v[164:167], v[180:183], v[118:121]
	v_mfma_f32_16x16x32_bf16 v[114:117], v[172:175], v[180:183], v[114:117]
	v_mfma_f32_16x16x32_bf16 v[102:105], v[164:167], v[196:199], v[102:105]
	v_mfma_f32_16x16x32_bf16 v[98:101], v[172:175], v[196:199], v[98:101]
	v_mfma_f32_16x16x32_bf16 v[86:89], v[164:167], v[204:207], v[86:89]
	v_mfma_f32_16x16x32_bf16 v[82:85], v[172:175], v[204:207], v[82:85]
	v_mfma_f32_16x16x32_bf16 v[70:73], v[164:167], v[212:215], v[70:73]
	v_mfma_f32_16x16x32_bf16 v[66:69], v[172:175], v[212:215], v[66:69]
	v_mfma_f32_16x16x32_bf16 v[118:121], v[168:171], v[184:187], v[118:121]
	v_mfma_f32_16x16x32_bf16 v[114:117], v[176:179], v[184:187], v[114:117]
	v_mfma_f32_16x16x32_bf16 v[102:105], v[168:171], v[200:203], v[102:105]
	v_mfma_f32_16x16x32_bf16 v[98:101], v[176:179], v[200:203], v[98:101]
	v_mfma_f32_16x16x32_bf16 v[86:89], v[168:171], v[208:211], v[86:89]
	v_mfma_f32_16x16x32_bf16 v[82:85], v[176:179], v[208:211], v[82:85]
	v_mfma_f32_16x16x32_bf16 v[70:73], v[168:171], v[216:219], v[70:73]
	v_mfma_f32_16x16x32_bf16 v[66:69], v[176:179], v[216:219], v[66:69]
	s_setprio 0
	s_barrier
	s_add_i32 s4, s61, s44
	v_lshl_add_u64 v[188:189], s[6:7], 0, v[140:141]
	s_mov_b32 m0, s4
	ds_read_b128 v[180:183], v194 offset:16384
	ds_read_b128 v[184:187], v194 offset:17408
	ds_read_b128 v[196:199], v194 offset:18432
	ds_read_b128 v[200:203], v194 offset:19456
	ds_read_b128 v[204:207], v194 offset:20480
	ds_read_b128 v[208:211], v194 offset:21504
	ds_read_b128 v[212:215], v194 offset:22528
	ds_read_b128 v[216:219], v194 offset:23552
	global_load_lds_dwordx4 v[188:189], off
	s_add_i32 m0, s4, 0x2000
	s_add_u32 s4, s6, 0xb0000
	v_lshl_add_u64 v[220:221], s[6:7], 0, v[144:145]
	s_addc_u32 s5, s7, 0
	s_add_i32 s38, s62, s44
	global_load_lds_dwordx4 v[220:221], off
	v_lshl_add_u64 v[222:223], s[4:5], 0, v[140:141]
	s_mov_b32 m0, s38
	v_lshl_add_u64 v[224:225], s[30:31], 0, v[142:143]
	global_load_lds_dwordx4 v[222:223], off
	v_lshl_add_u64 v[222:223], s[4:5], 0, v[144:145]
	s_add_i32 m0, s38, 0x2000
	s_nop 0
	global_load_lds_dwordx4 v[222:223], off
	v_lshl_add_u64 v[222:223], s[30:31], 0, v[138:139]
	s_mov_b32 m0, s45
	s_nop 0
	global_load_lds_dwordx4 v[222:223], off
	s_mov_b32 m0, s46
	s_nop 0
	global_load_lds_dwordx4 v[224:225], off
	s_waitcnt vmcnt(8) lgkmcnt(0)
	s_setprio 1
	s_barrier
	v_mfma_f32_16x16x32_bf16 v[62:65], v[130:133], v[180:183], v[62:65]
	v_mfma_f32_16x16x32_bf16 v[58:61], v[156:159], v[180:183], v[58:61]
	v_mfma_f32_16x16x32_bf16 v[46:49], v[130:133], v[196:199], v[46:49]
	v_mfma_f32_16x16x32_bf16 v[42:45], v[156:159], v[196:199], v[42:45]
	v_mfma_f32_16x16x32_bf16 v[30:33], v[130:133], v[204:207], v[30:33]
	v_mfma_f32_16x16x32_bf16 v[26:29], v[156:159], v[204:207], v[26:29]
	v_mfma_f32_16x16x32_bf16 v[14:17], v[130:133], v[212:215], v[14:17]
	v_mfma_f32_16x16x32_bf16 v[10:13], v[156:159], v[212:215], v[10:13]
	v_mfma_f32_16x16x32_bf16 v[62:65], v[134:137], v[184:187], v[62:65]
	v_mfma_f32_16x16x32_bf16 v[58:61], v[160:163], v[184:187], v[58:61]
	v_mfma_f32_16x16x32_bf16 v[46:49], v[134:137], v[200:203], v[46:49]
	v_mfma_f32_16x16x32_bf16 v[42:45], v[160:163], v[200:203], v[42:45]
	v_mfma_f32_16x16x32_bf16 v[30:33], v[134:137], v[208:211], v[30:33]
	v_mfma_f32_16x16x32_bf16 v[26:29], v[160:163], v[208:211], v[26:29]
	v_mfma_f32_16x16x32_bf16 v[14:17], v[134:137], v[216:219], v[14:17]
	v_mfma_f32_16x16x32_bf16 v[10:13], v[160:163], v[216:219], v[10:13]
	v_mfma_f32_16x16x32_bf16 v[54:57], v[164:167], v[180:183], v[54:57]
	v_mfma_f32_16x16x32_bf16 v[50:53], v[172:175], v[180:183], v[50:53]
	v_mfma_f32_16x16x32_bf16 v[38:41], v[164:167], v[196:199], v[38:41]
	v_mfma_f32_16x16x32_bf16 v[34:37], v[172:175], v[196:199], v[34:37]
	v_mfma_f32_16x16x32_bf16 v[22:25], v[164:167], v[204:207], v[22:25]
	v_mfma_f32_16x16x32_bf16 v[18:21], v[172:175], v[204:207], v[18:21]
	v_mfma_f32_16x16x32_bf16 v[6:9], v[164:167], v[212:215], v[6:9]
	v_mfma_f32_16x16x32_bf16 v[2:5], v[172:175], v[212:215], v[2:5]
	v_mfma_f32_16x16x32_bf16 v[54:57], v[168:171], v[184:187], v[54:57]
	v_mfma_f32_16x16x32_bf16 v[50:53], v[176:179], v[184:187], v[50:53]
	v_mfma_f32_16x16x32_bf16 v[38:41], v[168:171], v[200:203], v[38:41]
	v_mfma_f32_16x16x32_bf16 v[34:37], v[176:179], v[200:203], v[34:37]
	v_mfma_f32_16x16x32_bf16 v[22:25], v[168:171], v[208:211], v[22:25]
	v_mfma_f32_16x16x32_bf16 v[18:21], v[176:179], v[208:211], v[18:21]
	v_mfma_f32_16x16x32_bf16 v[6:9], v[168:171], v[216:219], v[6:9]
	v_mfma_f32_16x16x32_bf16 v[2:5], v[176:179], v[216:219], v[2:5]
	s_setprio 0
	s_barrier
; #define PG8_STAGE(bufoff, gbase, voff) do { _Pragma("unroll") for (int _i = 0; _i < 2; ++_i) \
;         __builtin_amdgcn_global_load_lds((const unsigned*)((const char*)(gbase) + (voff)[_i]), (PG8_LAS unsigned*)(lds + (bufoff) + ldsw + _i * 8192), 16, 0, 0); } while (0)
; #define PG8_LDA(dst, b, h) do { _Pragma("unroll") for (int m = 0; m < 4; ++m) _Pragma("unroll") for (int k = 0; k < 2; ++k) dst[m][k] = *(const PG8_LAS bf16x8*)(lds + PG8_SA(b, h) + aoff + m * 2048 + k * 1024); } while (0)
; #define PG8_LDB(dst, b, h) do { _Pragma("unroll") for (int n = 0; n < 2; ++n) _Pragma("unroll") for (int k = 0; k < 2; ++k) dst[n][k] = *(const PG8_LAS bf16x8*)(lds + PG8_SB(b, h) + boff + n * 2048 + k * 1024); } while (0)
; #define PG8_MMA(ai, bj, At, Bt) do { __builtin_amdgcn_s_setprio(1); _Pragma("unroll") for (int m = 0; m < 4; ++m) _Pragma("unroll") for (int n = 0; n < 2; ++n) _Pragma("unroll") for (int k = 0; k < 2; ++k) \
;         acc[ai][bj][m][n] = __builtin_amdgcn_mfma_f32_16x16x32_bf16(Bt[n][k], At[m][k], acc[ai][bj][m][n], 0, 0, 0); __builtin_amdgcn_s_setprio(0); } while (0)
; #define PG8_WAIT_V(n) asm volatile("s_waitcnt vmcnt(" #n ")" ::: "memory")
; #define PG8_WAIT_L(n) asm volatile("s_waitcnt lgkmcnt(" #n ")" ::: "memory")
; #define PG8_BAR __builtin_amdgcn_s_barrier()
; #define PG8_SCHED __builtin_amdgcn_sched_barrier(0)
; template <class Epi, class Sched, bool ALIGN_EPI = false, bool SP2 = false>
; __device__ __forceinline__ void gemm_phase(PG8_LAS unsigned char* lds, const Gemm g, const Sched& S, const Epi& E) {
;     ...
;             PG8_LDB(B0, 1, 0); PG8_LDB(B1, 1, 1); PG8_SCHED; PG8_LDA(At, 1, 0); PG8_STAGE(PG8_SA(0, 1), a2 + hstep, voffA);
;             PG8_WAIT_V(8); PG8_WAIT_L(0); PG8_BAR; PG8_MMA(0, 0, At, B0); PG8_MMA(0, 1, At, B1); PG8_BAR; PG8_SCHED;
.Lpz6_mid:
	s_add_i32 s38, 0, 0x18000
	v_add_u32_e32 v146, s38, v191
	s_add_i32 s39, 0, 0x1c000
	ds_read_b128 v[130:133], v146
	ds_read_b128 v[134:137], v146 offset:1024
	ds_read_b128 v[156:159], v146 offset:2048
	ds_read_b128 v[160:163], v146 offset:3072
	v_add_u32_e32 v146, s39, v191
	ds_read_b128 v[164:167], v146
	ds_read_b128 v[168:171], v146 offset:1024
	ds_read_b128 v[172:175], v146 offset:2048
	ds_read_b128 v[176:179], v146 offset:3072
	s_add_u32 s4, s30, 0xb0000
	s_addc_u32 s5, s31, 0
	s_mov_b32 m0, s47
	v_lshl_add_u64 v[226:227], s[4:5], 0, v[138:139]
	ds_read_b128 v[180:183], v194 offset:32768
	ds_read_b128 v[184:187], v194 offset:33792
	ds_read_b128 v[196:199], v194 offset:34816
	ds_read_b128 v[200:203], v194 offset:35840
	ds_read_b128 v[204:207], v194 offset:36864
	ds_read_b128 v[208:211], v194 offset:37888
	ds_read_b128 v[212:215], v194 offset:38912
	ds_read_b128 v[216:219], v194 offset:39936
	global_load_lds_dwordx4 v[226:227], off
	v_lshl_add_u64 v[226:227], s[4:5], 0, v[142:143]
	s_mov_b32 m0, s48
	s_nop 0
	global_load_lds_dwordx4 v[226:227], off
	s_waitcnt vmcnt(8) lgkmcnt(0)
	s_setprio 1
	s_barrier
	v_mfma_f32_16x16x32_bf16 v[126:129], v[130:133], v[180:183], v[126:129]
	v_mfma_f32_16x16x32_bf16 v[122:125], v[156:159], v[180:183], v[122:125]
	v_mfma_f32_16x16x32_bf16 v[110:113], v[130:133], v[196:199], v[110:113]
	v_mfma_f32_16x16x32_bf16 v[106:109], v[156:159], v[196:199], v[106:109]
	v_mfma_f32_16x16x32_bf16 v[94:97], v[130:133], v[204:207], v[94:97]
	v_mfma_f32_16x16x32_bf16 v[90:93], v[156:159], v[204:207], v[90:93]
	v_mfma_f32_16x16x32_bf16 v[78:81], v[130:133], v[212:215], v[78:81]
	v_mfma_f32_16x16x32_bf16 v[74:77], v[156:159], v[212:215], v[74:77]
	v_mfma_f32_16x16x32_bf16 v[126:129], v[134:137], v[184:187], v[126:129]
	v_mfma_f32_16x16x32_bf16 v[122:125], v[160:163], v[184:187], v[122:125]
	v_mfma_f32_16x16x32_bf16 v[110:113], v[134:137], v[200:203], v[110:113]
	v_mfma_f32_16x16x32_bf16 v[106:109], v[160:163], v[200:203], v[106:109]
	v_mfma_f32_16x16x32_bf16 v[94:97], v[134:137], v[208:211], v[94:97]
	v_mfma_f32_16x16x32_bf16 v[90:93], v[160:163], v[208:211], v[90:93]
	v_mfma_f32_16x16x32_bf16 v[78:81], v[134:137], v[216:219], v[78:81]
	v_mfma_f32_16x16x32_bf16 v[74:77], v[160:163], v[216:219], v[74:77]
	v_mfma_f32_16x16x32_bf16 v[118:121], v[164:167], v[180:183], v[118:121]
	v_mfma_f32_16x16x32_bf16 v[114:117], v[172:175], v[180:183], v[114:117]
	v_mfma_f32_16x16x32_bf16 v[102:105], v[164:167], v[196:199], v[102:105]
	v_mfma_f32_16x16x32_bf16 v[98:101], v[172:175], v[196:199], v[98:101]
	v_mfma_f32_16x16x32_bf16 v[86:89], v[164:167], v[204:207], v[86:89]
	v_mfma_f32_16x16x32_bf16 v[82:85], v[172:175], v[204:207], v[82:85]
	v_mfma_f32_16x16x32_bf16 v[70:73], v[164:167], v[212:215], v[70:73]
	v_mfma_f32_16x16x32_bf16 v[66:69], v[172:175], v[212:215], v[66:69]
	v_mfma_f32_16x16x32_bf16 v[118:121], v[168:171], v[184:187], v[118:121]
	v_mfma_f32_16x16x32_bf16 v[114:117], v[176:179], v[184:187], v[114:117]
	v_mfma_f32_16x16x32_bf16 v[102:105], v[168:171], v[200:203], v[102:105]
	v_mfma_f32_16x16x32_bf16 v[98:101], v[176:179], v[200:203], v[98:101]
	v_mfma_f32_16x16x32_bf16 v[86:89], v[168:171], v[208:211], v[86:89]
	v_mfma_f32_16x16x32_bf16 v[82:85], v[176:179], v[208:211], v[82:85]
	v_mfma_f32_16x16x32_bf16 v[70:73], v[168:171], v[216:219], v[70:73]
	v_mfma_f32_16x16x32_bf16 v[66:69], v[176:179], v[216:219], v[66:69]
	s_setprio 0
	s_barrier
; #define PG8_STAGE(bufoff, gbase, voff) do { _Pragma("unroll") for (int _i = 0; _i < 2; ++_i) \
;         __builtin_amdgcn_global_load_lds((const unsigned*)((const char*)(gbase) + (voff)[_i]), (PG8_LAS unsigned*)(lds + (bufoff) + ldsw + _i * 8192), 16, 0, 0); } while (0)
; #define PG8_LDA(dst, b, h) do { _Pragma("unroll") for (int m = 0; m < 4; ++m) _Pragma("unroll") for (int k = 0; k < 2; ++k) dst[m][k] = *(const PG8_LAS bf16x8*)(lds + PG8_SA(b, h) + aoff + m * 2048 + k * 1024); } while (0)
; #define PG8_MMA(ai, bj, At, Bt) do { __builtin_amdgcn_s_setprio(1); _Pragma("unroll") for (int m = 0; m < 4; ++m) _Pragma("unroll") for (int n = 0; n < 2; ++n) _Pragma("unroll") for (int k = 0; k < 2; ++k) \
;         acc[ai][bj][m][n] = __builtin_amdgcn_mfma_f32_16x16x32_bf16(Bt[n][k], At[m][k], acc[ai][bj][m][n], 0, 0, 0); __builtin_amdgcn_s_setprio(0); } while (0)
; #define PG8_WAIT_V(n) asm volatile("s_waitcnt vmcnt(" #n ")" ::: "memory")
; #define PG8_WAIT_L(n) asm volatile("s_waitcnt lgkmcnt(" #n ")" ::: "memory")
; #define PG8_BAR __builtin_amdgcn_s_barrier()
; #define PG8_SCHED __builtin_amdgcn_sched_barrier(0)
; template <class Epi, class Sched, bool ALIGN_EPI = false, bool SP2 = false>
; __device__ __forceinline__ void gemm_phase(PG8_LAS unsigned char* lds, const Gemm g, const Sched& S, const Epi& E) {
;     ...
;             PG8_LDA(At, 1, 1); PG8_STAGE(PG8_SB(1, 0), b3, voffB); PG8_STAGE(PG8_SB(1, 1), b3 + hstep, voffB); PG8_STAGE(PG8_SA(1, 0), a3, voffA);
;             PG8_WAIT_V(8); PG8_WAIT_L(0); PG8_BAR; PG8_MMA(1, 0, At, B0); PG8_MMA(1, 1, At, B1); PG8_BAR; PG8_SCHED;
;     ...
;         if constexpr (ALIGN_EPI) { if (wr == 0) PG8_BAR; }
	s_add_i32 s4, s38, s44
	v_lshl_add_u64 v[188:189], v[188:189], 0, s[18:19]
	s_mov_b32 m0, s4
	ds_read_b128 v[180:183], v194 offset:49152
	ds_read_b128 v[184:187], v194 offset:50176
	ds_read_b128 v[196:199], v194 offset:51200
	ds_read_b128 v[200:203], v194 offset:52224
	ds_read_b128 v[204:207], v194 offset:53248
	ds_read_b128 v[208:211], v194 offset:54272
	ds_read_b128 v[212:215], v194 offset:55296
	ds_read_b128 v[216:219], v194 offset:56320
	global_load_lds_dwordx4 v[188:189], off
	s_add_i32 m0, s4, 0x2000
	s_add_u32 s4, s6, 0xb0080
	v_lshl_add_u64 v[188:189], v[220:221], 0, s[18:19]
	s_addc_u32 s5, s7, 0
	s_add_i32 s6, s39, s44
	global_load_lds_dwordx4 v[188:189], off
	v_lshl_add_u64 v[188:189], s[4:5], 0, v[140:141]
	s_mov_b32 m0, s6
	s_nop 0
	global_load_lds_dwordx4 v[188:189], off
	v_lshl_add_u64 v[188:189], s[4:5], 0, v[144:145]
	s_add_i32 m0, s6, 0x2000
	s_nop 0
	global_load_lds_dwordx4 v[188:189], off
	v_lshl_add_u64 v[188:189], v[222:223], 0, s[20:21]
	s_mov_b32 m0, s55
	s_nop 0
	global_load_lds_dwordx4 v[188:189], off
	v_lshl_add_u64 v[188:189], v[224:225], 0, s[20:21]
	s_mov_b32 m0, s56
	s_nop 0
	global_load_lds_dwordx4 v[188:189], off
	s_waitcnt vmcnt(8) lgkmcnt(0)
	s_setprio 1
	s_barrier
	v_mfma_f32_16x16x32_bf16 v[62:65], v[130:133], v[180:183], v[62:65]
	v_mfma_f32_16x16x32_bf16 v[58:61], v[156:159], v[180:183], v[58:61]
	v_mfma_f32_16x16x32_bf16 v[46:49], v[130:133], v[196:199], v[46:49]
	v_mfma_f32_16x16x32_bf16 v[42:45], v[156:159], v[196:199], v[42:45]
	v_mfma_f32_16x16x32_bf16 v[30:33], v[130:133], v[204:207], v[30:33]
	v_mfma_f32_16x16x32_bf16 v[26:29], v[156:159], v[204:207], v[26:29]
	v_mfma_f32_16x16x32_bf16 v[14:17], v[130:133], v[212:215], v[14:17]
	v_mfma_f32_16x16x32_bf16 v[10:13], v[156:159], v[212:215], v[10:13]
	v_mfma_f32_16x16x32_bf16 v[62:65], v[134:137], v[184:187], v[62:65]
	v_mfma_f32_16x16x32_bf16 v[58:61], v[160:163], v[184:187], v[58:61]
	v_mfma_f32_16x16x32_bf16 v[46:49], v[134:137], v[200:203], v[46:49]
	v_mfma_f32_16x16x32_bf16 v[42:45], v[160:163], v[200:203], v[42:45]
	v_mfma_f32_16x16x32_bf16 v[30:33], v[134:137], v[208:211], v[30:33]
	v_mfma_f32_16x16x32_bf16 v[26:29], v[160:163], v[208:211], v[26:29]
	v_mfma_f32_16x16x32_bf16 v[14:17], v[134:137], v[216:219], v[14:17]
	v_mfma_f32_16x16x32_bf16 v[10:13], v[160:163], v[216:219], v[10:13]
	v_mfma_f32_16x16x32_bf16 v[54:57], v[164:167], v[180:183], v[54:57]
	v_mfma_f32_16x16x32_bf16 v[50:53], v[172:175], v[180:183], v[50:53]
	v_mfma_f32_16x16x32_bf16 v[38:41], v[164:167], v[196:199], v[38:41]
	v_mfma_f32_16x16x32_bf16 v[34:37], v[172:175], v[196:199], v[34:37]
	v_mfma_f32_16x16x32_bf16 v[22:25], v[164:167], v[204:207], v[22:25]
	v_mfma_f32_16x16x32_bf16 v[18:21], v[172:175], v[204:207], v[18:21]
	v_mfma_f32_16x16x32_bf16 v[6:9], v[164:167], v[212:215], v[6:9]
	v_mfma_f32_16x16x32_bf16 v[2:5], v[172:175], v[212:215], v[2:5]
	v_mfma_f32_16x16x32_bf16 v[54:57], v[168:171], v[184:187], v[54:57]
	v_mfma_f32_16x16x32_bf16 v[50:53], v[176:179], v[184:187], v[50:53]
	v_mfma_f32_16x16x32_bf16 v[38:41], v[168:171], v[200:203], v[38:41]
	v_mfma_f32_16x16x32_bf16 v[34:37], v[176:179], v[200:203], v[34:37]
	v_mfma_f32_16x16x32_bf16 v[22:25], v[168:171], v[208:211], v[22:25]
	v_mfma_f32_16x16x32_bf16 v[18:21], v[176:179], v[208:211], v[18:21]
	v_mfma_f32_16x16x32_bf16 v[6:9], v[168:171], v[216:219], v[6:9]
	v_mfma_f32_16x16x32_bf16 v[2:5], v[176:179], v[216:219], v[2:5]
	s_setprio 0
	s_barrier
	s_add_i32 s37, s37, 2
	s_add_u32 s35, s35, 0x100
	s_addc_u32 s36, s36, 0
	s_cmp_gt_u32 s37, 41
	s_mov_b64 s[4:5], s[0:1]
	s_cbranch_scc0 .LBB0_1069
	s_and_b64 vcc, exec, s[22:23]
	s_cbranch_vccz .LBB0_1072
	s_barrier
